# GEMM K-loops: SP2 address math hoisted into SP1 load segment, A-half-0 restage moved to next SP1 load (4/4 DMA split, vmcnt 10/4/10/4), loader segments at prio 1; EpiIn/EpiSwiglu rowss loads hoisted;
# speedup vs baseline: 1.0015x; 1.0015x over previous
; #define PG8_STAGE(bufoff, gbase, voff) do { _Pragma("unroll") for (int _i = 0; _i < 2; ++_i) \
;         __builtin_amdgcn_global_load_lds((const unsigned*)((const char*)(gbase) + (voff)[_i]), (PG8_LAS unsigned*)(lds + (bufoff) + ldsw + _i * 8192), 16, 0, 0); } while (0)
; #define PG8_WAIT_V(n) asm volatile("s_waitcnt vmcnt(" #n ")" ::: "memory")
; #define PG8_BAR __builtin_amdgcn_s_barrier()
; template <class Epi, class Sched, bool ALIGN_EPI = false, bool SP2 = false>
; __device__ __forceinline__ void gemm_phase(PG8_LAS unsigned char* lds, const Gemm g, const Sched& S, const Epi& E) {
;     ...
;     const unsigned ldsw = (unsigned)wid * 1024u;
;     const int aoff = lds_byte(wr * 64 + fr, fq * 8), boff = lds_byte(wc * 32 + fr, fq * 8);
;     ...
;     Unit cur, nxt; int ui = 0;
;     if (!S.next(0, cur)) return;
;     f32x4 acc[2][2][4][2];
; #pragma unroll
;     for (int a = 0; a < 2; ++a)
; #pragma unroll
;         for (int b = 0; b < 2; ++b)
; #pragma unroll
;             for (int m = 0; m < 4; ++m)
; #pragma unroll
;                 for (int n = 0; n < 2; ++n) acc[a][b][m][n] = (f32x4){0.f, 0.f, 0.f, 0.f};
;     bf16x8 At[4][2], B0[2][2], B1[2][2];
;     const char* cA = (const char*)g.A + (size_t)cur.pm * tstep; const char* cB = (const char*)g.Bt + (size_t)cur.pn * tstep;
;     S.a_ready(cur);
;     if constexpr (SP2) {
;         PG8_STAGE(PG8_SB(0, 0), cB, voffB); PG8_STAGE(PG8_SB(0, 1), cB + hstep, voffB); PG8_STAGE(PG8_SA(0, 0), cA, voffA); PG8_STAGE(PG8_SA(0, 1), cA + hstep, voffA);
;         if (wr == 1) PG8_BAR;
;         PG8_WAIT_V(2); PG8_BAR;
;         PG8_STAGE(PG8_SB(1, 0), cB + kstep, voffB); PG8_STAGE(PG8_SA(1, 0), cA + kstep, voffA); PG8_STAGE(PG8_SB(1, 1), cB + hstep + kstep, voffB);
;         PG8_WAIT_V(6); PG8_BAR;
.LBB0_144:
	s_add_u32 s4, s6, 0x1c600000
	s_addc_u32 s5, s7, 0
	s_add_u32 s6, s6, 0x34f00000
	s_addc_u32 s7, s7, 0
	s_lshl_b32 s8, s8, 5
	s_and_b32 s14, s8, 0x60
	s_mov_b64 s[8:9], 0x80
	s_add_i32 m0, s25, 0x18000
	v_lshl_add_u64 v[6:7], v[6:7], 0, s[8:9]
	s_lshl_b32 s11, s10, 13
	s_lshl_b32 s15, s14, 7
	s_waitcnt vmcnt(2)
	s_barrier
	global_load_lds_dwordx4 v[6:7], off
	v_lshl_add_u64 v[4:5], v[4:5], 0, s[8:9]
	s_add_i32 m0, s25, 0x1a000
	s_add_i32 s48, s25, 0x8000
	s_add_i32 s49, s25, 0xa000
	global_load_lds_dwordx4 v[4:5], off
	v_lshl_add_u64 v[0:1], v[0:1], 0, s[8:9]
	s_mov_b32 m0, s48
	s_add_u32 s12, s30, 0x80080
	global_load_lds_dwordx4 v[0:1], off
	v_mov_b64_e32 v[250:251], v[0:1]
	v_lshl_add_u64 v[0:1], v[2:3], 0, s[8:9]
	s_mov_b32 m0, s49
	s_addc_u32 s13, s31, 0
	global_load_lds_dwordx4 v[0:1], off
	v_mov_b64_e32 v[252:253], v[0:1]
	s_add_i32 m0, s25, 0x1c000
	v_lshl_add_u64 v[0:1], s[12:13], 0, v[132:133]
	global_load_lds_dwordx4 v[0:1], off
	v_lshl_add_u64 v[0:1], s[12:13], 0, v[128:129]
	s_add_i32 m0, s25, 0x1e000
	s_cmpk_lt_u32 s3, 0x100
	global_load_lds_dwordx4 v[0:1], off
	v_lshrrev_b32_e32 v1, 1, v9
	v_and_b32_e32 v1, 24, v1
	v_and_b32_e32 v0, 15, v9
	v_lshlrev_b32_e32 v2, 1, v1
	v_lshl_or_b32 v152, s10, 6, v0
	v_lshl_or_b32 v0, v0, 6, v2
	v_lshlrev_b32_e32 v2, 2, v9
	v_and_b32_e32 v2, 32, v2
	v_bitop3_b32 v3, v0, s11, v2 bitop3:0xde
	v_bitop3_b32 v153, v0, s15, v2 bitop3:0xde
	v_lshlrev_b32_e32 v0, 15, v13
	v_and_b32_e32 v0, 0xffff0000, v0
	v_or_b32_e32 v154, s14, v1
	v_lshl_add_u32 v0, v12, 12, v0
	v_and_b32_e32 v1, 1, v13
	v_lshl_or_b32 v0, v1, 6, v0
	v_lshl_add_u32 v136, v14, 1, v0
	v_lshlrev_b32_e32 v0, 15, v8
	v_and_b32_e32 v0, 0xffff0000, v0
	s_waitcnt vmcnt(6)
	v_lshl_add_u32 v0, v10, 12, v0
	v_and_b32_e32 v1, 1, v8
	s_cselect_b64 s[10:11], -1, 0
	v_lshl_or_b32 v0, v1, 6, v0
	s_add_i32 s52, 0, 0x10000
	s_add_i32 s53, 0, 0x14000
	s_sext_i32_i16 s55, s2
	s_mov_b32 s50, 0
	s_ashr_i32 s51, s37, 31
	v_mov_b32_e32 v137, v133
	v_lshl_add_u32 v138, v11, 1, v0
	v_mov_b32_e32 v139, v133
	v_mov_b64_e32 v[140:141], 0x5c0
	v_mov_b64_e32 v[142:143], 0x5bf
	v_add_u32_e32 v155, s52, v153
	v_add_u32_e32 v156, s53, v153
	v_add_u32_e32 v157, 0, v3
	v_mov_b32_e32 v158, 0x358637bd
	s_movk_i32 s54, 0x2e00
	v_mov_b32_e32 v159, 0x3e38aa3b
	s_barrier
	s_branch .LBB0_147

; #define PG8_STAGE(bufoff, gbase, voff) do { _Pragma("unroll") for (int _i = 0; _i < 2; ++_i) \
;         __builtin_amdgcn_global_load_lds((const unsigned*)((const char*)(gbase) + (voff)[_i]), (PG8_LAS unsigned*)(lds + (bufoff) + ldsw + _i * 8192), 16, 0, 0); } while (0)
; #define PG8_LDA(dst, b, h) do { _Pragma("unroll") for (int m = 0; m < 4; ++m) _Pragma("unroll") for (int k = 0; k < 2; ++k) dst[m][k] = *(const PG8_LAS bf16x8*)(lds + PG8_SA(b, h) + aoff + m * 2048 + k * 1024); } while (0)
; #define PG8_LDB(dst, b, h) do { _Pragma("unroll") for (int n = 0; n < 2; ++n) _Pragma("unroll") for (int k = 0; k < 2; ++k) dst[n][k] = *(const PG8_LAS bf16x8*)(lds + PG8_SB(b, h) + boff + n * 2048 + k * 1024); } while (0)
; #define PG8_WAIT_V(n) asm volatile("s_waitcnt vmcnt(" #n ")" ::: "memory")
; #define PG8_WAIT_L(n) asm volatile("s_waitcnt lgkmcnt(" #n ")" ::: "memory")
; #define PG8_BAR __builtin_amdgcn_s_barrier()
; #define PG8_SCHED __builtin_amdgcn_sched_barrier(0)
; template <class Epi, class Sched, bool ALIGN_EPI = false, bool SP2 = false>
; __device__ __forceinline__ void gemm_phase(PG8_LAS unsigned char* lds, const Gemm g, const Sched& S, const Epi& E) {
;     ...
;         const bool has_next = S.next(ui + 1, nxt);
;         const char* nA = has_next ? (const char*)g.A + (size_t)nxt.pm * tstep : cA; const char* nB = has_next ? (const char*)g.Bt + (size_t)nxt.pn * tstep : cB;
;         for (int t = 0; t < nt; t += 2) {
;             const bool last = (t == nt - 2);
;             const char* a1 = cA + (size_t)(t + 1) * kstep;
;             const char* a2 = last ? nA : cA + (size_t)(t + 2) * kstep; const char* b2 = last ? nB : cB + (size_t)(t + 2) * kstep;
;             const char* a3 = a2 + kstep; const char* b3 = b2 + kstep;
;             if (last && has_next) S.a_ready(nxt);
;             if constexpr (SP2) {
;             PG8_LDB(B0, 0, 0); PG8_LDB(B1, 0, 1); PG8_SCHED; PG8_LDA(At, 0, 0); PG8_STAGE(PG8_SA(1, 1), a1 + hstep, voffA);
;             PG8_WAIT_V(8); PG8_WAIT_L(0); PG8_BAR; PG8_MMA(0, 0, At, B0); PG8_MMA(0, 1, At, B1); PG8_BAR; PG8_SCHED;
;             PG8_LDA(At, 0, 1); PG8_STAGE(PG8_SB(0, 0), b2, voffB); PG8_STAGE(PG8_SB(0, 1), b2 + hstep, voffB); PG8_STAGE(PG8_SA(0, 0), a2, voffA);
;             PG8_WAIT_V(8); PG8_WAIT_L(0); PG8_BAR; PG8_MMA(1, 0, At, B0); PG8_MMA(1, 1, At, B1); PG8_BAR; PG8_SCHED;
.LBB0_150:
	s_setprio 1
	ds_read_b128 v[144:147], v155
	ds_read_b128 v[148:151], v155 offset:1024
	ds_read_b128 v[160:163], v155 offset:2048
	ds_read_b128 v[164:167], v155 offset:3072
	ds_read_b128 v[168:171], v156
	ds_read_b128 v[172:175], v156 offset:1024
	ds_read_b128 v[176:179], v156 offset:2048
	ds_read_b128 v[180:183], v156 offset:3072
	s_add_u32 s30, s28, 0xfff80080
	s_addc_u32 s31, s29, -1
	s_cmp_eq_u32 s60, 28
	s_cselect_b32 s35, s15, s31
	s_cselect_b32 s34, s56, s30
	s_cselect_b32 s31, s13, s59
	s_cselect_b32 s30, s57, s58
	v_lshl_add_u64 v[216:217], s[28:29], 0, v[136:137]
	s_add_i32 m0, s25, 0xc000
	ds_read_b128 v[184:187], v157
	ds_read_b128 v[188:191], v157 offset:1024
	ds_read_b128 v[192:195], v157 offset:2048
	ds_read_b128 v[196:199], v157 offset:3072
	ds_read_b128 v[200:203], v157 offset:4096
	ds_read_b128 v[204:207], v157 offset:5120
	ds_read_b128 v[208:211], v157 offset:6144
	ds_read_b128 v[212:215], v157 offset:7168
	global_load_lds_dwordx4 v[216:217], off
	v_lshl_add_u64 v[216:217], s[28:29], 0, v[138:139]
	s_add_i32 m0, s25, 0xe000
	s_nop 0
	global_load_lds_dwordx4 v[216:217], off
	s_mov_b32 m0, s48
	s_nop 0
	global_load_lds_dwordx4 v[250:251], off
	s_mov_b32 m0, s49
	s_nop 0
	global_load_lds_dwordx4 v[252:253], off
	s_add_u32 s62, s30, 0x80000
	s_addc_u32 s63, s31, 0
	v_lshl_add_u64 v[216:217], s[30:31], 0, v[132:133]
	v_lshl_add_u64 v[218:219], s[30:31], 0, v[128:129]
	v_lshl_add_u64 v[246:247], s[62:63], 0, v[132:133]
	v_lshl_add_u64 v[222:223], s[34:35], 0, v[130:131]
	v_lshl_add_u64 v[248:249], s[62:63], 0, v[128:129]
	v_lshl_add_u64 v[220:221], s[34:35], 0, v[134:135]
	s_waitcnt vmcnt(10)
	s_waitcnt lgkmcnt(0)
	s_setprio 0
	s_barrier
	s_waitcnt lgkmcnt(0)
	v_mfma_f32_16x16x32_bf16 v[124:127], v[144:147], v[184:187], v[124:127]
	v_mfma_f32_16x16x32_bf16 v[120:123], v[160:163], v[184:187], v[120:123]
	v_mfma_f32_16x16x32_bf16 v[108:111], v[144:147], v[192:195], v[108:111]
	v_mfma_f32_16x16x32_bf16 v[104:107], v[160:163], v[192:195], v[104:107]
	v_mfma_f32_16x16x32_bf16 v[92:95], v[144:147], v[200:203], v[92:95]
	v_mfma_f32_16x16x32_bf16 v[88:91], v[160:163], v[200:203], v[88:91]
	v_mfma_f32_16x16x32_bf16 v[76:79], v[144:147], v[208:211], v[76:79]
	v_mfma_f32_16x16x32_bf16 v[72:75], v[160:163], v[208:211], v[72:75]
	v_mfma_f32_16x16x32_bf16 v[124:127], v[148:151], v[188:191], v[124:127]
	v_mfma_f32_16x16x32_bf16 v[120:123], v[164:167], v[188:191], v[120:123]
	v_mfma_f32_16x16x32_bf16 v[108:111], v[148:151], v[196:199], v[108:111]
	v_mfma_f32_16x16x32_bf16 v[104:107], v[164:167], v[196:199], v[104:107]
	v_mfma_f32_16x16x32_bf16 v[92:95], v[148:151], v[204:207], v[92:95]
	v_mfma_f32_16x16x32_bf16 v[88:91], v[164:167], v[204:207], v[88:91]
	v_mfma_f32_16x16x32_bf16 v[76:79], v[148:151], v[212:215], v[76:79]
	v_mfma_f32_16x16x32_bf16 v[72:75], v[164:167], v[212:215], v[72:75]
	v_mfma_f32_16x16x32_bf16 v[116:119], v[168:171], v[184:187], v[116:119]
	v_mfma_f32_16x16x32_bf16 v[112:115], v[176:179], v[184:187], v[112:115]
	v_mfma_f32_16x16x32_bf16 v[100:103], v[168:171], v[192:195], v[100:103]
	v_mfma_f32_16x16x32_bf16 v[96:99], v[176:179], v[192:195], v[96:99]
	v_mfma_f32_16x16x32_bf16 v[84:87], v[168:171], v[200:203], v[84:87]
	v_mfma_f32_16x16x32_bf16 v[80:83], v[176:179], v[200:203], v[80:83]
	v_mfma_f32_16x16x32_bf16 v[68:71], v[168:171], v[208:211], v[68:71]
	v_mfma_f32_16x16x32_bf16 v[64:67], v[176:179], v[208:211], v[64:67]
	v_mfma_f32_16x16x32_bf16 v[116:119], v[172:175], v[188:191], v[116:119]
	v_mfma_f32_16x16x32_bf16 v[112:115], v[180:183], v[188:191], v[112:115]
	v_mfma_f32_16x16x32_bf16 v[100:103], v[172:175], v[196:199], v[100:103]
	v_mfma_f32_16x16x32_bf16 v[96:99], v[180:183], v[196:199], v[96:99]
	v_mfma_f32_16x16x32_bf16 v[84:87], v[172:175], v[204:207], v[84:87]
	v_mfma_f32_16x16x32_bf16 v[80:83], v[180:183], v[204:207], v[80:83]
	v_mfma_f32_16x16x32_bf16 v[68:71], v[172:175], v[212:215], v[68:71]
	v_mfma_f32_16x16x32_bf16 v[64:67], v[180:183], v[212:215], v[64:67]
	s_barrier
	s_setprio 1
	s_add_i32 s61, s52, s42
	s_mov_b32 m0, s61
	ds_read_b128 v[184:187], v157 offset:16384
	ds_read_b128 v[188:191], v157 offset:17408
	ds_read_b128 v[192:195], v157 offset:18432
	ds_read_b128 v[196:199], v157 offset:19456
	ds_read_b128 v[200:203], v157 offset:20480
	ds_read_b128 v[204:207], v157 offset:21504
	ds_read_b128 v[208:211], v157 offset:22528
	ds_read_b128 v[212:215], v157 offset:23552
	global_load_lds_dwordx4 v[216:217], off
	s_add_i32 m0, s61, 0x2000
	s_add_i32 s61, s53, s42
	global_load_lds_dwordx4 v[218:219], off
	s_mov_b32 m0, s61
	s_nop 0
	global_load_lds_dwordx4 v[246:247], off
	s_add_i32 m0, s61, 0x2000
	s_nop 0
	global_load_lds_dwordx4 v[248:249], off
	s_waitcnt vmcnt(4)
	s_waitcnt lgkmcnt(0)
	s_setprio 0
	s_barrier
; #define PG8_STAGE(bufoff, gbase, voff) do { _Pragma("unroll") for (int _i = 0; _i < 2; ++_i) \
;         __builtin_amdgcn_global_load_lds((const unsigned*)((const char*)(gbase) + (voff)[_i]), (PG8_LAS unsigned*)(lds + (bufoff) + ldsw + _i * 8192), 16, 0, 0); } while (0)
; #define PG8_LDA(dst, b, h) do { _Pragma("unroll") for (int m = 0; m < 4; ++m) _Pragma("unroll") for (int k = 0; k < 2; ++k) dst[m][k] = *(const PG8_LAS bf16x8*)(lds + PG8_SA(b, h) + aoff + m * 2048 + k * 1024); } while (0)
; #define PG8_LDB(dst, b, h) do { _Pragma("unroll") for (int n = 0; n < 2; ++n) _Pragma("unroll") for (int k = 0; k < 2; ++k) dst[n][k] = *(const PG8_LAS bf16x8*)(lds + PG8_SB(b, h) + boff + n * 2048 + k * 1024); } while (0)
; #define PG8_MMA(ai, bj, At, Bt) do { __builtin_amdgcn_s_setprio(1); _Pragma("unroll") for (int m = 0; m < 4; ++m) _Pragma("unroll") for (int n = 0; n < 2; ++n) _Pragma("unroll") for (int k = 0; k < 2; ++k) \
;         acc[ai][bj][m][n] = __builtin_amdgcn_mfma_f32_16x16x32_bf16(Bt[n][k], At[m][k], acc[ai][bj][m][n], 0, 0, 0); __builtin_amdgcn_s_setprio(0); } while (0)
; #define PG8_WAIT_V(n) asm volatile("s_waitcnt vmcnt(" #n ")" ::: "memory")
; #define PG8_WAIT_L(n) asm volatile("s_waitcnt lgkmcnt(" #n ")" ::: "memory")
; #define PG8_BAR __builtin_amdgcn_s_barrier()
; #define PG8_SCHED __builtin_amdgcn_sched_barrier(0)
; template <class Epi, class Sched, bool ALIGN_EPI = false, bool SP2 = false>
; __device__ __forceinline__ void gemm_phase(PG8_LAS unsigned char* lds, const Gemm g, const Sched& S, const Epi& E) {
;     ...
;             PG8_LDA(At, 0, 1); PG8_STAGE(PG8_SB(0, 0), b2, voffB); PG8_STAGE(PG8_SB(0, 1), b2 + hstep, voffB); PG8_STAGE(PG8_SA(0, 0), a2, voffA);
;             PG8_WAIT_V(8); PG8_WAIT_L(0); PG8_BAR; PG8_MMA(1, 0, At, B0); PG8_MMA(1, 1, At, B1); PG8_BAR; PG8_SCHED;
;             PG8_LDB(B0, 1, 0); PG8_LDB(B1, 1, 1); PG8_SCHED; PG8_LDA(At, 1, 0); PG8_STAGE(PG8_SA(0, 1), a2 + hstep, voffA);
;             PG8_WAIT_V(8); PG8_WAIT_L(0); PG8_BAR; PG8_MMA(0, 0, At, B0); PG8_MMA(0, 1, At, B1); PG8_BAR; PG8_SCHED;
	s_waitcnt lgkmcnt(0)
	v_mfma_f32_16x16x32_bf16 v[60:63], v[144:147], v[184:187], v[60:63]
	v_mfma_f32_16x16x32_bf16 v[56:59], v[160:163], v[184:187], v[56:59]
	v_mfma_f32_16x16x32_bf16 v[44:47], v[144:147], v[192:195], v[44:47]
	v_mfma_f32_16x16x32_bf16 v[40:43], v[160:163], v[192:195], v[40:43]
	v_mfma_f32_16x16x32_bf16 v[28:31], v[144:147], v[200:203], v[28:31]
	v_mfma_f32_16x16x32_bf16 v[24:27], v[160:163], v[200:203], v[24:27]
	v_mfma_f32_16x16x32_bf16 v[12:15], v[144:147], v[208:211], v[12:15]
	v_mfma_f32_16x16x32_bf16 v[8:11], v[160:163], v[208:211], v[8:11]
	v_mfma_f32_16x16x32_bf16 v[60:63], v[148:151], v[188:191], v[60:63]
	v_mfma_f32_16x16x32_bf16 v[56:59], v[164:167], v[188:191], v[56:59]
	v_mfma_f32_16x16x32_bf16 v[44:47], v[148:151], v[196:199], v[44:47]
	v_mfma_f32_16x16x32_bf16 v[40:43], v[164:167], v[196:199], v[40:43]
	v_mfma_f32_16x16x32_bf16 v[28:31], v[148:151], v[204:207], v[28:31]
	v_mfma_f32_16x16x32_bf16 v[24:27], v[164:167], v[204:207], v[24:27]
	v_mfma_f32_16x16x32_bf16 v[12:15], v[148:151], v[212:215], v[12:15]
	v_mfma_f32_16x16x32_bf16 v[8:11], v[164:167], v[212:215], v[8:11]
	v_mfma_f32_16x16x32_bf16 v[52:55], v[168:171], v[184:187], v[52:55]
	v_mfma_f32_16x16x32_bf16 v[48:51], v[176:179], v[184:187], v[48:51]
	v_mfma_f32_16x16x32_bf16 v[36:39], v[168:171], v[192:195], v[36:39]
	v_mfma_f32_16x16x32_bf16 v[32:35], v[176:179], v[192:195], v[32:35]
	v_mfma_f32_16x16x32_bf16 v[20:23], v[168:171], v[200:203], v[20:23]
	v_mfma_f32_16x16x32_bf16 v[16:19], v[176:179], v[200:203], v[16:19]
	v_mfma_f32_16x16x32_bf16 v[4:7], v[168:171], v[208:211], v[4:7]
	v_mfma_f32_16x16x32_bf16 v[0:3], v[176:179], v[208:211], v[0:3]
	v_mfma_f32_16x16x32_bf16 v[52:55], v[172:175], v[188:191], v[52:55]
	v_mfma_f32_16x16x32_bf16 v[48:51], v[180:183], v[188:191], v[48:51]
	v_mfma_f32_16x16x32_bf16 v[36:39], v[172:175], v[196:199], v[36:39]
	v_mfma_f32_16x16x32_bf16 v[32:35], v[180:183], v[196:199], v[32:35]
	v_mfma_f32_16x16x32_bf16 v[20:23], v[172:175], v[204:207], v[20:23]
	v_mfma_f32_16x16x32_bf16 v[16:19], v[180:183], v[204:207], v[16:19]
	v_mfma_f32_16x16x32_bf16 v[4:7], v[172:175], v[212:215], v[4:7]
	v_mfma_f32_16x16x32_bf16 v[0:3], v[180:183], v[212:215], v[0:3]
	s_barrier
	s_setprio 1
	s_add_i32 s61, 0, 0x18000
	s_add_i32 s62, 0, 0x1c000
	v_add_u32_e32 v164, s61, v153
	v_add_u32_e32 v180, s62, v153
	ds_read_b128 v[144:147], v164
	ds_read_b128 v[148:151], v164 offset:1024
	ds_read_b128 v[160:163], v164 offset:2048
	ds_read_b128 v[164:167], v164 offset:3072
	ds_read_b128 v[168:171], v180
	ds_read_b128 v[172:175], v180 offset:1024
	ds_read_b128 v[176:179], v180 offset:2048
	ds_read_b128 v[180:183], v180 offset:3072
	s_add_u32 s34, s34, 0x80000
	s_addc_u32 s35, s35, 0
	s_mov_b32 m0, s46
	v_lshl_add_u64 v[224:225], s[34:35], 0, v[134:135]
	ds_read_b128 v[184:187], v157 offset:32768
	ds_read_b128 v[188:191], v157 offset:33792
	ds_read_b128 v[192:195], v157 offset:34816
	ds_read_b128 v[196:199], v157 offset:35840
	ds_read_b128 v[200:203], v157 offset:36864
	ds_read_b128 v[204:207], v157 offset:37888
	ds_read_b128 v[208:211], v157 offset:38912
	ds_read_b128 v[212:215], v157 offset:39936
	global_load_lds_dwordx4 v[224:225], off
	v_lshl_add_u64 v[224:225], s[34:35], 0, v[130:131]
	s_mov_b32 m0, s47
	s_nop 0
	global_load_lds_dwordx4 v[224:225], off
	s_mov_b32 m0, s25
	s_nop 0
	global_load_lds_dwordx4 v[220:221], off
	s_mov_b32 m0, s45
	s_nop 0
	global_load_lds_dwordx4 v[222:223], off
	s_add_u32 s30, s30, 0x80080
	s_addc_u32 s31, s31, 0
	v_lshl_add_u64 v[216:217], v[216:217], 0, s[8:9]
	v_lshl_add_u64 v[218:219], v[218:219], 0, s[8:9]
	v_lshl_add_u64 v[246:247], s[30:31], 0, v[132:133]
	v_lshl_add_u64 v[248:249], s[30:31], 0, v[128:129]
	v_lshl_add_u64 v[250:251], v[220:221], 0, s[8:9]
	v_lshl_add_u64 v[252:253], v[222:223], 0, s[8:9]
	s_waitcnt vmcnt(10)
	s_waitcnt lgkmcnt(0)
	s_setprio 0
	s_barrier
; #define PG8_STAGE(bufoff, gbase, voff) do { _Pragma("unroll") for (int _i = 0; _i < 2; ++_i) \
;         __builtin_amdgcn_global_load_lds((const unsigned*)((const char*)(gbase) + (voff)[_i]), (PG8_LAS unsigned*)(lds + (bufoff) + ldsw + _i * 8192), 16, 0, 0); } while (0)
; #define PG8_LDA(dst, b, h) do { _Pragma("unroll") for (int m = 0; m < 4; ++m) _Pragma("unroll") for (int k = 0; k < 2; ++k) dst[m][k] = *(const PG8_LAS bf16x8*)(lds + PG8_SA(b, h) + aoff + m * 2048 + k * 1024); } while (0)
; #define PG8_MMA(ai, bj, At, Bt) do { __builtin_amdgcn_s_setprio(1); _Pragma("unroll") for (int m = 0; m < 4; ++m) _Pragma("unroll") for (int n = 0; n < 2; ++n) _Pragma("unroll") for (int k = 0; k < 2; ++k) \
;         acc[ai][bj][m][n] = __builtin_amdgcn_mfma_f32_16x16x32_bf16(Bt[n][k], At[m][k], acc[ai][bj][m][n], 0, 0, 0); __builtin_amdgcn_s_setprio(0); } while (0)
; #define PG8_WAIT_V(n) asm volatile("s_waitcnt vmcnt(" #n ")" ::: "memory")
; #define PG8_WAIT_L(n) asm volatile("s_waitcnt lgkmcnt(" #n ")" ::: "memory")
; #define PG8_BAR __builtin_amdgcn_s_barrier()
; #define PG8_SCHED __builtin_amdgcn_sched_barrier(0)
; template <class Epi, class Sched, bool ALIGN_EPI = false, bool SP2 = false>
; __device__ __forceinline__ void gemm_phase(PG8_LAS unsigned char* lds, const Gemm g, const Sched& S, const Epi& E) {
;     ...
;             PG8_WAIT_V(8); PG8_WAIT_L(0); PG8_BAR; PG8_MMA(0, 0, At, B0); PG8_MMA(0, 1, At, B1); PG8_BAR; PG8_SCHED;
;             PG8_LDA(At, 1, 1); PG8_STAGE(PG8_SB(1, 0), b3, voffB); PG8_STAGE(PG8_SB(1, 1), b3 + hstep, voffB); PG8_STAGE(PG8_SA(1, 0), a3, voffA);
;             PG8_WAIT_V(8); PG8_WAIT_L(0); PG8_BAR; PG8_MMA(1, 0, At, B0); PG8_MMA(1, 1, At, B1); PG8_BAR; PG8_SCHED;
;     ...
;         if constexpr (ALIGN_EPI) { if (wr == 0) PG8_BAR; }
	s_waitcnt lgkmcnt(0)
	v_mfma_f32_16x16x32_bf16 v[124:127], v[144:147], v[184:187], v[124:127]
	v_mfma_f32_16x16x32_bf16 v[120:123], v[160:163], v[184:187], v[120:123]
	v_mfma_f32_16x16x32_bf16 v[108:111], v[144:147], v[192:195], v[108:111]
	v_mfma_f32_16x16x32_bf16 v[104:107], v[160:163], v[192:195], v[104:107]
	v_mfma_f32_16x16x32_bf16 v[92:95], v[144:147], v[200:203], v[92:95]
	v_mfma_f32_16x16x32_bf16 v[88:91], v[160:163], v[200:203], v[88:91]
	v_mfma_f32_16x16x32_bf16 v[76:79], v[144:147], v[208:211], v[76:79]
	v_mfma_f32_16x16x32_bf16 v[72:75], v[160:163], v[208:211], v[72:75]
	v_mfma_f32_16x16x32_bf16 v[124:127], v[148:151], v[188:191], v[124:127]
	v_mfma_f32_16x16x32_bf16 v[120:123], v[164:167], v[188:191], v[120:123]
	v_mfma_f32_16x16x32_bf16 v[108:111], v[148:151], v[196:199], v[108:111]
	v_mfma_f32_16x16x32_bf16 v[104:107], v[164:167], v[196:199], v[104:107]
	v_mfma_f32_16x16x32_bf16 v[92:95], v[148:151], v[204:207], v[92:95]
	v_mfma_f32_16x16x32_bf16 v[88:91], v[164:167], v[204:207], v[88:91]
	v_mfma_f32_16x16x32_bf16 v[76:79], v[148:151], v[212:215], v[76:79]
	v_mfma_f32_16x16x32_bf16 v[72:75], v[164:167], v[212:215], v[72:75]
	v_mfma_f32_16x16x32_bf16 v[116:119], v[168:171], v[184:187], v[116:119]
	v_mfma_f32_16x16x32_bf16 v[112:115], v[176:179], v[184:187], v[112:115]
	v_mfma_f32_16x16x32_bf16 v[100:103], v[168:171], v[192:195], v[100:103]
	v_mfma_f32_16x16x32_bf16 v[96:99], v[176:179], v[192:195], v[96:99]
	v_mfma_f32_16x16x32_bf16 v[84:87], v[168:171], v[200:203], v[84:87]
	v_mfma_f32_16x16x32_bf16 v[80:83], v[176:179], v[200:203], v[80:83]
	v_mfma_f32_16x16x32_bf16 v[68:71], v[168:171], v[208:211], v[68:71]
	v_mfma_f32_16x16x32_bf16 v[64:67], v[176:179], v[208:211], v[64:67]
	v_mfma_f32_16x16x32_bf16 v[116:119], v[172:175], v[188:191], v[116:119]
	v_mfma_f32_16x16x32_bf16 v[112:115], v[180:183], v[188:191], v[112:115]
	v_mfma_f32_16x16x32_bf16 v[100:103], v[172:175], v[196:199], v[100:103]
	v_mfma_f32_16x16x32_bf16 v[96:99], v[180:183], v[196:199], v[96:99]
	v_mfma_f32_16x16x32_bf16 v[84:87], v[172:175], v[204:207], v[84:87]
	v_mfma_f32_16x16x32_bf16 v[80:83], v[180:183], v[204:207], v[80:83]
	v_mfma_f32_16x16x32_bf16 v[68:71], v[172:175], v[212:215], v[68:71]
	v_mfma_f32_16x16x32_bf16 v[64:67], v[180:183], v[212:215], v[64:67]
	s_barrier
	s_setprio 1
	s_add_i32 s34, s61, s42
	s_mov_b32 m0, s34
	ds_read_b128 v[184:187], v157 offset:49152
	ds_read_b128 v[188:191], v157 offset:50176
	ds_read_b128 v[192:195], v157 offset:51200
	ds_read_b128 v[196:199], v157 offset:52224
	ds_read_b128 v[200:203], v157 offset:53248
	ds_read_b128 v[204:207], v157 offset:54272
	ds_read_b128 v[208:211], v157 offset:55296
	ds_read_b128 v[212:215], v157 offset:56320
	global_load_lds_dwordx4 v[216:217], off
	s_add_i32 m0, s34, 0x2000
	s_add_i32 s34, s62, s42
	global_load_lds_dwordx4 v[218:219], off
	s_mov_b32 m0, s34
	s_nop 0
	global_load_lds_dwordx4 v[246:247], off
	s_add_i32 m0, s34, 0x2000
	s_nop 0
	global_load_lds_dwordx4 v[248:249], off
	s_waitcnt vmcnt(4)
	s_waitcnt lgkmcnt(0)
	s_setprio 0
	s_barrier
	s_waitcnt lgkmcnt(0)
	v_mfma_f32_16x16x32_bf16 v[60:63], v[144:147], v[184:187], v[60:63]
	v_mfma_f32_16x16x32_bf16 v[56:59], v[160:163], v[184:187], v[56:59]
	v_mfma_f32_16x16x32_bf16 v[44:47], v[144:147], v[192:195], v[44:47]
	v_mfma_f32_16x16x32_bf16 v[40:43], v[160:163], v[192:195], v[40:43]
	v_mfma_f32_16x16x32_bf16 v[28:31], v[144:147], v[200:203], v[28:31]
	v_mfma_f32_16x16x32_bf16 v[24:27], v[160:163], v[200:203], v[24:27]
	v_mfma_f32_16x16x32_bf16 v[12:15], v[144:147], v[208:211], v[12:15]
	v_mfma_f32_16x16x32_bf16 v[8:11], v[160:163], v[208:211], v[8:11]
	v_mfma_f32_16x16x32_bf16 v[60:63], v[148:151], v[188:191], v[60:63]
	v_mfma_f32_16x16x32_bf16 v[56:59], v[164:167], v[188:191], v[56:59]
	v_mfma_f32_16x16x32_bf16 v[44:47], v[148:151], v[196:199], v[44:47]
	v_mfma_f32_16x16x32_bf16 v[40:43], v[164:167], v[196:199], v[40:43]
	v_mfma_f32_16x16x32_bf16 v[28:31], v[148:151], v[204:207], v[28:31]
	v_mfma_f32_16x16x32_bf16 v[24:27], v[164:167], v[204:207], v[24:27]
	v_mfma_f32_16x16x32_bf16 v[12:15], v[148:151], v[212:215], v[12:15]
	v_mfma_f32_16x16x32_bf16 v[8:11], v[164:167], v[212:215], v[8:11]
	v_mfma_f32_16x16x32_bf16 v[52:55], v[168:171], v[184:187], v[52:55]
	v_mfma_f32_16x16x32_bf16 v[48:51], v[176:179], v[184:187], v[48:51]
	v_mfma_f32_16x16x32_bf16 v[36:39], v[168:171], v[192:195], v[36:39]
	v_mfma_f32_16x16x32_bf16 v[32:35], v[176:179], v[192:195], v[32:35]
	v_mfma_f32_16x16x32_bf16 v[20:23], v[168:171], v[200:203], v[20:23]
	v_mfma_f32_16x16x32_bf16 v[16:19], v[176:179], v[200:203], v[16:19]
	v_mfma_f32_16x16x32_bf16 v[4:7], v[168:171], v[208:211], v[4:7]
	v_mfma_f32_16x16x32_bf16 v[0:3], v[176:179], v[208:211], v[0:3]
	v_mfma_f32_16x16x32_bf16 v[52:55], v[172:175], v[188:191], v[52:55]
	v_mfma_f32_16x16x32_bf16 v[48:51], v[180:183], v[188:191], v[48:51]
	v_mfma_f32_16x16x32_bf16 v[36:39], v[172:175], v[196:199], v[36:39]
	v_mfma_f32_16x16x32_bf16 v[32:35], v[180:183], v[196:199], v[32:35]
	v_mfma_f32_16x16x32_bf16 v[20:23], v[172:175], v[204:207], v[20:23]
	v_mfma_f32_16x16x32_bf16 v[16:19], v[180:183], v[204:207], v[16:19]
	v_mfma_f32_16x16x32_bf16 v[4:7], v[172:175], v[212:215], v[4:7]
	v_mfma_f32_16x16x32_bf16 v[0:3], v[180:183], v[212:215], v[0:3]
	s_barrier
	s_add_i32 s60, s60, 2
	s_add_u32 s28, s28, 0x100
	s_addc_u32 s29, s29, 0
	s_add_u32 s58, s58, 0x100
	s_addc_u32 s59, s59, 0
	s_cmp_gt_u32 s60, 29
	s_cbranch_scc0 .LBB0_150
	s_and_b64 vcc, exec, s[10:11]
	s_cbranch_vccz .LBB0_153
	s_barrier

; #define PG8_STAGE(bufoff, gbase, voff) do { _Pragma("unroll") for (int _i = 0; _i < 2; ++_i) \
;         __builtin_amdgcn_global_load_lds((const unsigned*)((const char*)(gbase) + (voff)[_i]), (PG8_LAS unsigned*)(lds + (bufoff) + ldsw + _i * 8192), 16, 0, 0); } while (0)
; #define PG8_WAIT_V(n) asm volatile("s_waitcnt vmcnt(" #n ")" ::: "memory")
; #define PG8_BAR __builtin_amdgcn_s_barrier()
; template <class Epi, class Sched, bool ALIGN_EPI = false, bool SP2 = false>
; __device__ __forceinline__ void gemm_phase(PG8_LAS unsigned char* lds, const Gemm g, const Sched& S, const Epi& E) {
;     ...
;     const unsigned ldsw = (unsigned)wid * 1024u;
;     const int aoff = lds_byte(wr * 64 + fr, fq * 8), boff = lds_byte(wc * 32 + fr, fq * 8);
;     ...
;     Unit cur, nxt; int ui = 0;
;     if (!S.next(0, cur)) return;
;     f32x4 acc[2][2][4][2];
; #pragma unroll
;     for (int a = 0; a < 2; ++a)
; #pragma unroll
;         for (int b = 0; b < 2; ++b)
; #pragma unroll
;             for (int m = 0; m < 4; ++m)
; #pragma unroll
;                 for (int n = 0; n < 2; ++n) acc[a][b][m][n] = (f32x4){0.f, 0.f, 0.f, 0.f};
;     bf16x8 At[4][2], B0[2][2], B1[2][2];
;     const char* cA = (const char*)g.A + (size_t)cur.pm * tstep; const char* cB = (const char*)g.Bt + (size_t)cur.pn * tstep;
;     S.a_ready(cur);
;     if constexpr (SP2) {
;         PG8_STAGE(PG8_SB(0, 0), cB, voffB); PG8_STAGE(PG8_SB(0, 1), cB + hstep, voffB); PG8_STAGE(PG8_SA(0, 0), cA, voffA); PG8_STAGE(PG8_SA(0, 1), cA + hstep, voffA);
;         if (wr == 1) PG8_BAR;
;         PG8_WAIT_V(2); PG8_BAR;
;         PG8_STAGE(PG8_SB(1, 0), cB + kstep, voffB); PG8_STAGE(PG8_SA(1, 0), cA + kstep, voffA); PG8_STAGE(PG8_SB(1, 1), cB + hstep + kstep, voffB);
;         PG8_WAIT_V(6); PG8_BAR;
.LBB0_611:
	s_add_u32 s6, s8, 0x18600000
	s_addc_u32 s7, s5, 0
	s_add_u32 s8, s8, 0x34f20000
	s_addc_u32 s9, s5, 0
	s_lshl_b32 s3, s3, 5
	s_mov_b64 s[10:11], 0x80
	s_and_b32 s14, s3, 0x60
	s_add_i32 m0, s31, 0x18000
	v_lshl_add_u64 v[6:7], v[6:7], 0, s[10:11]
	s_lshl_b32 s5, s2, 13
	s_lshl_b32 s3, s14, 7
	s_waitcnt vmcnt(2)
	s_barrier
	global_load_lds_dwordx4 v[6:7], off
	v_lshl_add_u64 v[4:5], v[4:5], 0, s[10:11]
	s_add_i32 m0, s31, 0x1a000
	s_add_i32 s50, s31, 0x8000
	s_add_i32 s51, s31, 0xa000
	global_load_lds_dwordx4 v[4:5], off
	v_lshl_add_u64 v[0:1], v[0:1], 0, s[10:11]
	s_mov_b32 m0, s50
	s_add_u32 s12, s36, 0x80080
	global_load_lds_dwordx4 v[0:1], off
	v_mov_b64_e32 v[250:251], v[0:1]
	v_lshl_add_u64 v[0:1], v[2:3], 0, s[10:11]
	s_mov_b32 m0, s51
	s_addc_u32 s13, s37, 0
	global_load_lds_dwordx4 v[0:1], off
	v_mov_b64_e32 v[252:253], v[0:1]
	s_add_i32 m0, s31, 0x1c000
	v_lshl_add_u64 v[0:1], s[12:13], 0, v[154:155]
	global_load_lds_dwordx4 v[0:1], off
	v_lshl_add_u64 v[0:1], s[12:13], 0, v[158:159]
	s_add_i32 m0, s31, 0x1e000
	s_cmpk_lt_u32 s4, 0x100
	global_load_lds_dwordx4 v[0:1], off
	v_bfe_u32 v0, v8, 4, 2
	v_and_b32_e32 v1, 15, v8
	v_lshlrev_b32_e32 v2, 4, v0
	v_lshl_or_b32 v186, s2, 6, v1
	v_lshl_or_b32 v1, v1, 6, v2
	v_lshlrev_b32_e32 v2, 2, v8
	v_and_b32_e32 v2, 32, v2
	v_bitop3_b32 v187, v1, s3, v2 bitop3:0xde
	v_cmp_eq_u32_e64 s[2:3], 0, v0
	v_lshl_or_b32 v188, v0, 3, s14
	v_lshlrev_b32_e32 v0, 15, v9
	v_and_b32_e32 v0, 0xffff0000, v0
	v_bitop3_b32 v3, v1, s5, v2 bitop3:0xde
	v_lshl_add_u32 v0, v10, 12, v0
	v_and_b32_e32 v1, 1, v9
	v_lshl_or_b32 v0, v1, 6, v0
	v_lshl_add_u32 v160, v11, 1, v0
	v_lshlrev_b32_e32 v0, 15, v12
	v_and_b32_e32 v0, 0xffff0000, v0
	s_waitcnt vmcnt(6)
	v_lshl_add_u32 v0, v13, 12, v0
	v_and_b32_e32 v1, 1, v12
	s_cselect_b64 s[12:13], -1, 0
	v_lshl_or_b32 v0, v1, 6, v0
	s_add_i32 s54, 0, 0x10000
	s_add_i32 s55, 0, 0x14000
	s_ashr_i32 s52, s40, 31
	s_ashr_i32 s53, s33, 31
	v_mov_b32_e32 v161, v155
	v_lshl_add_u32 v162, v14, 1, v0
	v_mov_b32_e32 v163, v155
	v_mov_b64_e32 v[164:165], 0x200
	v_mov_b64_e32 v[166:167], 0x1ff
	v_add_u32_e32 v189, s54, v187
	v_add_u32_e32 v190, s55, v187
	v_add_u32_e32 v191, 0, v3
	s_mov_b32 s56, 0x4b800000
	s_barrier
	s_branch .LBB0_614

; #define PG8_STAGE(bufoff, gbase, voff) do { _Pragma("unroll") for (int _i = 0; _i < 2; ++_i) \
;         __builtin_amdgcn_global_load_lds((const unsigned*)((const char*)(gbase) + (voff)[_i]), (PG8_LAS unsigned*)(lds + (bufoff) + ldsw + _i * 8192), 16, 0, 0); } while (0)
; #define PG8_LDA(dst, b, h) do { _Pragma("unroll") for (int m = 0; m < 4; ++m) _Pragma("unroll") for (int k = 0; k < 2; ++k) dst[m][k] = *(const PG8_LAS bf16x8*)(lds + PG8_SA(b, h) + aoff + m * 2048 + k * 1024); } while (0)
; #define PG8_LDB(dst, b, h) do { _Pragma("unroll") for (int n = 0; n < 2; ++n) _Pragma("unroll") for (int k = 0; k < 2; ++k) dst[n][k] = *(const PG8_LAS bf16x8*)(lds + PG8_SB(b, h) + boff + n * 2048 + k * 1024); } while (0)
; #define PG8_WAIT_V(n) asm volatile("s_waitcnt vmcnt(" #n ")" ::: "memory")
; #define PG8_WAIT_L(n) asm volatile("s_waitcnt lgkmcnt(" #n ")" ::: "memory")
; #define PG8_BAR __builtin_amdgcn_s_barrier()
; #define PG8_SCHED __builtin_amdgcn_sched_barrier(0)
; template <class Epi, class Sched, bool ALIGN_EPI = false, bool SP2 = false>
; __device__ __forceinline__ void gemm_phase(PG8_LAS unsigned char* lds, const Gemm g, const Sched& S, const Epi& E) {
;     ...
;         const bool has_next = S.next(ui + 1, nxt);
;         const char* nA = has_next ? (const char*)g.A + (size_t)nxt.pm * tstep : cA; const char* nB = has_next ? (const char*)g.Bt + (size_t)nxt.pn * tstep : cB;
;         for (int t = 0; t < nt; t += 2) {
;             const bool last = (t == nt - 2);
;             const char* a1 = cA + (size_t)(t + 1) * kstep;
;             const char* a2 = last ? nA : cA + (size_t)(t + 2) * kstep; const char* b2 = last ? nB : cB + (size_t)(t + 2) * kstep;
;             const char* a3 = a2 + kstep; const char* b3 = b2 + kstep;
;             if (last && has_next) S.a_ready(nxt);
;             if constexpr (SP2) {
;             PG8_LDB(B0, 0, 0); PG8_LDB(B1, 0, 1); PG8_SCHED; PG8_LDA(At, 0, 0); PG8_STAGE(PG8_SA(1, 1), a1 + hstep, voffA);
;             PG8_WAIT_V(8); PG8_WAIT_L(0); PG8_BAR; PG8_MMA(0, 0, At, B0); PG8_MMA(0, 1, At, B1); PG8_BAR; PG8_SCHED;
;             PG8_LDA(At, 0, 1); PG8_STAGE(PG8_SB(0, 0), b2, voffB); PG8_STAGE(PG8_SB(0, 1), b2 + hstep, voffB); PG8_STAGE(PG8_SA(0, 0), a2, voffA);
;             PG8_WAIT_V(8); PG8_WAIT_L(0); PG8_BAR; PG8_MMA(1, 0, At, B0); PG8_MMA(1, 1, At, B1); PG8_BAR; PG8_SCHED;
.LBB0_621:
	s_setprio 1
	ds_read_b128 v[128:131], v189
	ds_read_b128 v[132:135], v189 offset:1024
	ds_read_b128 v[136:139], v189 offset:2048
	ds_read_b128 v[140:143], v189 offset:3072
	ds_read_b128 v[144:147], v190
	ds_read_b128 v[148:151], v190 offset:1024
	ds_read_b128 v[168:171], v190 offset:2048
	ds_read_b128 v[172:175], v190 offset:3072
	s_add_u32 s36, s34, 0xfff80080
	s_addc_u32 s37, s35, -1
	s_cmp_eq_u32 s60, 28
	s_cselect_b32 s39, s17, s37
	s_cselect_b32 s38, s29, s36
	s_cselect_b32 s37, s15, s59
	s_cselect_b32 s36, s57, s58
	v_lshl_add_u64 v[184:185], s[34:35], 0, v[160:161]
	s_add_i32 m0, s31, 0xc000
	ds_read_b128 v[176:179], v191
	ds_read_b128 v[180:183], v191 offset:1024
	ds_read_b128 v[192:195], v191 offset:2048
	ds_read_b128 v[196:199], v191 offset:3072
	ds_read_b128 v[200:203], v191 offset:4096
	ds_read_b128 v[204:207], v191 offset:5120
	ds_read_b128 v[208:211], v191 offset:6144
	ds_read_b128 v[212:215], v191 offset:7168
	global_load_lds_dwordx4 v[184:185], off
	v_lshl_add_u64 v[184:185], s[34:35], 0, v[162:163]
	s_add_i32 m0, s31, 0xe000
	s_nop 0
	global_load_lds_dwordx4 v[184:185], off
	s_mov_b32 m0, s50
	s_nop 0
	global_load_lds_dwordx4 v[250:251], off
	s_mov_b32 m0, s51
	s_nop 0
	global_load_lds_dwordx4 v[252:253], off
	s_add_u32 s62, s36, 0x80000
	s_addc_u32 s63, s37, 0
	v_lshl_add_u64 v[184:185], s[36:37], 0, v[154:155]
	v_lshl_add_u64 v[216:217], s[36:37], 0, v[158:159]
	v_lshl_add_u64 v[246:247], s[62:63], 0, v[154:155]
	v_lshl_add_u64 v[220:221], s[38:39], 0, v[156:157]
	v_lshl_add_u64 v[248:249], s[62:63], 0, v[158:159]
	v_lshl_add_u64 v[218:219], s[38:39], 0, v[152:153]
	s_waitcnt vmcnt(10)
	s_waitcnt lgkmcnt(0)
	s_setprio 0
	s_barrier
	s_waitcnt lgkmcnt(0)
	v_mfma_f32_16x16x32_bf16 v[124:127], v[128:131], v[176:179], v[124:127]
	v_mfma_f32_16x16x32_bf16 v[120:123], v[136:139], v[176:179], v[120:123]
	v_mfma_f32_16x16x32_bf16 v[108:111], v[128:131], v[192:195], v[108:111]
	v_mfma_f32_16x16x32_bf16 v[104:107], v[136:139], v[192:195], v[104:107]
	v_mfma_f32_16x16x32_bf16 v[92:95], v[128:131], v[200:203], v[92:95]
	v_mfma_f32_16x16x32_bf16 v[88:91], v[136:139], v[200:203], v[88:91]
	v_mfma_f32_16x16x32_bf16 v[76:79], v[128:131], v[208:211], v[76:79]
	v_mfma_f32_16x16x32_bf16 v[72:75], v[136:139], v[208:211], v[72:75]
	v_mfma_f32_16x16x32_bf16 v[124:127], v[132:135], v[180:183], v[124:127]
	v_mfma_f32_16x16x32_bf16 v[120:123], v[140:143], v[180:183], v[120:123]
	v_mfma_f32_16x16x32_bf16 v[108:111], v[132:135], v[196:199], v[108:111]
	v_mfma_f32_16x16x32_bf16 v[104:107], v[140:143], v[196:199], v[104:107]
	v_mfma_f32_16x16x32_bf16 v[92:95], v[132:135], v[204:207], v[92:95]
	v_mfma_f32_16x16x32_bf16 v[88:91], v[140:143], v[204:207], v[88:91]
	v_mfma_f32_16x16x32_bf16 v[76:79], v[132:135], v[212:215], v[76:79]
	v_mfma_f32_16x16x32_bf16 v[72:75], v[140:143], v[212:215], v[72:75]
	v_mfma_f32_16x16x32_bf16 v[116:119], v[144:147], v[176:179], v[116:119]
	v_mfma_f32_16x16x32_bf16 v[112:115], v[168:171], v[176:179], v[112:115]
	v_mfma_f32_16x16x32_bf16 v[100:103], v[144:147], v[192:195], v[100:103]
	v_mfma_f32_16x16x32_bf16 v[96:99], v[168:171], v[192:195], v[96:99]
	v_mfma_f32_16x16x32_bf16 v[84:87], v[144:147], v[200:203], v[84:87]
	v_mfma_f32_16x16x32_bf16 v[80:83], v[168:171], v[200:203], v[80:83]
	v_mfma_f32_16x16x32_bf16 v[68:71], v[144:147], v[208:211], v[68:71]
	v_mfma_f32_16x16x32_bf16 v[64:67], v[168:171], v[208:211], v[64:67]
	v_mfma_f32_16x16x32_bf16 v[116:119], v[148:151], v[180:183], v[116:119]
	v_mfma_f32_16x16x32_bf16 v[112:115], v[172:175], v[180:183], v[112:115]
	v_mfma_f32_16x16x32_bf16 v[100:103], v[148:151], v[196:199], v[100:103]
	v_mfma_f32_16x16x32_bf16 v[96:99], v[172:175], v[196:199], v[96:99]
	v_mfma_f32_16x16x32_bf16 v[84:87], v[148:151], v[204:207], v[84:87]
	v_mfma_f32_16x16x32_bf16 v[80:83], v[172:175], v[204:207], v[80:83]
	v_mfma_f32_16x16x32_bf16 v[68:71], v[148:151], v[212:215], v[68:71]
	v_mfma_f32_16x16x32_bf16 v[64:67], v[172:175], v[212:215], v[64:67]
	s_barrier
	s_setprio 1
	s_add_i32 s61, s54, s45
	s_mov_b32 m0, s61
	ds_read_b128 v[176:179], v191 offset:16384
	ds_read_b128 v[180:183], v191 offset:17408
	ds_read_b128 v[192:195], v191 offset:18432
	ds_read_b128 v[196:199], v191 offset:19456
	ds_read_b128 v[200:203], v191 offset:20480
	ds_read_b128 v[204:207], v191 offset:21504
	ds_read_b128 v[208:211], v191 offset:22528
	ds_read_b128 v[212:215], v191 offset:23552
	global_load_lds_dwordx4 v[184:185], off
	s_add_i32 m0, s61, 0x2000
	s_add_i32 s61, s55, s45
	global_load_lds_dwordx4 v[216:217], off
	s_mov_b32 m0, s61
	s_nop 0
	global_load_lds_dwordx4 v[246:247], off
	s_add_i32 m0, s61, 0x2000
	s_nop 0
	global_load_lds_dwordx4 v[248:249], off
	s_waitcnt vmcnt(4)
	s_waitcnt lgkmcnt(0)
	s_setprio 0
	s_barrier
; #define PG8_STAGE(bufoff, gbase, voff) do { _Pragma("unroll") for (int _i = 0; _i < 2; ++_i) \
;         __builtin_amdgcn_global_load_lds((const unsigned*)((const char*)(gbase) + (voff)[_i]), (PG8_LAS unsigned*)(lds + (bufoff) + ldsw + _i * 8192), 16, 0, 0); } while (0)
; #define PG8_LDA(dst, b, h) do { _Pragma("unroll") for (int m = 0; m < 4; ++m) _Pragma("unroll") for (int k = 0; k < 2; ++k) dst[m][k] = *(const PG8_LAS bf16x8*)(lds + PG8_SA(b, h) + aoff + m * 2048 + k * 1024); } while (0)
; #define PG8_LDB(dst, b, h) do { _Pragma("unroll") for (int n = 0; n < 2; ++n) _Pragma("unroll") for (int k = 0; k < 2; ++k) dst[n][k] = *(const PG8_LAS bf16x8*)(lds + PG8_SB(b, h) + boff + n * 2048 + k * 1024); } while (0)
; #define PG8_MMA(ai, bj, At, Bt) do { __builtin_amdgcn_s_setprio(1); _Pragma("unroll") for (int m = 0; m < 4; ++m) _Pragma("unroll") for (int n = 0; n < 2; ++n) _Pragma("unroll") for (int k = 0; k < 2; ++k) \
;         acc[ai][bj][m][n] = __builtin_amdgcn_mfma_f32_16x16x32_bf16(Bt[n][k], At[m][k], acc[ai][bj][m][n], 0, 0, 0); __builtin_amdgcn_s_setprio(0); } while (0)
; #define PG8_WAIT_V(n) asm volatile("s_waitcnt vmcnt(" #n ")" ::: "memory")
; #define PG8_WAIT_L(n) asm volatile("s_waitcnt lgkmcnt(" #n ")" ::: "memory")
; #define PG8_BAR __builtin_amdgcn_s_barrier()
; #define PG8_SCHED __builtin_amdgcn_sched_barrier(0)
; template <class Epi, class Sched, bool ALIGN_EPI = false, bool SP2 = false>
; __device__ __forceinline__ void gemm_phase(PG8_LAS unsigned char* lds, const Gemm g, const Sched& S, const Epi& E) {
;     ...
;             PG8_LDA(At, 0, 1); PG8_STAGE(PG8_SB(0, 0), b2, voffB); PG8_STAGE(PG8_SB(0, 1), b2 + hstep, voffB); PG8_STAGE(PG8_SA(0, 0), a2, voffA);
;             PG8_WAIT_V(8); PG8_WAIT_L(0); PG8_BAR; PG8_MMA(1, 0, At, B0); PG8_MMA(1, 1, At, B1); PG8_BAR; PG8_SCHED;
;             PG8_LDB(B0, 1, 0); PG8_LDB(B1, 1, 1); PG8_SCHED; PG8_LDA(At, 1, 0); PG8_STAGE(PG8_SA(0, 1), a2 + hstep, voffA);
;             PG8_WAIT_V(8); PG8_WAIT_L(0); PG8_BAR; PG8_MMA(0, 0, At, B0); PG8_MMA(0, 1, At, B1); PG8_BAR; PG8_SCHED;
	s_waitcnt lgkmcnt(0)
	v_mfma_f32_16x16x32_bf16 v[60:63], v[128:131], v[176:179], v[60:63]
	v_mfma_f32_16x16x32_bf16 v[56:59], v[136:139], v[176:179], v[56:59]
	v_mfma_f32_16x16x32_bf16 v[44:47], v[128:131], v[192:195], v[44:47]
	v_mfma_f32_16x16x32_bf16 v[40:43], v[136:139], v[192:195], v[40:43]
	v_mfma_f32_16x16x32_bf16 v[28:31], v[128:131], v[200:203], v[28:31]
	v_mfma_f32_16x16x32_bf16 v[24:27], v[136:139], v[200:203], v[24:27]
	v_mfma_f32_16x16x32_bf16 v[12:15], v[128:131], v[208:211], v[12:15]
	v_mfma_f32_16x16x32_bf16 v[8:11], v[136:139], v[208:211], v[8:11]
	v_mfma_f32_16x16x32_bf16 v[60:63], v[132:135], v[180:183], v[60:63]
	v_mfma_f32_16x16x32_bf16 v[56:59], v[140:143], v[180:183], v[56:59]
	v_mfma_f32_16x16x32_bf16 v[44:47], v[132:135], v[196:199], v[44:47]
	v_mfma_f32_16x16x32_bf16 v[40:43], v[140:143], v[196:199], v[40:43]
	v_mfma_f32_16x16x32_bf16 v[28:31], v[132:135], v[204:207], v[28:31]
	v_mfma_f32_16x16x32_bf16 v[24:27], v[140:143], v[204:207], v[24:27]
	v_mfma_f32_16x16x32_bf16 v[12:15], v[132:135], v[212:215], v[12:15]
	v_mfma_f32_16x16x32_bf16 v[8:11], v[140:143], v[212:215], v[8:11]
	v_mfma_f32_16x16x32_bf16 v[52:55], v[144:147], v[176:179], v[52:55]
	v_mfma_f32_16x16x32_bf16 v[48:51], v[168:171], v[176:179], v[48:51]
	v_mfma_f32_16x16x32_bf16 v[36:39], v[144:147], v[192:195], v[36:39]
	v_mfma_f32_16x16x32_bf16 v[32:35], v[168:171], v[192:195], v[32:35]
	v_mfma_f32_16x16x32_bf16 v[20:23], v[144:147], v[200:203], v[20:23]
	v_mfma_f32_16x16x32_bf16 v[16:19], v[168:171], v[200:203], v[16:19]
	v_mfma_f32_16x16x32_bf16 v[4:7], v[144:147], v[208:211], v[4:7]
	v_mfma_f32_16x16x32_bf16 v[0:3], v[168:171], v[208:211], v[0:3]
	v_mfma_f32_16x16x32_bf16 v[52:55], v[148:151], v[180:183], v[52:55]
	v_mfma_f32_16x16x32_bf16 v[48:51], v[172:175], v[180:183], v[48:51]
	v_mfma_f32_16x16x32_bf16 v[36:39], v[148:151], v[196:199], v[36:39]
	v_mfma_f32_16x16x32_bf16 v[32:35], v[172:175], v[196:199], v[32:35]
	v_mfma_f32_16x16x32_bf16 v[20:23], v[148:151], v[204:207], v[20:23]
	v_mfma_f32_16x16x32_bf16 v[16:19], v[172:175], v[204:207], v[16:19]
	v_mfma_f32_16x16x32_bf16 v[4:7], v[148:151], v[212:215], v[4:7]
	v_mfma_f32_16x16x32_bf16 v[0:3], v[172:175], v[212:215], v[0:3]
	s_barrier
	s_setprio 1
	s_add_i32 s61, 0, 0x18000
	s_add_i32 s62, 0, 0x1c000
	v_add_u32_e32 v140, s61, v187
	v_add_u32_e32 v172, s62, v187
	ds_read_b128 v[128:131], v140
	ds_read_b128 v[132:135], v140 offset:1024
	ds_read_b128 v[136:139], v140 offset:2048
	ds_read_b128 v[140:143], v140 offset:3072
	ds_read_b128 v[144:147], v172
	ds_read_b128 v[148:151], v172 offset:1024
	ds_read_b128 v[168:171], v172 offset:2048
	ds_read_b128 v[172:175], v172 offset:3072
	s_add_u32 s38, s38, 0x80000
	s_addc_u32 s39, s39, 0
	s_mov_b32 m0, s47
	v_lshl_add_u64 v[222:223], s[38:39], 0, v[152:153]
	ds_read_b128 v[176:179], v191 offset:32768
	ds_read_b128 v[180:183], v191 offset:33792
	ds_read_b128 v[192:195], v191 offset:34816
	ds_read_b128 v[196:199], v191 offset:35840
	ds_read_b128 v[200:203], v191 offset:36864
	ds_read_b128 v[204:207], v191 offset:37888
	ds_read_b128 v[208:211], v191 offset:38912
	ds_read_b128 v[212:215], v191 offset:39936
	global_load_lds_dwordx4 v[222:223], off
	v_lshl_add_u64 v[222:223], s[38:39], 0, v[156:157]
	s_mov_b32 m0, s48
	s_nop 0
	global_load_lds_dwordx4 v[222:223], off
	s_mov_b32 m0, s31
	s_nop 0
	global_load_lds_dwordx4 v[218:219], off
	s_mov_b32 m0, s46
	s_nop 0
	global_load_lds_dwordx4 v[220:221], off
	s_add_u32 s36, s36, 0x80080
	s_addc_u32 s37, s37, 0
	v_lshl_add_u64 v[184:185], v[184:185], 0, s[10:11]
	v_lshl_add_u64 v[216:217], v[216:217], 0, s[10:11]
	v_lshl_add_u64 v[246:247], s[36:37], 0, v[154:155]
	v_lshl_add_u64 v[248:249], s[36:37], 0, v[158:159]
	v_lshl_add_u64 v[250:251], v[218:219], 0, s[10:11]
	v_lshl_add_u64 v[252:253], v[220:221], 0, s[10:11]
	s_waitcnt vmcnt(10)
	s_waitcnt lgkmcnt(0)
	s_setprio 0
	s_barrier
; #define PG8_STAGE(bufoff, gbase, voff) do { _Pragma("unroll") for (int _i = 0; _i < 2; ++_i) \
;         __builtin_amdgcn_global_load_lds((const unsigned*)((const char*)(gbase) + (voff)[_i]), (PG8_LAS unsigned*)(lds + (bufoff) + ldsw + _i * 8192), 16, 0, 0); } while (0)
; #define PG8_LDA(dst, b, h) do { _Pragma("unroll") for (int m = 0; m < 4; ++m) _Pragma("unroll") for (int k = 0; k < 2; ++k) dst[m][k] = *(const PG8_LAS bf16x8*)(lds + PG8_SA(b, h) + aoff + m * 2048 + k * 1024); } while (0)
; #define PG8_MMA(ai, bj, At, Bt) do { __builtin_amdgcn_s_setprio(1); _Pragma("unroll") for (int m = 0; m < 4; ++m) _Pragma("unroll") for (int n = 0; n < 2; ++n) _Pragma("unroll") for (int k = 0; k < 2; ++k) \
;         acc[ai][bj][m][n] = __builtin_amdgcn_mfma_f32_16x16x32_bf16(Bt[n][k], At[m][k], acc[ai][bj][m][n], 0, 0, 0); __builtin_amdgcn_s_setprio(0); } while (0)
; #define PG8_WAIT_V(n) asm volatile("s_waitcnt vmcnt(" #n ")" ::: "memory")
; #define PG8_WAIT_L(n) asm volatile("s_waitcnt lgkmcnt(" #n ")" ::: "memory")
; #define PG8_BAR __builtin_amdgcn_s_barrier()
; #define PG8_SCHED __builtin_amdgcn_sched_barrier(0)
; template <class Epi, class Sched, bool ALIGN_EPI = false, bool SP2 = false>
; __device__ __forceinline__ void gemm_phase(PG8_LAS unsigned char* lds, const Gemm g, const Sched& S, const Epi& E) {
;     ...
;             PG8_WAIT_V(8); PG8_WAIT_L(0); PG8_BAR; PG8_MMA(0, 0, At, B0); PG8_MMA(0, 1, At, B1); PG8_BAR; PG8_SCHED;
;             PG8_LDA(At, 1, 1); PG8_STAGE(PG8_SB(1, 0), b3, voffB); PG8_STAGE(PG8_SB(1, 1), b3 + hstep, voffB); PG8_STAGE(PG8_SA(1, 0), a3, voffA);
;             PG8_WAIT_V(8); PG8_WAIT_L(0); PG8_BAR; PG8_MMA(1, 0, At, B0); PG8_MMA(1, 1, At, B1); PG8_BAR; PG8_SCHED;
;     ...
;         if constexpr (ALIGN_EPI) { if (wr == 0) PG8_BAR; }
	s_waitcnt lgkmcnt(0)
	v_mfma_f32_16x16x32_bf16 v[124:127], v[128:131], v[176:179], v[124:127]
	v_mfma_f32_16x16x32_bf16 v[120:123], v[136:139], v[176:179], v[120:123]
	v_mfma_f32_16x16x32_bf16 v[108:111], v[128:131], v[192:195], v[108:111]
	v_mfma_f32_16x16x32_bf16 v[104:107], v[136:139], v[192:195], v[104:107]
	v_mfma_f32_16x16x32_bf16 v[92:95], v[128:131], v[200:203], v[92:95]
	v_mfma_f32_16x16x32_bf16 v[88:91], v[136:139], v[200:203], v[88:91]
	v_mfma_f32_16x16x32_bf16 v[76:79], v[128:131], v[208:211], v[76:79]
	v_mfma_f32_16x16x32_bf16 v[72:75], v[136:139], v[208:211], v[72:75]
	v_mfma_f32_16x16x32_bf16 v[124:127], v[132:135], v[180:183], v[124:127]
	v_mfma_f32_16x16x32_bf16 v[120:123], v[140:143], v[180:183], v[120:123]
	v_mfma_f32_16x16x32_bf16 v[108:111], v[132:135], v[196:199], v[108:111]
	v_mfma_f32_16x16x32_bf16 v[104:107], v[140:143], v[196:199], v[104:107]
	v_mfma_f32_16x16x32_bf16 v[92:95], v[132:135], v[204:207], v[92:95]
	v_mfma_f32_16x16x32_bf16 v[88:91], v[140:143], v[204:207], v[88:91]
	v_mfma_f32_16x16x32_bf16 v[76:79], v[132:135], v[212:215], v[76:79]
	v_mfma_f32_16x16x32_bf16 v[72:75], v[140:143], v[212:215], v[72:75]
	v_mfma_f32_16x16x32_bf16 v[116:119], v[144:147], v[176:179], v[116:119]
	v_mfma_f32_16x16x32_bf16 v[112:115], v[168:171], v[176:179], v[112:115]
	v_mfma_f32_16x16x32_bf16 v[100:103], v[144:147], v[192:195], v[100:103]
	v_mfma_f32_16x16x32_bf16 v[96:99], v[168:171], v[192:195], v[96:99]
	v_mfma_f32_16x16x32_bf16 v[84:87], v[144:147], v[200:203], v[84:87]
	v_mfma_f32_16x16x32_bf16 v[80:83], v[168:171], v[200:203], v[80:83]
	v_mfma_f32_16x16x32_bf16 v[68:71], v[144:147], v[208:211], v[68:71]
	v_mfma_f32_16x16x32_bf16 v[64:67], v[168:171], v[208:211], v[64:67]
	v_mfma_f32_16x16x32_bf16 v[116:119], v[148:151], v[180:183], v[116:119]
	v_mfma_f32_16x16x32_bf16 v[112:115], v[172:175], v[180:183], v[112:115]
	v_mfma_f32_16x16x32_bf16 v[100:103], v[148:151], v[196:199], v[100:103]
	v_mfma_f32_16x16x32_bf16 v[96:99], v[172:175], v[196:199], v[96:99]
	v_mfma_f32_16x16x32_bf16 v[84:87], v[148:151], v[204:207], v[84:87]
	v_mfma_f32_16x16x32_bf16 v[80:83], v[172:175], v[204:207], v[80:83]
	v_mfma_f32_16x16x32_bf16 v[68:71], v[148:151], v[212:215], v[68:71]
	v_mfma_f32_16x16x32_bf16 v[64:67], v[172:175], v[212:215], v[64:67]
	s_barrier
	s_setprio 1
	s_add_i32 s38, s61, s45
	s_mov_b32 m0, s38
	ds_read_b128 v[176:179], v191 offset:49152
	ds_read_b128 v[180:183], v191 offset:50176
	ds_read_b128 v[192:195], v191 offset:51200
	ds_read_b128 v[196:199], v191 offset:52224
	ds_read_b128 v[200:203], v191 offset:53248
	ds_read_b128 v[204:207], v191 offset:54272
	ds_read_b128 v[208:211], v191 offset:55296
	ds_read_b128 v[212:215], v191 offset:56320
	global_load_lds_dwordx4 v[184:185], off
	s_add_i32 m0, s38, 0x2000
	s_add_i32 s38, s62, s45
	global_load_lds_dwordx4 v[216:217], off
	s_mov_b32 m0, s38
	s_nop 0
	global_load_lds_dwordx4 v[246:247], off
	s_add_i32 m0, s38, 0x2000
	s_nop 0
	global_load_lds_dwordx4 v[248:249], off
	s_waitcnt vmcnt(4)
	s_waitcnt lgkmcnt(0)
	s_setprio 0
	s_barrier
	s_waitcnt lgkmcnt(0)
	v_mfma_f32_16x16x32_bf16 v[60:63], v[128:131], v[176:179], v[60:63]
	v_mfma_f32_16x16x32_bf16 v[56:59], v[136:139], v[176:179], v[56:59]
	v_mfma_f32_16x16x32_bf16 v[44:47], v[128:131], v[192:195], v[44:47]
	v_mfma_f32_16x16x32_bf16 v[40:43], v[136:139], v[192:195], v[40:43]
	v_mfma_f32_16x16x32_bf16 v[28:31], v[128:131], v[200:203], v[28:31]
	v_mfma_f32_16x16x32_bf16 v[24:27], v[136:139], v[200:203], v[24:27]
	v_mfma_f32_16x16x32_bf16 v[12:15], v[128:131], v[208:211], v[12:15]
	v_mfma_f32_16x16x32_bf16 v[8:11], v[136:139], v[208:211], v[8:11]
	v_mfma_f32_16x16x32_bf16 v[60:63], v[132:135], v[180:183], v[60:63]
	v_mfma_f32_16x16x32_bf16 v[56:59], v[140:143], v[180:183], v[56:59]
	v_mfma_f32_16x16x32_bf16 v[44:47], v[132:135], v[196:199], v[44:47]
	v_mfma_f32_16x16x32_bf16 v[40:43], v[140:143], v[196:199], v[40:43]
	v_mfma_f32_16x16x32_bf16 v[28:31], v[132:135], v[204:207], v[28:31]
	v_mfma_f32_16x16x32_bf16 v[24:27], v[140:143], v[204:207], v[24:27]
	v_mfma_f32_16x16x32_bf16 v[12:15], v[132:135], v[212:215], v[12:15]
	v_mfma_f32_16x16x32_bf16 v[8:11], v[140:143], v[212:215], v[8:11]
	v_mfma_f32_16x16x32_bf16 v[52:55], v[144:147], v[176:179], v[52:55]
	v_mfma_f32_16x16x32_bf16 v[48:51], v[168:171], v[176:179], v[48:51]
	v_mfma_f32_16x16x32_bf16 v[36:39], v[144:147], v[192:195], v[36:39]
	v_mfma_f32_16x16x32_bf16 v[32:35], v[168:171], v[192:195], v[32:35]
	v_mfma_f32_16x16x32_bf16 v[20:23], v[144:147], v[200:203], v[20:23]
	v_mfma_f32_16x16x32_bf16 v[16:19], v[168:171], v[200:203], v[16:19]
	v_mfma_f32_16x16x32_bf16 v[4:7], v[144:147], v[208:211], v[4:7]
	v_mfma_f32_16x16x32_bf16 v[0:3], v[168:171], v[208:211], v[0:3]
	v_mfma_f32_16x16x32_bf16 v[52:55], v[148:151], v[180:183], v[52:55]
	v_mfma_f32_16x16x32_bf16 v[48:51], v[172:175], v[180:183], v[48:51]
	v_mfma_f32_16x16x32_bf16 v[36:39], v[148:151], v[196:199], v[36:39]
	v_mfma_f32_16x16x32_bf16 v[32:35], v[172:175], v[196:199], v[32:35]
	v_mfma_f32_16x16x32_bf16 v[20:23], v[148:151], v[204:207], v[20:23]
	v_mfma_f32_16x16x32_bf16 v[16:19], v[172:175], v[204:207], v[16:19]
	v_mfma_f32_16x16x32_bf16 v[4:7], v[148:151], v[212:215], v[4:7]
	v_mfma_f32_16x16x32_bf16 v[0:3], v[172:175], v[212:215], v[0:3]
	s_barrier
	s_add_i32 s60, s60, 2
	s_add_u32 s34, s34, 0x100
	s_addc_u32 s35, s35, 0
	s_add_u32 s58, s58, 0x100
	s_addc_u32 s59, s59, 0
	s_cmp_gt_u32 s60, 29
	s_cbranch_scc0 .LBB0_621
	s_and_b64 vcc, exec, s[12:13]
	s_cbranch_vccz .LBB0_624
	s_barrier

; #define PG8_STAGE(bufoff, gbase, voff) do { _Pragma("unroll") for (int _i = 0; _i < 2; ++_i) \
;         __builtin_amdgcn_global_load_lds((const unsigned*)((const char*)(gbase) + (voff)[_i]), (PG8_LAS unsigned*)(lds + (bufoff) + ldsw + _i * 8192), 16, 0, 0); } while (0)
; #define PG8_WAIT_V(n) asm volatile("s_waitcnt vmcnt(" #n ")" ::: "memory")
; #define PG8_BAR __builtin_amdgcn_s_barrier()
; template <class Epi, class Sched, bool ALIGN_EPI = false, bool SP2 = false>
; __device__ __forceinline__ void gemm_phase(PG8_LAS unsigned char* lds, const Gemm g, const Sched& S, const Epi& E) {
;     ...
;     const unsigned ldsw = (unsigned)wid * 1024u;
;     const int aoff = lds_byte(wr * 64 + fr, fq * 8), boff = lds_byte(wc * 32 + fr, fq * 8);
;     ...
;     Unit cur, nxt; int ui = 0;
;     if (!S.next(0, cur)) return;
;     f32x4 acc[2][2][4][2];
; #pragma unroll
;     for (int a = 0; a < 2; ++a)
; #pragma unroll
;         for (int b = 0; b < 2; ++b)
; #pragma unroll
;             for (int m = 0; m < 4; ++m)
; #pragma unroll
;                 for (int n = 0; n < 2; ++n) acc[a][b][m][n] = (f32x4){0.f, 0.f, 0.f, 0.f};
;     bf16x8 At[4][2], B0[2][2], B1[2][2];
;     const char* cA = (const char*)g.A + (size_t)cur.pm * tstep; const char* cB = (const char*)g.Bt + (size_t)cur.pn * tstep;
;     S.a_ready(cur);
;     if constexpr (SP2) {
;         PG8_STAGE(PG8_SB(0, 0), cB, voffB); PG8_STAGE(PG8_SB(0, 1), cB + hstep, voffB); PG8_STAGE(PG8_SA(0, 0), cA, voffA); PG8_STAGE(PG8_SA(0, 1), cA + hstep, voffA);
;         if (wr == 1) PG8_BAR;
;         PG8_WAIT_V(2); PG8_BAR;
;         PG8_STAGE(PG8_SB(1, 0), cB + kstep, voffB); PG8_STAGE(PG8_SA(1, 0), cA + kstep, voffA); PG8_STAGE(PG8_SB(1, 1), cB + hstep + kstep, voffB);
;         PG8_WAIT_V(6); PG8_BAR;
.LBB0_699:
	s_add_u32 s4, s6, 0x1c600000
	s_addc_u32 s5, s7, 0
	s_add_u32 s6, s6, 0x34f20000
	s_addc_u32 s7, s7, 0
	s_lshl_b32 s8, s8, 5
	s_and_b32 s14, s8, 0x60
	s_mov_b64 s[8:9], 0x80
	s_add_i32 m0, s25, 0x18000
	v_lshl_add_u64 v[6:7], v[6:7], 0, s[8:9]
	s_lshl_b32 s11, s10, 13
	s_lshl_b32 s15, s14, 7
	s_waitcnt vmcnt(2)
	s_barrier
	global_load_lds_dwordx4 v[6:7], off
	v_lshl_add_u64 v[4:5], v[4:5], 0, s[8:9]
	s_add_i32 m0, s25, 0x1a000
	s_add_i32 s48, s25, 0x8000
	s_add_i32 s49, s25, 0xa000
	global_load_lds_dwordx4 v[4:5], off
	v_lshl_add_u64 v[0:1], v[0:1], 0, s[8:9]
	s_mov_b32 m0, s48
	s_add_u32 s12, s30, 0x80080
	global_load_lds_dwordx4 v[0:1], off
	v_mov_b64_e32 v[250:251], v[0:1]
	v_lshl_add_u64 v[0:1], v[2:3], 0, s[8:9]
	s_mov_b32 m0, s49
	s_addc_u32 s13, s31, 0
	global_load_lds_dwordx4 v[0:1], off
	v_mov_b64_e32 v[252:253], v[0:1]
	s_add_i32 m0, s25, 0x1c000
	v_lshl_add_u64 v[0:1], s[12:13], 0, v[132:133]
	global_load_lds_dwordx4 v[0:1], off
	v_lshl_add_u64 v[0:1], s[12:13], 0, v[128:129]
	s_add_i32 m0, s25, 0x1e000
	s_cmpk_lt_u32 s3, 0x100
	global_load_lds_dwordx4 v[0:1], off
	v_lshrrev_b32_e32 v1, 1, v9
	v_and_b32_e32 v1, 24, v1
	v_and_b32_e32 v0, 15, v9
	v_lshlrev_b32_e32 v2, 1, v1
	v_lshl_or_b32 v148, s10, 6, v0
	v_lshl_or_b32 v0, v0, 6, v2
	v_lshlrev_b32_e32 v2, 2, v9
	v_and_b32_e32 v2, 32, v2
	v_bitop3_b32 v3, v0, s11, v2 bitop3:0xde
	v_bitop3_b32 v149, v0, s15, v2 bitop3:0xde
	v_lshlrev_b32_e32 v0, 15, v13
	v_and_b32_e32 v0, 0xffff0000, v0
	v_or_b32_e32 v150, s14, v1
	v_lshl_add_u32 v0, v12, 12, v0
	v_and_b32_e32 v1, 1, v13
	v_lshl_or_b32 v0, v1, 6, v0
	v_lshl_add_u32 v136, v14, 1, v0
	v_lshlrev_b32_e32 v0, 15, v8
	v_and_b32_e32 v0, 0xffff0000, v0
	s_waitcnt vmcnt(6)
	v_lshl_add_u32 v0, v10, 12, v0
	v_and_b32_e32 v1, 1, v8
	s_cselect_b64 s[10:11], -1, 0
	v_lshl_or_b32 v0, v1, 6, v0
	s_add_i32 s52, 0, 0x10000
	s_add_i32 s53, 0, 0x14000
	s_sext_i32_i16 s55, s2
	s_mov_b32 s50, 0
	s_ashr_i32 s51, s37, 31
	v_mov_b32_e32 v137, v133
	v_lshl_add_u32 v138, v11, 1, v0
	v_mov_b32_e32 v139, v133
	v_mov_b64_e32 v[140:141], 0xb00
	v_mov_b64_e32 v[142:143], 0xaff
	v_add_u32_e32 v151, s52, v149
	v_add_u32_e32 v152, s53, v149
	v_add_u32_e32 v153, 0, v3
	v_mov_b32_e32 v154, 0x358637bd
	s_movk_i32 s54, 0x2c00
	s_barrier
	s_branch .LBB0_702

; #define PG8_STAGE(bufoff, gbase, voff) do { _Pragma("unroll") for (int _i = 0; _i < 2; ++_i) \
;         __builtin_amdgcn_global_load_lds((const unsigned*)((const char*)(gbase) + (voff)[_i]), (PG8_LAS unsigned*)(lds + (bufoff) + ldsw + _i * 8192), 16, 0, 0); } while (0)
; #define PG8_LDA(dst, b, h) do { _Pragma("unroll") for (int m = 0; m < 4; ++m) _Pragma("unroll") for (int k = 0; k < 2; ++k) dst[m][k] = *(const PG8_LAS bf16x8*)(lds + PG8_SA(b, h) + aoff + m * 2048 + k * 1024); } while (0)
; #define PG8_LDB(dst, b, h) do { _Pragma("unroll") for (int n = 0; n < 2; ++n) _Pragma("unroll") for (int k = 0; k < 2; ++k) dst[n][k] = *(const PG8_LAS bf16x8*)(lds + PG8_SB(b, h) + boff + n * 2048 + k * 1024); } while (0)
; #define PG8_WAIT_V(n) asm volatile("s_waitcnt vmcnt(" #n ")" ::: "memory")
; #define PG8_WAIT_L(n) asm volatile("s_waitcnt lgkmcnt(" #n ")" ::: "memory")
; #define PG8_BAR __builtin_amdgcn_s_barrier()
; #define PG8_SCHED __builtin_amdgcn_sched_barrier(0)
; template <class Epi, class Sched, bool ALIGN_EPI = false, bool SP2 = false>
; __device__ __forceinline__ void gemm_phase(PG8_LAS unsigned char* lds, const Gemm g, const Sched& S, const Epi& E) {
;     ...
;         const bool has_next = S.next(ui + 1, nxt);
;         const char* nA = has_next ? (const char*)g.A + (size_t)nxt.pm * tstep : cA; const char* nB = has_next ? (const char*)g.Bt + (size_t)nxt.pn * tstep : cB;
;         for (int t = 0; t < nt; t += 2) {
;             const bool last = (t == nt - 2);
;             const char* a1 = cA + (size_t)(t + 1) * kstep;
;             const char* a2 = last ? nA : cA + (size_t)(t + 2) * kstep; const char* b2 = last ? nB : cB + (size_t)(t + 2) * kstep;
;             const char* a3 = a2 + kstep; const char* b3 = b2 + kstep;
;             if (last && has_next) S.a_ready(nxt);
;             if constexpr (SP2) {
;             PG8_LDB(B0, 0, 0); PG8_LDB(B1, 0, 1); PG8_SCHED; PG8_LDA(At, 0, 0); PG8_STAGE(PG8_SA(1, 1), a1 + hstep, voffA);
;             PG8_WAIT_V(8); PG8_WAIT_L(0); PG8_BAR; PG8_MMA(0, 0, At, B0); PG8_MMA(0, 1, At, B1); PG8_BAR; PG8_SCHED;
;             PG8_LDA(At, 0, 1); PG8_STAGE(PG8_SB(0, 0), b2, voffB); PG8_STAGE(PG8_SB(0, 1), b2 + hstep, voffB); PG8_STAGE(PG8_SA(0, 0), a2, voffA);
;             PG8_WAIT_V(8); PG8_WAIT_L(0); PG8_BAR; PG8_MMA(1, 0, At, B0); PG8_MMA(1, 1, At, B1); PG8_BAR; PG8_SCHED;
.LBB0_705:
	s_setprio 1
	ds_read_b128 v[144:147], v151
	ds_read_b128 v[156:159], v151 offset:1024
	ds_read_b128 v[160:163], v151 offset:2048
	ds_read_b128 v[164:167], v151 offset:3072
	ds_read_b128 v[168:171], v152
	ds_read_b128 v[172:175], v152 offset:1024
	ds_read_b128 v[176:179], v152 offset:2048
	ds_read_b128 v[180:183], v152 offset:3072
	s_add_u32 s30, s28, 0xfff80080
	s_addc_u32 s31, s29, -1
	s_cmp_eq_u32 s60, 28
	s_cselect_b32 s35, s15, s31
	s_cselect_b32 s34, s56, s30
	s_cselect_b32 s31, s13, s59
	s_cselect_b32 s30, s57, s58
	v_lshl_add_u64 v[216:217], s[28:29], 0, v[136:137]
	s_add_i32 m0, s25, 0xc000
	ds_read_b128 v[184:187], v153
	ds_read_b128 v[188:191], v153 offset:1024
	ds_read_b128 v[192:195], v153 offset:2048
	ds_read_b128 v[196:199], v153 offset:3072
	ds_read_b128 v[200:203], v153 offset:4096
	ds_read_b128 v[204:207], v153 offset:5120
	ds_read_b128 v[208:211], v153 offset:6144
	ds_read_b128 v[212:215], v153 offset:7168
	global_load_lds_dwordx4 v[216:217], off
	v_lshl_add_u64 v[216:217], s[28:29], 0, v[138:139]
	s_add_i32 m0, s25, 0xe000
	s_nop 0
	global_load_lds_dwordx4 v[216:217], off
	s_mov_b32 m0, s48
	s_nop 0
	global_load_lds_dwordx4 v[250:251], off
	s_mov_b32 m0, s49
	s_nop 0
	global_load_lds_dwordx4 v[252:253], off
	s_add_u32 s62, s30, 0x80000
	s_addc_u32 s63, s31, 0
	v_lshl_add_u64 v[216:217], s[30:31], 0, v[132:133]
	v_lshl_add_u64 v[218:219], s[30:31], 0, v[128:129]
	v_lshl_add_u64 v[246:247], s[62:63], 0, v[132:133]
	v_lshl_add_u64 v[222:223], s[34:35], 0, v[130:131]
	v_lshl_add_u64 v[248:249], s[62:63], 0, v[128:129]
	v_lshl_add_u64 v[220:221], s[34:35], 0, v[134:135]
	s_waitcnt vmcnt(10)
	s_waitcnt lgkmcnt(0)
	s_setprio 0
	s_barrier
	s_waitcnt lgkmcnt(0)
	v_mfma_f32_16x16x32_bf16 v[116:119], v[144:147], v[184:187], v[116:119]
	v_mfma_f32_16x16x32_bf16 v[112:115], v[160:163], v[184:187], v[112:115]
	v_mfma_f32_16x16x32_bf16 v[100:103], v[144:147], v[192:195], v[100:103]
	v_mfma_f32_16x16x32_bf16 v[96:99], v[160:163], v[192:195], v[96:99]
	v_mfma_f32_16x16x32_bf16 v[84:87], v[144:147], v[200:203], v[84:87]
	v_mfma_f32_16x16x32_bf16 v[80:83], v[160:163], v[200:203], v[80:83]
	v_mfma_f32_16x16x32_bf16 v[72:75], v[144:147], v[208:211], v[72:75]
	v_mfma_f32_16x16x32_bf16 v[68:71], v[160:163], v[208:211], v[68:71]
	v_mfma_f32_16x16x32_bf16 v[116:119], v[156:159], v[188:191], v[116:119]
	v_mfma_f32_16x16x32_bf16 v[112:115], v[164:167], v[188:191], v[112:115]
	v_mfma_f32_16x16x32_bf16 v[100:103], v[156:159], v[196:199], v[100:103]
	v_mfma_f32_16x16x32_bf16 v[96:99], v[164:167], v[196:199], v[96:99]
	v_mfma_f32_16x16x32_bf16 v[84:87], v[156:159], v[204:207], v[84:87]
	v_mfma_f32_16x16x32_bf16 v[80:83], v[164:167], v[204:207], v[80:83]
	v_mfma_f32_16x16x32_bf16 v[72:75], v[156:159], v[212:215], v[72:75]
	v_mfma_f32_16x16x32_bf16 v[68:71], v[164:167], v[212:215], v[68:71]
	v_mfma_f32_16x16x32_bf16 v[124:127], v[168:171], v[184:187], v[124:127]
	v_mfma_f32_16x16x32_bf16 v[120:123], v[176:179], v[184:187], v[120:123]
	v_mfma_f32_16x16x32_bf16 v[108:111], v[168:171], v[192:195], v[108:111]
	v_mfma_f32_16x16x32_bf16 v[104:107], v[176:179], v[192:195], v[104:107]
	v_mfma_f32_16x16x32_bf16 v[92:95], v[168:171], v[200:203], v[92:95]
	v_mfma_f32_16x16x32_bf16 v[88:91], v[176:179], v[200:203], v[88:91]
	v_mfma_f32_16x16x32_bf16 v[76:79], v[168:171], v[208:211], v[76:79]
	v_mfma_f32_16x16x32_bf16 v[64:67], v[176:179], v[208:211], v[64:67]
	v_mfma_f32_16x16x32_bf16 v[124:127], v[172:175], v[188:191], v[124:127]
	v_mfma_f32_16x16x32_bf16 v[120:123], v[180:183], v[188:191], v[120:123]
	v_mfma_f32_16x16x32_bf16 v[108:111], v[172:175], v[196:199], v[108:111]
	v_mfma_f32_16x16x32_bf16 v[104:107], v[180:183], v[196:199], v[104:107]
	v_mfma_f32_16x16x32_bf16 v[92:95], v[172:175], v[204:207], v[92:95]
	v_mfma_f32_16x16x32_bf16 v[88:91], v[180:183], v[204:207], v[88:91]
	v_mfma_f32_16x16x32_bf16 v[76:79], v[172:175], v[212:215], v[76:79]
	v_mfma_f32_16x16x32_bf16 v[64:67], v[180:183], v[212:215], v[64:67]
	s_barrier
	s_setprio 1
	s_add_i32 s61, s52, s42
	s_mov_b32 m0, s61
	ds_read_b128 v[184:187], v153 offset:16384
	ds_read_b128 v[188:191], v153 offset:17408
	ds_read_b128 v[192:195], v153 offset:18432
	ds_read_b128 v[196:199], v153 offset:19456
	ds_read_b128 v[200:203], v153 offset:20480
	ds_read_b128 v[204:207], v153 offset:21504
	ds_read_b128 v[208:211], v153 offset:22528
	ds_read_b128 v[212:215], v153 offset:23552
	global_load_lds_dwordx4 v[216:217], off
	s_add_i32 m0, s61, 0x2000
	s_add_i32 s61, s53, s42
	global_load_lds_dwordx4 v[218:219], off
	s_mov_b32 m0, s61
	s_nop 0
	global_load_lds_dwordx4 v[246:247], off
	s_add_i32 m0, s61, 0x2000
	s_nop 0
	global_load_lds_dwordx4 v[248:249], off
	s_waitcnt vmcnt(4)
	s_waitcnt lgkmcnt(0)
	s_setprio 0
	s_barrier
; #define PG8_STAGE(bufoff, gbase, voff) do { _Pragma("unroll") for (int _i = 0; _i < 2; ++_i) \
;         __builtin_amdgcn_global_load_lds((const unsigned*)((const char*)(gbase) + (voff)[_i]), (PG8_LAS unsigned*)(lds + (bufoff) + ldsw + _i * 8192), 16, 0, 0); } while (0)
; #define PG8_LDA(dst, b, h) do { _Pragma("unroll") for (int m = 0; m < 4; ++m) _Pragma("unroll") for (int k = 0; k < 2; ++k) dst[m][k] = *(const PG8_LAS bf16x8*)(lds + PG8_SA(b, h) + aoff + m * 2048 + k * 1024); } while (0)
; #define PG8_LDB(dst, b, h) do { _Pragma("unroll") for (int n = 0; n < 2; ++n) _Pragma("unroll") for (int k = 0; k < 2; ++k) dst[n][k] = *(const PG8_LAS bf16x8*)(lds + PG8_SB(b, h) + boff + n * 2048 + k * 1024); } while (0)
; #define PG8_MMA(ai, bj, At, Bt) do { __builtin_amdgcn_s_setprio(1); _Pragma("unroll") for (int m = 0; m < 4; ++m) _Pragma("unroll") for (int n = 0; n < 2; ++n) _Pragma("unroll") for (int k = 0; k < 2; ++k) \
;         acc[ai][bj][m][n] = __builtin_amdgcn_mfma_f32_16x16x32_bf16(Bt[n][k], At[m][k], acc[ai][bj][m][n], 0, 0, 0); __builtin_amdgcn_s_setprio(0); } while (0)
; #define PG8_WAIT_V(n) asm volatile("s_waitcnt vmcnt(" #n ")" ::: "memory")
; #define PG8_WAIT_L(n) asm volatile("s_waitcnt lgkmcnt(" #n ")" ::: "memory")
; #define PG8_BAR __builtin_amdgcn_s_barrier()
; #define PG8_SCHED __builtin_amdgcn_sched_barrier(0)
; template <class Epi, class Sched, bool ALIGN_EPI = false, bool SP2 = false>
; __device__ __forceinline__ void gemm_phase(PG8_LAS unsigned char* lds, const Gemm g, const Sched& S, const Epi& E) {
;     ...
;             PG8_LDA(At, 0, 1); PG8_STAGE(PG8_SB(0, 0), b2, voffB); PG8_STAGE(PG8_SB(0, 1), b2 + hstep, voffB); PG8_STAGE(PG8_SA(0, 0), a2, voffA);
;             PG8_WAIT_V(8); PG8_WAIT_L(0); PG8_BAR; PG8_MMA(1, 0, At, B0); PG8_MMA(1, 1, At, B1); PG8_BAR; PG8_SCHED;
;             PG8_LDB(B0, 1, 0); PG8_LDB(B1, 1, 1); PG8_SCHED; PG8_LDA(At, 1, 0); PG8_STAGE(PG8_SA(0, 1), a2 + hstep, voffA);
;             PG8_WAIT_V(8); PG8_WAIT_L(0); PG8_BAR; PG8_MMA(0, 0, At, B0); PG8_MMA(0, 1, At, B1); PG8_BAR; PG8_SCHED;
	s_waitcnt lgkmcnt(0)
	v_mfma_f32_16x16x32_bf16 v[56:59], v[144:147], v[184:187], v[56:59]
	v_mfma_f32_16x16x32_bf16 v[52:55], v[160:163], v[184:187], v[52:55]
	v_mfma_f32_16x16x32_bf16 v[40:43], v[144:147], v[192:195], v[40:43]
	v_mfma_f32_16x16x32_bf16 v[36:39], v[160:163], v[192:195], v[36:39]
	v_mfma_f32_16x16x32_bf16 v[24:27], v[144:147], v[200:203], v[24:27]
	v_mfma_f32_16x16x32_bf16 v[20:23], v[160:163], v[200:203], v[20:23]
	v_mfma_f32_16x16x32_bf16 v[8:11], v[144:147], v[208:211], v[8:11]
	v_mfma_f32_16x16x32_bf16 v[0:3], v[160:163], v[208:211], v[0:3]
	v_mfma_f32_16x16x32_bf16 v[56:59], v[156:159], v[188:191], v[56:59]
	v_mfma_f32_16x16x32_bf16 v[52:55], v[164:167], v[188:191], v[52:55]
	v_mfma_f32_16x16x32_bf16 v[40:43], v[156:159], v[196:199], v[40:43]
	v_mfma_f32_16x16x32_bf16 v[36:39], v[164:167], v[196:199], v[36:39]
	v_mfma_f32_16x16x32_bf16 v[24:27], v[156:159], v[204:207], v[24:27]
	v_mfma_f32_16x16x32_bf16 v[20:23], v[164:167], v[204:207], v[20:23]
	v_mfma_f32_16x16x32_bf16 v[8:11], v[156:159], v[212:215], v[8:11]
	v_mfma_f32_16x16x32_bf16 v[0:3], v[164:167], v[212:215], v[0:3]
	v_mfma_f32_16x16x32_bf16 v[60:63], v[168:171], v[184:187], v[60:63]
	v_mfma_f32_16x16x32_bf16 v[48:51], v[176:179], v[184:187], v[48:51]
	v_mfma_f32_16x16x32_bf16 v[44:47], v[168:171], v[192:195], v[44:47]
	v_mfma_f32_16x16x32_bf16 v[32:35], v[176:179], v[192:195], v[32:35]
	v_mfma_f32_16x16x32_bf16 v[28:31], v[168:171], v[200:203], v[28:31]
	v_mfma_f32_16x16x32_bf16 v[16:19], v[176:179], v[200:203], v[16:19]
	v_mfma_f32_16x16x32_bf16 v[12:15], v[168:171], v[208:211], v[12:15]
	v_mfma_f32_16x16x32_bf16 v[4:7], v[176:179], v[208:211], v[4:7]
	v_mfma_f32_16x16x32_bf16 v[60:63], v[172:175], v[188:191], v[60:63]
	v_mfma_f32_16x16x32_bf16 v[48:51], v[180:183], v[188:191], v[48:51]
	v_mfma_f32_16x16x32_bf16 v[44:47], v[172:175], v[196:199], v[44:47]
	v_mfma_f32_16x16x32_bf16 v[32:35], v[180:183], v[196:199], v[32:35]
	v_mfma_f32_16x16x32_bf16 v[28:31], v[172:175], v[204:207], v[28:31]
	v_mfma_f32_16x16x32_bf16 v[16:19], v[180:183], v[204:207], v[16:19]
	v_mfma_f32_16x16x32_bf16 v[12:15], v[172:175], v[212:215], v[12:15]
	v_mfma_f32_16x16x32_bf16 v[4:7], v[180:183], v[212:215], v[4:7]
	s_barrier
	s_setprio 1
	s_add_i32 s61, 0, 0x18000
	v_add_u32_e32 v155, s61, v149
	s_add_i32 s62, 0, 0x1c000
	ds_read_b128 v[144:147], v155
	ds_read_b128 v[156:159], v155 offset:1024
	ds_read_b128 v[160:163], v155 offset:2048
	ds_read_b128 v[164:167], v155 offset:3072
	v_add_u32_e32 v155, s62, v149
	ds_read_b128 v[168:171], v155
	ds_read_b128 v[172:175], v155 offset:1024
	ds_read_b128 v[176:179], v155 offset:2048
	ds_read_b128 v[180:183], v155 offset:3072
	s_add_u32 s34, s34, 0x80000
	s_addc_u32 s35, s35, 0
	s_mov_b32 m0, s46
	v_lshl_add_u64 v[224:225], s[34:35], 0, v[134:135]
	ds_read_b128 v[184:187], v153 offset:32768
	ds_read_b128 v[188:191], v153 offset:33792
	ds_read_b128 v[192:195], v153 offset:34816
	ds_read_b128 v[196:199], v153 offset:35840
	ds_read_b128 v[200:203], v153 offset:36864
	ds_read_b128 v[204:207], v153 offset:37888
	ds_read_b128 v[208:211], v153 offset:38912
	ds_read_b128 v[212:215], v153 offset:39936
	global_load_lds_dwordx4 v[224:225], off
	v_lshl_add_u64 v[224:225], s[34:35], 0, v[130:131]
	s_mov_b32 m0, s47
	s_nop 0
	global_load_lds_dwordx4 v[224:225], off
	s_mov_b32 m0, s25
	s_nop 0
	global_load_lds_dwordx4 v[220:221], off
	s_mov_b32 m0, s45
	s_nop 0
	global_load_lds_dwordx4 v[222:223], off
	s_add_u32 s30, s30, 0x80080
	s_addc_u32 s31, s31, 0
	v_lshl_add_u64 v[216:217], v[216:217], 0, s[8:9]
	v_lshl_add_u64 v[218:219], v[218:219], 0, s[8:9]
	v_lshl_add_u64 v[246:247], s[30:31], 0, v[132:133]
	v_lshl_add_u64 v[248:249], s[30:31], 0, v[128:129]
	v_lshl_add_u64 v[250:251], v[220:221], 0, s[8:9]
	v_lshl_add_u64 v[252:253], v[222:223], 0, s[8:9]
	s_waitcnt vmcnt(10)
	s_waitcnt lgkmcnt(0)
	s_setprio 0
	s_barrier
; #define PG8_STAGE(bufoff, gbase, voff) do { _Pragma("unroll") for (int _i = 0; _i < 2; ++_i) \
;         __builtin_amdgcn_global_load_lds((const unsigned*)((const char*)(gbase) + (voff)[_i]), (PG8_LAS unsigned*)(lds + (bufoff) + ldsw + _i * 8192), 16, 0, 0); } while (0)
; #define PG8_LDA(dst, b, h) do { _Pragma("unroll") for (int m = 0; m < 4; ++m) _Pragma("unroll") for (int k = 0; k < 2; ++k) dst[m][k] = *(const PG8_LAS bf16x8*)(lds + PG8_SA(b, h) + aoff + m * 2048 + k * 1024); } while (0)
; #define PG8_MMA(ai, bj, At, Bt) do { __builtin_amdgcn_s_setprio(1); _Pragma("unroll") for (int m = 0; m < 4; ++m) _Pragma("unroll") for (int n = 0; n < 2; ++n) _Pragma("unroll") for (int k = 0; k < 2; ++k) \
;         acc[ai][bj][m][n] = __builtin_amdgcn_mfma_f32_16x16x32_bf16(Bt[n][k], At[m][k], acc[ai][bj][m][n], 0, 0, 0); __builtin_amdgcn_s_setprio(0); } while (0)
; #define PG8_WAIT_V(n) asm volatile("s_waitcnt vmcnt(" #n ")" ::: "memory")
; #define PG8_WAIT_L(n) asm volatile("s_waitcnt lgkmcnt(" #n ")" ::: "memory")
; #define PG8_BAR __builtin_amdgcn_s_barrier()
; #define PG8_SCHED __builtin_amdgcn_sched_barrier(0)
; template <class Epi, class Sched, bool ALIGN_EPI = false, bool SP2 = false>
; __device__ __forceinline__ void gemm_phase(PG8_LAS unsigned char* lds, const Gemm g, const Sched& S, const Epi& E) {
;     ...
;             PG8_WAIT_V(8); PG8_WAIT_L(0); PG8_BAR; PG8_MMA(0, 0, At, B0); PG8_MMA(0, 1, At, B1); PG8_BAR; PG8_SCHED;
;             PG8_LDA(At, 1, 1); PG8_STAGE(PG8_SB(1, 0), b3, voffB); PG8_STAGE(PG8_SB(1, 1), b3 + hstep, voffB); PG8_STAGE(PG8_SA(1, 0), a3, voffA);
;             PG8_WAIT_V(8); PG8_WAIT_L(0); PG8_BAR; PG8_MMA(1, 0, At, B0); PG8_MMA(1, 1, At, B1); PG8_BAR; PG8_SCHED;
;     ...
;         if constexpr (ALIGN_EPI) { if (wr == 0) PG8_BAR; }
	s_waitcnt lgkmcnt(0)
	v_mfma_f32_16x16x32_bf16 v[116:119], v[144:147], v[184:187], v[116:119]
	v_mfma_f32_16x16x32_bf16 v[112:115], v[160:163], v[184:187], v[112:115]
	v_mfma_f32_16x16x32_bf16 v[100:103], v[144:147], v[192:195], v[100:103]
	v_mfma_f32_16x16x32_bf16 v[96:99], v[160:163], v[192:195], v[96:99]
	v_mfma_f32_16x16x32_bf16 v[84:87], v[144:147], v[200:203], v[84:87]
	v_mfma_f32_16x16x32_bf16 v[80:83], v[160:163], v[200:203], v[80:83]
	v_mfma_f32_16x16x32_bf16 v[72:75], v[144:147], v[208:211], v[72:75]
	v_mfma_f32_16x16x32_bf16 v[68:71], v[160:163], v[208:211], v[68:71]
	v_mfma_f32_16x16x32_bf16 v[116:119], v[156:159], v[188:191], v[116:119]
	v_mfma_f32_16x16x32_bf16 v[112:115], v[164:167], v[188:191], v[112:115]
	v_mfma_f32_16x16x32_bf16 v[100:103], v[156:159], v[196:199], v[100:103]
	v_mfma_f32_16x16x32_bf16 v[96:99], v[164:167], v[196:199], v[96:99]
	v_mfma_f32_16x16x32_bf16 v[84:87], v[156:159], v[204:207], v[84:87]
	v_mfma_f32_16x16x32_bf16 v[80:83], v[164:167], v[204:207], v[80:83]
	v_mfma_f32_16x16x32_bf16 v[72:75], v[156:159], v[212:215], v[72:75]
	v_mfma_f32_16x16x32_bf16 v[68:71], v[164:167], v[212:215], v[68:71]
	v_mfma_f32_16x16x32_bf16 v[124:127], v[168:171], v[184:187], v[124:127]
	v_mfma_f32_16x16x32_bf16 v[120:123], v[176:179], v[184:187], v[120:123]
	v_mfma_f32_16x16x32_bf16 v[108:111], v[168:171], v[192:195], v[108:111]
	v_mfma_f32_16x16x32_bf16 v[104:107], v[176:179], v[192:195], v[104:107]
	v_mfma_f32_16x16x32_bf16 v[92:95], v[168:171], v[200:203], v[92:95]
	v_mfma_f32_16x16x32_bf16 v[88:91], v[176:179], v[200:203], v[88:91]
	v_mfma_f32_16x16x32_bf16 v[76:79], v[168:171], v[208:211], v[76:79]
	v_mfma_f32_16x16x32_bf16 v[64:67], v[176:179], v[208:211], v[64:67]
	v_mfma_f32_16x16x32_bf16 v[124:127], v[172:175], v[188:191], v[124:127]
	v_mfma_f32_16x16x32_bf16 v[120:123], v[180:183], v[188:191], v[120:123]
	v_mfma_f32_16x16x32_bf16 v[108:111], v[172:175], v[196:199], v[108:111]
	v_mfma_f32_16x16x32_bf16 v[104:107], v[180:183], v[196:199], v[104:107]
	v_mfma_f32_16x16x32_bf16 v[92:95], v[172:175], v[204:207], v[92:95]
	v_mfma_f32_16x16x32_bf16 v[88:91], v[180:183], v[204:207], v[88:91]
	v_mfma_f32_16x16x32_bf16 v[76:79], v[172:175], v[212:215], v[76:79]
	v_mfma_f32_16x16x32_bf16 v[64:67], v[180:183], v[212:215], v[64:67]
	s_barrier
	s_setprio 1
	s_add_i32 s34, s61, s42
	s_mov_b32 m0, s34
	ds_read_b128 v[184:187], v153 offset:49152
	ds_read_b128 v[188:191], v153 offset:50176
	ds_read_b128 v[192:195], v153 offset:51200
	ds_read_b128 v[196:199], v153 offset:52224
	ds_read_b128 v[200:203], v153 offset:53248
	ds_read_b128 v[204:207], v153 offset:54272
	ds_read_b128 v[208:211], v153 offset:55296
	ds_read_b128 v[212:215], v153 offset:56320
	global_load_lds_dwordx4 v[216:217], off
	s_add_i32 m0, s34, 0x2000
	s_add_i32 s34, s62, s42
	global_load_lds_dwordx4 v[218:219], off
	s_mov_b32 m0, s34
	s_nop 0
	global_load_lds_dwordx4 v[246:247], off
	s_add_i32 m0, s34, 0x2000
	s_nop 0
	global_load_lds_dwordx4 v[248:249], off
	s_waitcnt vmcnt(4)
	s_waitcnt lgkmcnt(0)
	s_setprio 0
	s_barrier
	s_waitcnt lgkmcnt(0)
	v_mfma_f32_16x16x32_bf16 v[56:59], v[144:147], v[184:187], v[56:59]
	v_mfma_f32_16x16x32_bf16 v[52:55], v[160:163], v[184:187], v[52:55]
	v_mfma_f32_16x16x32_bf16 v[40:43], v[144:147], v[192:195], v[40:43]
	v_mfma_f32_16x16x32_bf16 v[36:39], v[160:163], v[192:195], v[36:39]
	v_mfma_f32_16x16x32_bf16 v[24:27], v[144:147], v[200:203], v[24:27]
	v_mfma_f32_16x16x32_bf16 v[20:23], v[160:163], v[200:203], v[20:23]
	v_mfma_f32_16x16x32_bf16 v[8:11], v[144:147], v[208:211], v[8:11]
	v_mfma_f32_16x16x32_bf16 v[0:3], v[160:163], v[208:211], v[0:3]
	v_mfma_f32_16x16x32_bf16 v[56:59], v[156:159], v[188:191], v[56:59]
	v_mfma_f32_16x16x32_bf16 v[52:55], v[164:167], v[188:191], v[52:55]
	v_mfma_f32_16x16x32_bf16 v[40:43], v[156:159], v[196:199], v[40:43]
	v_mfma_f32_16x16x32_bf16 v[36:39], v[164:167], v[196:199], v[36:39]
	v_mfma_f32_16x16x32_bf16 v[24:27], v[156:159], v[204:207], v[24:27]
	v_mfma_f32_16x16x32_bf16 v[20:23], v[164:167], v[204:207], v[20:23]
	v_mfma_f32_16x16x32_bf16 v[8:11], v[156:159], v[212:215], v[8:11]
	v_mfma_f32_16x16x32_bf16 v[0:3], v[164:167], v[212:215], v[0:3]
	v_mfma_f32_16x16x32_bf16 v[60:63], v[168:171], v[184:187], v[60:63]
	v_mfma_f32_16x16x32_bf16 v[48:51], v[176:179], v[184:187], v[48:51]
	v_mfma_f32_16x16x32_bf16 v[44:47], v[168:171], v[192:195], v[44:47]
	v_mfma_f32_16x16x32_bf16 v[32:35], v[176:179], v[192:195], v[32:35]
	v_mfma_f32_16x16x32_bf16 v[28:31], v[168:171], v[200:203], v[28:31]
	v_mfma_f32_16x16x32_bf16 v[16:19], v[176:179], v[200:203], v[16:19]
	v_mfma_f32_16x16x32_bf16 v[12:15], v[168:171], v[208:211], v[12:15]
	v_mfma_f32_16x16x32_bf16 v[4:7], v[176:179], v[208:211], v[4:7]
	v_mfma_f32_16x16x32_bf16 v[60:63], v[172:175], v[188:191], v[60:63]
	v_mfma_f32_16x16x32_bf16 v[48:51], v[180:183], v[188:191], v[48:51]
	v_mfma_f32_16x16x32_bf16 v[44:47], v[172:175], v[196:199], v[44:47]
	v_mfma_f32_16x16x32_bf16 v[32:35], v[180:183], v[196:199], v[32:35]
	v_mfma_f32_16x16x32_bf16 v[28:31], v[172:175], v[204:207], v[28:31]
	v_mfma_f32_16x16x32_bf16 v[16:19], v[180:183], v[204:207], v[16:19]
	v_mfma_f32_16x16x32_bf16 v[12:15], v[172:175], v[212:215], v[12:15]
	v_mfma_f32_16x16x32_bf16 v[4:7], v[180:183], v[212:215], v[4:7]
	s_barrier
	s_add_i32 s60, s60, 2
	s_add_u32 s28, s28, 0x100
	s_addc_u32 s29, s29, 0
	s_add_u32 s58, s58, 0x100
	s_addc_u32 s59, s59, 0
	s_cmp_gt_u32 s60, 29
	s_cbranch_scc0 .LBB0_705
	s_and_b64 vcc, exec, s[10:11]
	s_cbranch_vccz .LBB0_708
	s_barrier

; #define PG8_STAGE(bufoff, gbase, voff) do { _Pragma("unroll") for (int _i = 0; _i < 2; ++_i) \
;         __builtin_amdgcn_global_load_lds((const unsigned*)((const char*)(gbase) + (voff)[_i]), (PG8_LAS unsigned*)(lds + (bufoff) + ldsw + _i * 8192), 16, 0, 0); } while (0)
; #define PG8_WAIT_V(n) asm volatile("s_waitcnt vmcnt(" #n ")" ::: "memory")
; #define PG8_BAR __builtin_amdgcn_s_barrier()
; template <class Epi, class Sched, bool ALIGN_EPI = false, bool SP2 = false>
; __device__ __forceinline__ void gemm_phase(PG8_LAS unsigned char* lds, const Gemm g, const Sched& S, const Epi& E) {
;     ...
;     const unsigned ldsw = (unsigned)wid * 1024u;
;     const int aoff = lds_byte(wr * 64 + fr, fq * 8), boff = lds_byte(wc * 32 + fr, fq * 8);
;     ...
;     Unit cur, nxt; int ui = 0;
;     if (!S.next(0, cur)) return;
;     f32x4 acc[2][2][4][2];
; #pragma unroll
;     for (int a = 0; a < 2; ++a)
; #pragma unroll
;         for (int b = 0; b < 2; ++b)
; #pragma unroll
;             for (int m = 0; m < 4; ++m)
; #pragma unroll
;                 for (int n = 0; n < 2; ++n) acc[a][b][m][n] = (f32x4){0.f, 0.f, 0.f, 0.f};
;     bf16x8 At[4][2], B0[2][2], B1[2][2];
;     const char* cA = (const char*)g.A + (size_t)cur.pm * tstep; const char* cB = (const char*)g.Bt + (size_t)cur.pn * tstep;
;     S.a_ready(cur);
;     if constexpr (SP2) {
;         PG8_STAGE(PG8_SB(0, 0), cB, voffB); PG8_STAGE(PG8_SB(0, 1), cB + hstep, voffB); PG8_STAGE(PG8_SA(0, 0), cA, voffA); PG8_STAGE(PG8_SA(0, 1), cA + hstep, voffA);
;         if (wr == 1) PG8_BAR;
;         PG8_WAIT_V(2); PG8_BAR;
;         PG8_STAGE(PG8_SB(1, 0), cB + kstep, voffB); PG8_STAGE(PG8_SA(1, 0), cA + kstep, voffA); PG8_STAGE(PG8_SB(1, 1), cB + hstep + kstep, voffB);
;         PG8_WAIT_V(6); PG8_BAR;
.LBB0_774:
	s_add_u32 s8, s6, 0x18600000
	s_addc_u32 s9, s5, 0
	s_add_u32 s10, s6, 0x34f40000
	s_addc_u32 s11, s5, 0
	s_lshl_b32 s3, s3, 5
	s_mov_b64 s[12:13], 0x80
	s_and_b32 s6, s3, 0x60
	s_add_i32 m0, s40, 0x18000
	v_lshl_add_u64 v[6:7], v[6:7], 0, s[12:13]
	s_lshl_b32 s5, s2, 13
	s_lshl_b32 s3, s6, 7
	s_waitcnt vmcnt(2)
	s_barrier
	global_load_lds_dwordx4 v[6:7], off
	v_lshl_add_u64 v[2:3], v[2:3], 0, s[12:13]
	s_add_i32 m0, s40, 0x1a000
	s_add_i32 s45, s40, 0x8000
	s_add_i32 s46, s40, 0xa000
	global_load_lds_dwordx4 v[2:3], off
	v_lshl_add_u64 v[0:1], v[0:1], 0, s[12:13]
	s_mov_b32 m0, s45
	s_add_u32 s14, s24, 0x160080
	global_load_lds_dwordx4 v[0:1], off
	v_mov_b64_e32 v[250:251], v[0:1]
	v_lshl_add_u64 v[0:1], v[4:5], 0, s[12:13]
	s_mov_b32 m0, s46
	s_addc_u32 s15, s25, 0
	global_load_lds_dwordx4 v[0:1], off
	v_mov_b64_e32 v[252:253], v[0:1]
	s_add_i32 m0, s40, 0x1c000
	v_lshl_add_u64 v[0:1], s[14:15], 0, v[154:155]
	global_load_lds_dwordx4 v[0:1], off
	v_lshl_add_u64 v[0:1], s[14:15], 0, v[158:159]
	s_add_i32 m0, s40, 0x1e000
	s_cmpk_lt_u32 s4, 0x100
	global_load_lds_dwordx4 v[0:1], off
	v_bfe_u32 v0, v8, 4, 2
	v_and_b32_e32 v1, 15, v8
	v_lshlrev_b32_e32 v2, 4, v0
	v_lshl_or_b32 v186, s2, 6, v1
	v_lshl_or_b32 v1, v1, 6, v2
	v_lshlrev_b32_e32 v2, 2, v8
	v_and_b32_e32 v2, 32, v2
	v_bitop3_b32 v3, v1, s5, v2 bitop3:0xde
	v_bitop3_b32 v187, v1, s3, v2 bitop3:0xde
	v_cmp_eq_u32_e64 s[2:3], 0, v0
	v_lshl_or_b32 v188, v0, 3, s6
	v_lshrrev_b32_e32 v1, 1, v9
	v_mul_lo_u32 v0, v10, s7
	v_mad_u64_u32 v[0:1], s[4:5], v1, s16, v[0:1]
	v_or_b32_e32 v0, v0, v11
	s_mov_b64 s[28:29], 0x160080
	v_add_lshl_u32 v0, v0, v12, 1
	v_mov_b32_e32 v1, v155
	v_lshl_add_u64 v[160:161], v[0:1], 0, s[28:29]
	v_lshrrev_b32_e32 v1, 1, v13
	v_mul_lo_u32 v0, v14, s7
	v_mad_u64_u32 v[0:1], s[4:5], v1, s16, v[0:1]
	s_waitcnt vmcnt(6)
	v_or_b32_e32 v0, v0, v15
	s_cselect_b64 s[14:15], -1, 0
	v_add_lshl_u32 v0, v0, v16, 1
	v_mov_b32_e32 v1, v155
	s_add_i32 s49, 0, 0x10000
	s_add_i32 s50, 0, 0x14000
	s_ashr_i32 s47, s34, 31
	s_ashr_i32 s48, s33, 31
	v_lshl_add_u64 v[162:163], v[0:1], 0, s[28:29]
	v_mov_b64_e32 v[164:165], 0x200
	v_mov_b64_e32 v[166:167], 0x1ff
	v_add_u32_e32 v189, s49, v187
	v_add_u32_e32 v190, s50, v187
	v_add_u32_e32 v191, 0, v3
	s_mov_b32 s51, 0x4b800000
	s_barrier
	s_branch .LBB0_777

; #define PG8_STAGE(bufoff, gbase, voff) do { _Pragma("unroll") for (int _i = 0; _i < 2; ++_i) \
;         __builtin_amdgcn_global_load_lds((const unsigned*)((const char*)(gbase) + (voff)[_i]), (PG8_LAS unsigned*)(lds + (bufoff) + ldsw + _i * 8192), 16, 0, 0); } while (0)
; #define PG8_LDA(dst, b, h) do { _Pragma("unroll") for (int m = 0; m < 4; ++m) _Pragma("unroll") for (int k = 0; k < 2; ++k) dst[m][k] = *(const PG8_LAS bf16x8*)(lds + PG8_SA(b, h) + aoff + m * 2048 + k * 1024); } while (0)
; #define PG8_LDB(dst, b, h) do { _Pragma("unroll") for (int n = 0; n < 2; ++n) _Pragma("unroll") for (int k = 0; k < 2; ++k) dst[n][k] = *(const PG8_LAS bf16x8*)(lds + PG8_SB(b, h) + boff + n * 2048 + k * 1024); } while (0)
; #define PG8_WAIT_V(n) asm volatile("s_waitcnt vmcnt(" #n ")" ::: "memory")
; #define PG8_WAIT_L(n) asm volatile("s_waitcnt lgkmcnt(" #n ")" ::: "memory")
; #define PG8_BAR __builtin_amdgcn_s_barrier()
; #define PG8_SCHED __builtin_amdgcn_sched_barrier(0)
; template <class Epi, class Sched, bool ALIGN_EPI = false, bool SP2 = false>
; __device__ __forceinline__ void gemm_phase(PG8_LAS unsigned char* lds, const Gemm g, const Sched& S, const Epi& E) {
;     ...
;         const bool has_next = S.next(ui + 1, nxt);
;         const char* nA = has_next ? (const char*)g.A + (size_t)nxt.pm * tstep : cA; const char* nB = has_next ? (const char*)g.Bt + (size_t)nxt.pn * tstep : cB;
;         for (int t = 0; t < nt; t += 2) {
;             const bool last = (t == nt - 2);
;             const char* a1 = cA + (size_t)(t + 1) * kstep;
;             const char* a2 = last ? nA : cA + (size_t)(t + 2) * kstep; const char* b2 = last ? nB : cB + (size_t)(t + 2) * kstep;
;             const char* a3 = a2 + kstep; const char* b3 = b2 + kstep;
;             if (last && has_next) S.a_ready(nxt);
;             if constexpr (SP2) {
;             PG8_LDB(B0, 0, 0); PG8_LDB(B1, 0, 1); PG8_SCHED; PG8_LDA(At, 0, 0); PG8_STAGE(PG8_SA(1, 1), a1 + hstep, voffA);
;             PG8_WAIT_V(8); PG8_WAIT_L(0); PG8_BAR; PG8_MMA(0, 0, At, B0); PG8_MMA(0, 1, At, B1); PG8_BAR; PG8_SCHED;
;             PG8_LDA(At, 0, 1); PG8_STAGE(PG8_SB(0, 0), b2, voffB); PG8_STAGE(PG8_SB(0, 1), b2 + hstep, voffB); PG8_STAGE(PG8_SA(0, 0), a2, voffA);
;             PG8_WAIT_V(8); PG8_WAIT_L(0); PG8_BAR; PG8_MMA(1, 0, At, B0); PG8_MMA(1, 1, At, B1); PG8_BAR; PG8_SCHED;
.LBB0_788:
	s_setprio 1
	ds_read_b128 v[128:131], v189
	ds_read_b128 v[132:135], v189 offset:1024
	ds_read_b128 v[136:139], v189 offset:2048
	ds_read_b128 v[140:143], v189 offset:3072
	ds_read_b128 v[144:147], v190
	ds_read_b128 v[148:151], v190 offset:1024
	ds_read_b128 v[168:171], v190 offset:2048
	ds_read_b128 v[172:175], v190 offset:3072
	s_add_u32 s24, s22, 0x100
	s_addc_u32 s25, s23, 0
	s_cmpk_eq_i32 s58, 0x54
	s_cselect_b32 s31, s7, s25
	s_cselect_b32 s30, s6, s24
	s_cselect_b32 s29, s17, s57
	s_cselect_b32 s28, s16, s56
	v_lshl_add_u64 v[184:185], s[22:23], 0, v[160:161]
	s_add_i32 m0, s40, 0xc000
	ds_read_b128 v[176:179], v191
	ds_read_b128 v[180:183], v191 offset:1024
	ds_read_b128 v[192:195], v191 offset:2048
	ds_read_b128 v[196:199], v191 offset:3072
	ds_read_b128 v[200:203], v191 offset:4096
	ds_read_b128 v[204:207], v191 offset:5120
	ds_read_b128 v[208:211], v191 offset:6144
	ds_read_b128 v[212:215], v191 offset:7168
	global_load_lds_dwordx4 v[184:185], off
	v_lshl_add_u64 v[184:185], s[22:23], 0, v[162:163]
	s_add_i32 m0, s40, 0xe000
	s_nop 0
	global_load_lds_dwordx4 v[184:185], off
	s_mov_b32 m0, s45
	s_nop 0
	global_load_lds_dwordx4 v[250:251], off
	s_mov_b32 m0, s46
	s_nop 0
	global_load_lds_dwordx4 v[252:253], off
	s_add_u32 s22, s28, 0x160000
	s_addc_u32 s23, s29, 0
	v_lshl_add_u64 v[184:185], s[28:29], 0, v[154:155]
	v_lshl_add_u64 v[216:217], s[28:29], 0, v[158:159]
	v_lshl_add_u64 v[246:247], s[22:23], 0, v[154:155]
	v_lshl_add_u64 v[220:221], s[30:31], 0, v[156:157]
	v_lshl_add_u64 v[248:249], s[22:23], 0, v[158:159]
	v_lshl_add_u64 v[218:219], s[30:31], 0, v[152:153]
	s_waitcnt vmcnt(10)
	s_waitcnt lgkmcnt(0)
	s_setprio 0
	s_barrier
	s_waitcnt lgkmcnt(0)
	v_mfma_f32_16x16x32_bf16 v[124:127], v[128:131], v[176:179], v[124:127]
	v_mfma_f32_16x16x32_bf16 v[120:123], v[136:139], v[176:179], v[120:123]
	v_mfma_f32_16x16x32_bf16 v[108:111], v[128:131], v[192:195], v[108:111]
	v_mfma_f32_16x16x32_bf16 v[104:107], v[136:139], v[192:195], v[104:107]
	v_mfma_f32_16x16x32_bf16 v[92:95], v[128:131], v[200:203], v[92:95]
	v_mfma_f32_16x16x32_bf16 v[88:91], v[136:139], v[200:203], v[88:91]
	v_mfma_f32_16x16x32_bf16 v[76:79], v[128:131], v[208:211], v[76:79]
	v_mfma_f32_16x16x32_bf16 v[72:75], v[136:139], v[208:211], v[72:75]
	v_mfma_f32_16x16x32_bf16 v[124:127], v[132:135], v[180:183], v[124:127]
	v_mfma_f32_16x16x32_bf16 v[120:123], v[140:143], v[180:183], v[120:123]
	v_mfma_f32_16x16x32_bf16 v[108:111], v[132:135], v[196:199], v[108:111]
	v_mfma_f32_16x16x32_bf16 v[104:107], v[140:143], v[196:199], v[104:107]
	v_mfma_f32_16x16x32_bf16 v[92:95], v[132:135], v[204:207], v[92:95]
	v_mfma_f32_16x16x32_bf16 v[88:91], v[140:143], v[204:207], v[88:91]
	v_mfma_f32_16x16x32_bf16 v[76:79], v[132:135], v[212:215], v[76:79]
	v_mfma_f32_16x16x32_bf16 v[72:75], v[140:143], v[212:215], v[72:75]
	v_mfma_f32_16x16x32_bf16 v[116:119], v[144:147], v[176:179], v[116:119]
	v_mfma_f32_16x16x32_bf16 v[112:115], v[168:171], v[176:179], v[112:115]
	v_mfma_f32_16x16x32_bf16 v[100:103], v[144:147], v[192:195], v[100:103]
	v_mfma_f32_16x16x32_bf16 v[96:99], v[168:171], v[192:195], v[96:99]
	v_mfma_f32_16x16x32_bf16 v[84:87], v[144:147], v[200:203], v[84:87]
	v_mfma_f32_16x16x32_bf16 v[80:83], v[168:171], v[200:203], v[80:83]
	v_mfma_f32_16x16x32_bf16 v[68:71], v[144:147], v[208:211], v[68:71]
	v_mfma_f32_16x16x32_bf16 v[64:67], v[168:171], v[208:211], v[64:67]
	v_mfma_f32_16x16x32_bf16 v[116:119], v[148:151], v[180:183], v[116:119]
	v_mfma_f32_16x16x32_bf16 v[112:115], v[172:175], v[180:183], v[112:115]
	v_mfma_f32_16x16x32_bf16 v[100:103], v[148:151], v[196:199], v[100:103]
	v_mfma_f32_16x16x32_bf16 v[96:99], v[172:175], v[196:199], v[96:99]
	v_mfma_f32_16x16x32_bf16 v[84:87], v[148:151], v[204:207], v[84:87]
	v_mfma_f32_16x16x32_bf16 v[80:83], v[172:175], v[204:207], v[80:83]
	v_mfma_f32_16x16x32_bf16 v[68:71], v[148:151], v[212:215], v[68:71]
	v_mfma_f32_16x16x32_bf16 v[64:67], v[172:175], v[212:215], v[64:67]
	s_barrier
	s_setprio 1
	s_add_i32 s22, s49, s39
	s_mov_b32 m0, s22
	ds_read_b128 v[176:179], v191 offset:16384
	ds_read_b128 v[180:183], v191 offset:17408
	ds_read_b128 v[192:195], v191 offset:18432
	ds_read_b128 v[196:199], v191 offset:19456
	ds_read_b128 v[200:203], v191 offset:20480
	ds_read_b128 v[204:207], v191 offset:21504
	ds_read_b128 v[208:211], v191 offset:22528
	ds_read_b128 v[212:215], v191 offset:23552
	global_load_lds_dwordx4 v[184:185], off
	s_add_i32 m0, s22, 0x2000
	s_add_i32 s59, s50, s39
	global_load_lds_dwordx4 v[216:217], off
	s_mov_b32 m0, s59
	s_nop 0
	global_load_lds_dwordx4 v[246:247], off
	s_add_i32 m0, s59, 0x2000
	s_nop 0
	global_load_lds_dwordx4 v[248:249], off
	s_waitcnt vmcnt(4)
	s_waitcnt lgkmcnt(0)
	s_setprio 0
	s_barrier
; #define PG8_STAGE(bufoff, gbase, voff) do { _Pragma("unroll") for (int _i = 0; _i < 2; ++_i) \
;         __builtin_amdgcn_global_load_lds((const unsigned*)((const char*)(gbase) + (voff)[_i]), (PG8_LAS unsigned*)(lds + (bufoff) + ldsw + _i * 8192), 16, 0, 0); } while (0)
; #define PG8_LDA(dst, b, h) do { _Pragma("unroll") for (int m = 0; m < 4; ++m) _Pragma("unroll") for (int k = 0; k < 2; ++k) dst[m][k] = *(const PG8_LAS bf16x8*)(lds + PG8_SA(b, h) + aoff + m * 2048 + k * 1024); } while (0)
; #define PG8_LDB(dst, b, h) do { _Pragma("unroll") for (int n = 0; n < 2; ++n) _Pragma("unroll") for (int k = 0; k < 2; ++k) dst[n][k] = *(const PG8_LAS bf16x8*)(lds + PG8_SB(b, h) + boff + n * 2048 + k * 1024); } while (0)
; #define PG8_MMA(ai, bj, At, Bt) do { __builtin_amdgcn_s_setprio(1); _Pragma("unroll") for (int m = 0; m < 4; ++m) _Pragma("unroll") for (int n = 0; n < 2; ++n) _Pragma("unroll") for (int k = 0; k < 2; ++k) \
;         acc[ai][bj][m][n] = __builtin_amdgcn_mfma_f32_16x16x32_bf16(Bt[n][k], At[m][k], acc[ai][bj][m][n], 0, 0, 0); __builtin_amdgcn_s_setprio(0); } while (0)
; #define PG8_WAIT_V(n) asm volatile("s_waitcnt vmcnt(" #n ")" ::: "memory")
; #define PG8_WAIT_L(n) asm volatile("s_waitcnt lgkmcnt(" #n ")" ::: "memory")
; #define PG8_BAR __builtin_amdgcn_s_barrier()
; #define PG8_SCHED __builtin_amdgcn_sched_barrier(0)
; template <class Epi, class Sched, bool ALIGN_EPI = false, bool SP2 = false>
; __device__ __forceinline__ void gemm_phase(PG8_LAS unsigned char* lds, const Gemm g, const Sched& S, const Epi& E) {
;     ...
;             PG8_LDA(At, 0, 1); PG8_STAGE(PG8_SB(0, 0), b2, voffB); PG8_STAGE(PG8_SB(0, 1), b2 + hstep, voffB); PG8_STAGE(PG8_SA(0, 0), a2, voffA);
;             PG8_WAIT_V(8); PG8_WAIT_L(0); PG8_BAR; PG8_MMA(1, 0, At, B0); PG8_MMA(1, 1, At, B1); PG8_BAR; PG8_SCHED;
;             PG8_LDB(B0, 1, 0); PG8_LDB(B1, 1, 1); PG8_SCHED; PG8_LDA(At, 1, 0); PG8_STAGE(PG8_SA(0, 1), a2 + hstep, voffA);
;             PG8_WAIT_V(8); PG8_WAIT_L(0); PG8_BAR; PG8_MMA(0, 0, At, B0); PG8_MMA(0, 1, At, B1); PG8_BAR; PG8_SCHED;
	s_waitcnt lgkmcnt(0)
	v_mfma_f32_16x16x32_bf16 v[60:63], v[128:131], v[176:179], v[60:63]
	v_mfma_f32_16x16x32_bf16 v[56:59], v[136:139], v[176:179], v[56:59]
	v_mfma_f32_16x16x32_bf16 v[44:47], v[128:131], v[192:195], v[44:47]
	v_mfma_f32_16x16x32_bf16 v[40:43], v[136:139], v[192:195], v[40:43]
	v_mfma_f32_16x16x32_bf16 v[28:31], v[128:131], v[200:203], v[28:31]
	v_mfma_f32_16x16x32_bf16 v[24:27], v[136:139], v[200:203], v[24:27]
	v_mfma_f32_16x16x32_bf16 v[12:15], v[128:131], v[208:211], v[12:15]
	v_mfma_f32_16x16x32_bf16 v[8:11], v[136:139], v[208:211], v[8:11]
	v_mfma_f32_16x16x32_bf16 v[60:63], v[132:135], v[180:183], v[60:63]
	v_mfma_f32_16x16x32_bf16 v[56:59], v[140:143], v[180:183], v[56:59]
	v_mfma_f32_16x16x32_bf16 v[44:47], v[132:135], v[196:199], v[44:47]
	v_mfma_f32_16x16x32_bf16 v[40:43], v[140:143], v[196:199], v[40:43]
	v_mfma_f32_16x16x32_bf16 v[28:31], v[132:135], v[204:207], v[28:31]
	v_mfma_f32_16x16x32_bf16 v[24:27], v[140:143], v[204:207], v[24:27]
	v_mfma_f32_16x16x32_bf16 v[12:15], v[132:135], v[212:215], v[12:15]
	v_mfma_f32_16x16x32_bf16 v[8:11], v[140:143], v[212:215], v[8:11]
	v_mfma_f32_16x16x32_bf16 v[52:55], v[144:147], v[176:179], v[52:55]
	v_mfma_f32_16x16x32_bf16 v[48:51], v[168:171], v[176:179], v[48:51]
	v_mfma_f32_16x16x32_bf16 v[36:39], v[144:147], v[192:195], v[36:39]
	v_mfma_f32_16x16x32_bf16 v[32:35], v[168:171], v[192:195], v[32:35]
	v_mfma_f32_16x16x32_bf16 v[20:23], v[144:147], v[200:203], v[20:23]
	v_mfma_f32_16x16x32_bf16 v[16:19], v[168:171], v[200:203], v[16:19]
	v_mfma_f32_16x16x32_bf16 v[4:7], v[144:147], v[208:211], v[4:7]
	v_mfma_f32_16x16x32_bf16 v[0:3], v[168:171], v[208:211], v[0:3]
	v_mfma_f32_16x16x32_bf16 v[52:55], v[148:151], v[180:183], v[52:55]
	v_mfma_f32_16x16x32_bf16 v[48:51], v[172:175], v[180:183], v[48:51]
	v_mfma_f32_16x16x32_bf16 v[36:39], v[148:151], v[196:199], v[36:39]
	v_mfma_f32_16x16x32_bf16 v[32:35], v[172:175], v[196:199], v[32:35]
	v_mfma_f32_16x16x32_bf16 v[20:23], v[148:151], v[204:207], v[20:23]
	v_mfma_f32_16x16x32_bf16 v[16:19], v[172:175], v[204:207], v[16:19]
	v_mfma_f32_16x16x32_bf16 v[4:7], v[148:151], v[212:215], v[4:7]
	v_mfma_f32_16x16x32_bf16 v[0:3], v[172:175], v[212:215], v[0:3]
	s_barrier
	s_setprio 1
	s_add_i32 s59, 0, 0x18000
	s_add_i32 s60, 0, 0x1c000
	v_add_u32_e32 v140, s59, v187
	v_add_u32_e32 v172, s60, v187
	ds_read_b128 v[128:131], v140
	ds_read_b128 v[132:135], v140 offset:1024
	ds_read_b128 v[136:139], v140 offset:2048
	ds_read_b128 v[140:143], v140 offset:3072
	ds_read_b128 v[144:147], v172
	ds_read_b128 v[148:151], v172 offset:1024
	ds_read_b128 v[168:171], v172 offset:2048
	ds_read_b128 v[172:175], v172 offset:3072
	s_add_u32 s22, s30, 0x160000
	s_addc_u32 s23, s31, 0
	s_mov_b32 m0, s42
	v_lshl_add_u64 v[222:223], s[22:23], 0, v[152:153]
	ds_read_b128 v[176:179], v191 offset:32768
	ds_read_b128 v[180:183], v191 offset:33792
	ds_read_b128 v[192:195], v191 offset:34816
	ds_read_b128 v[196:199], v191 offset:35840
	ds_read_b128 v[200:203], v191 offset:36864
	ds_read_b128 v[204:207], v191 offset:37888
	ds_read_b128 v[208:211], v191 offset:38912
	ds_read_b128 v[212:215], v191 offset:39936
	global_load_lds_dwordx4 v[222:223], off
	v_lshl_add_u64 v[222:223], s[22:23], 0, v[156:157]
	s_mov_b32 m0, s43
	s_nop 0
	global_load_lds_dwordx4 v[222:223], off
	s_mov_b32 m0, s40
	s_nop 0
	global_load_lds_dwordx4 v[218:219], off
	s_mov_b32 m0, s41
	s_nop 0
	global_load_lds_dwordx4 v[220:221], off
	s_add_u32 s22, s28, 0x160080
	s_addc_u32 s23, s29, 0
	v_lshl_add_u64 v[184:185], v[184:185], 0, s[12:13]
	v_lshl_add_u64 v[216:217], v[216:217], 0, s[12:13]
	v_lshl_add_u64 v[246:247], s[22:23], 0, v[154:155]
	v_lshl_add_u64 v[248:249], s[22:23], 0, v[158:159]
	v_lshl_add_u64 v[250:251], v[218:219], 0, s[12:13]
	v_lshl_add_u64 v[252:253], v[220:221], 0, s[12:13]
	s_waitcnt vmcnt(10)
	s_waitcnt lgkmcnt(0)
	s_setprio 0
	s_barrier
; #define PG8_STAGE(bufoff, gbase, voff) do { _Pragma("unroll") for (int _i = 0; _i < 2; ++_i) \
;         __builtin_amdgcn_global_load_lds((const unsigned*)((const char*)(gbase) + (voff)[_i]), (PG8_LAS unsigned*)(lds + (bufoff) + ldsw + _i * 8192), 16, 0, 0); } while (0)
; #define PG8_LDA(dst, b, h) do { _Pragma("unroll") for (int m = 0; m < 4; ++m) _Pragma("unroll") for (int k = 0; k < 2; ++k) dst[m][k] = *(const PG8_LAS bf16x8*)(lds + PG8_SA(b, h) + aoff + m * 2048 + k * 1024); } while (0)
; #define PG8_MMA(ai, bj, At, Bt) do { __builtin_amdgcn_s_setprio(1); _Pragma("unroll") for (int m = 0; m < 4; ++m) _Pragma("unroll") for (int n = 0; n < 2; ++n) _Pragma("unroll") for (int k = 0; k < 2; ++k) \
;         acc[ai][bj][m][n] = __builtin_amdgcn_mfma_f32_16x16x32_bf16(Bt[n][k], At[m][k], acc[ai][bj][m][n], 0, 0, 0); __builtin_amdgcn_s_setprio(0); } while (0)
; #define PG8_WAIT_V(n) asm volatile("s_waitcnt vmcnt(" #n ")" ::: "memory")
; #define PG8_WAIT_L(n) asm volatile("s_waitcnt lgkmcnt(" #n ")" ::: "memory")
; #define PG8_BAR __builtin_amdgcn_s_barrier()
; #define PG8_SCHED __builtin_amdgcn_sched_barrier(0)
; template <class Epi, class Sched, bool ALIGN_EPI = false, bool SP2 = false>
; __device__ __forceinline__ void gemm_phase(PG8_LAS unsigned char* lds, const Gemm g, const Sched& S, const Epi& E) {
;     ...
;             PG8_WAIT_V(8); PG8_WAIT_L(0); PG8_BAR; PG8_MMA(0, 0, At, B0); PG8_MMA(0, 1, At, B1); PG8_BAR; PG8_SCHED;
;             PG8_LDA(At, 1, 1); PG8_STAGE(PG8_SB(1, 0), b3, voffB); PG8_STAGE(PG8_SB(1, 1), b3 + hstep, voffB); PG8_STAGE(PG8_SA(1, 0), a3, voffA);
;             PG8_WAIT_V(8); PG8_WAIT_L(0); PG8_BAR; PG8_MMA(1, 0, At, B0); PG8_MMA(1, 1, At, B1); PG8_BAR; PG8_SCHED;
;     ...
;         if constexpr (ALIGN_EPI) { if (wr == 0) PG8_BAR; }
	s_waitcnt lgkmcnt(0)
	v_mfma_f32_16x16x32_bf16 v[124:127], v[128:131], v[176:179], v[124:127]
	v_mfma_f32_16x16x32_bf16 v[120:123], v[136:139], v[176:179], v[120:123]
	v_mfma_f32_16x16x32_bf16 v[108:111], v[128:131], v[192:195], v[108:111]
	v_mfma_f32_16x16x32_bf16 v[104:107], v[136:139], v[192:195], v[104:107]
	v_mfma_f32_16x16x32_bf16 v[92:95], v[128:131], v[200:203], v[92:95]
	v_mfma_f32_16x16x32_bf16 v[88:91], v[136:139], v[200:203], v[88:91]
	v_mfma_f32_16x16x32_bf16 v[76:79], v[128:131], v[208:211], v[76:79]
	v_mfma_f32_16x16x32_bf16 v[72:75], v[136:139], v[208:211], v[72:75]
	v_mfma_f32_16x16x32_bf16 v[124:127], v[132:135], v[180:183], v[124:127]
	v_mfma_f32_16x16x32_bf16 v[120:123], v[140:143], v[180:183], v[120:123]
	v_mfma_f32_16x16x32_bf16 v[108:111], v[132:135], v[196:199], v[108:111]
	v_mfma_f32_16x16x32_bf16 v[104:107], v[140:143], v[196:199], v[104:107]
	v_mfma_f32_16x16x32_bf16 v[92:95], v[132:135], v[204:207], v[92:95]
	v_mfma_f32_16x16x32_bf16 v[88:91], v[140:143], v[204:207], v[88:91]
	v_mfma_f32_16x16x32_bf16 v[76:79], v[132:135], v[212:215], v[76:79]
	v_mfma_f32_16x16x32_bf16 v[72:75], v[140:143], v[212:215], v[72:75]
	v_mfma_f32_16x16x32_bf16 v[116:119], v[144:147], v[176:179], v[116:119]
	v_mfma_f32_16x16x32_bf16 v[112:115], v[168:171], v[176:179], v[112:115]
	v_mfma_f32_16x16x32_bf16 v[100:103], v[144:147], v[192:195], v[100:103]
	v_mfma_f32_16x16x32_bf16 v[96:99], v[168:171], v[192:195], v[96:99]
	v_mfma_f32_16x16x32_bf16 v[84:87], v[144:147], v[200:203], v[84:87]
	v_mfma_f32_16x16x32_bf16 v[80:83], v[168:171], v[200:203], v[80:83]
	v_mfma_f32_16x16x32_bf16 v[68:71], v[144:147], v[208:211], v[68:71]
	v_mfma_f32_16x16x32_bf16 v[64:67], v[168:171], v[208:211], v[64:67]
	v_mfma_f32_16x16x32_bf16 v[116:119], v[148:151], v[180:183], v[116:119]
	v_mfma_f32_16x16x32_bf16 v[112:115], v[172:175], v[180:183], v[112:115]
	v_mfma_f32_16x16x32_bf16 v[100:103], v[148:151], v[196:199], v[100:103]
	v_mfma_f32_16x16x32_bf16 v[96:99], v[172:175], v[196:199], v[96:99]
	v_mfma_f32_16x16x32_bf16 v[84:87], v[148:151], v[204:207], v[84:87]
	v_mfma_f32_16x16x32_bf16 v[80:83], v[172:175], v[204:207], v[80:83]
	v_mfma_f32_16x16x32_bf16 v[68:71], v[148:151], v[212:215], v[68:71]
	v_mfma_f32_16x16x32_bf16 v[64:67], v[172:175], v[212:215], v[64:67]
	s_barrier
	s_setprio 1
	s_add_i32 s22, s59, s39
	s_mov_b32 m0, s22
	ds_read_b128 v[176:179], v191 offset:49152
	ds_read_b128 v[180:183], v191 offset:50176
	ds_read_b128 v[192:195], v191 offset:51200
	ds_read_b128 v[196:199], v191 offset:52224
	ds_read_b128 v[200:203], v191 offset:53248
	ds_read_b128 v[204:207], v191 offset:54272
	ds_read_b128 v[208:211], v191 offset:55296
	ds_read_b128 v[212:215], v191 offset:56320
	global_load_lds_dwordx4 v[184:185], off
	s_add_i32 m0, s22, 0x2000
	s_add_i32 s28, s60, s39
	global_load_lds_dwordx4 v[216:217], off
	s_mov_b32 m0, s28
	s_nop 0
	global_load_lds_dwordx4 v[246:247], off
	s_add_i32 m0, s28, 0x2000
	s_nop 0
	global_load_lds_dwordx4 v[248:249], off
	s_waitcnt vmcnt(4)
	s_waitcnt lgkmcnt(0)
	s_setprio 0
	s_barrier
	s_waitcnt lgkmcnt(0)
	v_mfma_f32_16x16x32_bf16 v[60:63], v[128:131], v[176:179], v[60:63]
	v_mfma_f32_16x16x32_bf16 v[56:59], v[136:139], v[176:179], v[56:59]
	v_mfma_f32_16x16x32_bf16 v[44:47], v[128:131], v[192:195], v[44:47]
	v_mfma_f32_16x16x32_bf16 v[40:43], v[136:139], v[192:195], v[40:43]
	v_mfma_f32_16x16x32_bf16 v[28:31], v[128:131], v[200:203], v[28:31]
	v_mfma_f32_16x16x32_bf16 v[24:27], v[136:139], v[200:203], v[24:27]
	v_mfma_f32_16x16x32_bf16 v[12:15], v[128:131], v[208:211], v[12:15]
	v_mfma_f32_16x16x32_bf16 v[8:11], v[136:139], v[208:211], v[8:11]
	v_mfma_f32_16x16x32_bf16 v[60:63], v[132:135], v[180:183], v[60:63]
	v_mfma_f32_16x16x32_bf16 v[56:59], v[140:143], v[180:183], v[56:59]
	v_mfma_f32_16x16x32_bf16 v[44:47], v[132:135], v[196:199], v[44:47]
	v_mfma_f32_16x16x32_bf16 v[40:43], v[140:143], v[196:199], v[40:43]
	v_mfma_f32_16x16x32_bf16 v[28:31], v[132:135], v[204:207], v[28:31]
	v_mfma_f32_16x16x32_bf16 v[24:27], v[140:143], v[204:207], v[24:27]
	v_mfma_f32_16x16x32_bf16 v[12:15], v[132:135], v[212:215], v[12:15]
	v_mfma_f32_16x16x32_bf16 v[8:11], v[140:143], v[212:215], v[8:11]
	v_mfma_f32_16x16x32_bf16 v[52:55], v[144:147], v[176:179], v[52:55]
	v_mfma_f32_16x16x32_bf16 v[48:51], v[168:171], v[176:179], v[48:51]
	v_mfma_f32_16x16x32_bf16 v[36:39], v[144:147], v[192:195], v[36:39]
	v_mfma_f32_16x16x32_bf16 v[32:35], v[168:171], v[192:195], v[32:35]
	v_mfma_f32_16x16x32_bf16 v[20:23], v[144:147], v[200:203], v[20:23]
	v_mfma_f32_16x16x32_bf16 v[16:19], v[168:171], v[200:203], v[16:19]
	v_mfma_f32_16x16x32_bf16 v[4:7], v[144:147], v[208:211], v[4:7]
	v_mfma_f32_16x16x32_bf16 v[0:3], v[168:171], v[208:211], v[0:3]
	v_mfma_f32_16x16x32_bf16 v[52:55], v[148:151], v[180:183], v[52:55]
	v_mfma_f32_16x16x32_bf16 v[48:51], v[172:175], v[180:183], v[48:51]
	v_mfma_f32_16x16x32_bf16 v[36:39], v[148:151], v[196:199], v[36:39]
	v_mfma_f32_16x16x32_bf16 v[32:35], v[172:175], v[196:199], v[32:35]
	v_mfma_f32_16x16x32_bf16 v[20:23], v[148:151], v[204:207], v[20:23]
	v_mfma_f32_16x16x32_bf16 v[16:19], v[172:175], v[204:207], v[16:19]
	v_mfma_f32_16x16x32_bf16 v[4:7], v[148:151], v[212:215], v[4:7]
	v_mfma_f32_16x16x32_bf16 v[0:3], v[172:175], v[212:215], v[0:3]
	s_barrier
	s_add_i32 s58, s58, 2
	s_add_u32 s56, s56, 0x100
	s_addc_u32 s57, s57, 0
	s_cmpk_gt_u32 s58, 0x55
	s_mov_b64 s[22:23], s[24:25]
	s_cbranch_scc0 .LBB0_788
	s_and_b64 vcc, exec, s[14:15]
	s_cbranch_vccz .LBB0_791
	s_barrier

; #define PG8_STAGE(bufoff, gbase, voff) do { _Pragma("unroll") for (int _i = 0; _i < 2; ++_i) \
;         __builtin_amdgcn_global_load_lds((const unsigned*)((const char*)(gbase) + (voff)[_i]), (PG8_LAS unsigned*)(lds + (bufoff) + ldsw + _i * 8192), 16, 0, 0); } while (0)
; #define PG8_WAIT_V(n) asm volatile("s_waitcnt vmcnt(" #n ")" ::: "memory")
; #define PG8_BAR __builtin_amdgcn_s_barrier()
; template <class Epi, class Sched, bool ALIGN_EPI = false, bool SP2 = false>
; __device__ __forceinline__ void gemm_phase(PG8_LAS unsigned char* lds, const Gemm g, const Sched& S, const Epi& E) {
;     ...
;     const unsigned ldsw = (unsigned)wid * 1024u;
;     const int aoff = lds_byte(wr * 64 + fr, fq * 8), boff = lds_byte(wc * 32 + fr, fq * 8);
;     ...
;     Unit cur, nxt; int ui = 0;
;     if (!S.next(0, cur)) return;
;     f32x4 acc[2][2][4][2];
; #pragma unroll
;     for (int a = 0; a < 2; ++a)
; #pragma unroll
;         for (int b = 0; b < 2; ++b)
; #pragma unroll
;             for (int m = 0; m < 4; ++m)
; #pragma unroll
;                 for (int n = 0; n < 2; ++n) acc[a][b][m][n] = (f32x4){0.f, 0.f, 0.f, 0.f};
;     bf16x8 At[4][2], B0[2][2], B1[2][2];
;     const char* cA = (const char*)g.A + (size_t)cur.pm * tstep; const char* cB = (const char*)g.Bt + (size_t)cur.pn * tstep;
;     S.a_ready(cur);
;     if constexpr (SP2) {
;         PG8_STAGE(PG8_SB(0, 0), cB, voffB); PG8_STAGE(PG8_SB(0, 1), cB + hstep, voffB); PG8_STAGE(PG8_SA(0, 0), cA, voffA); PG8_STAGE(PG8_SA(0, 1), cA + hstep, voffA);
;         if (wr == 1) PG8_BAR;
;         PG8_WAIT_V(2); PG8_BAR;
;         PG8_STAGE(PG8_SB(1, 0), cB + kstep, voffB); PG8_STAGE(PG8_SA(1, 0), cA + kstep, voffA); PG8_STAGE(PG8_SB(1, 1), cB + hstep + kstep, voffB);
;         PG8_WAIT_V(6); PG8_BAR;
.LBB0_866:
	s_add_u32 s4, s6, 0x1c600000
	s_addc_u32 s5, s7, 0
	s_add_u32 s6, s6, 0x34f40000
	s_addc_u32 s7, s7, 0
	s_lshl_b32 s8, s8, 5
	s_and_b32 s14, s8, 0x60
	s_mov_b64 s[8:9], 0x80
	s_add_i32 m0, s25, 0x18000
	v_lshl_add_u64 v[6:7], v[6:7], 0, s[8:9]
	s_lshl_b32 s11, s10, 13
	s_lshl_b32 s15, s14, 7
	s_waitcnt vmcnt(2)
	s_barrier
	global_load_lds_dwordx4 v[6:7], off
	v_lshl_add_u64 v[4:5], v[4:5], 0, s[8:9]
	s_add_i32 m0, s25, 0x1a000
	s_add_i32 s48, s25, 0x8000
	s_add_i32 s49, s25, 0xa000
	global_load_lds_dwordx4 v[4:5], off
	v_lshl_add_u64 v[0:1], v[0:1], 0, s[8:9]
	s_mov_b32 m0, s48
	s_add_u32 s12, s30, 0x80080
	global_load_lds_dwordx4 v[0:1], off
	v_mov_b64_e32 v[250:251], v[0:1]
	v_lshl_add_u64 v[0:1], v[2:3], 0, s[8:9]
	s_mov_b32 m0, s49
	s_addc_u32 s13, s31, 0
	global_load_lds_dwordx4 v[0:1], off
	v_mov_b64_e32 v[252:253], v[0:1]
	s_add_i32 m0, s25, 0x1c000
	v_lshl_add_u64 v[0:1], s[12:13], 0, v[132:133]
	global_load_lds_dwordx4 v[0:1], off
	v_lshl_add_u64 v[0:1], s[12:13], 0, v[128:129]
	s_add_i32 m0, s25, 0x1e000
	s_cmpk_lt_u32 s3, 0x100
	global_load_lds_dwordx4 v[0:1], off
	v_lshrrev_b32_e32 v1, 1, v9
	v_and_b32_e32 v1, 24, v1
	v_and_b32_e32 v0, 15, v9
	v_lshlrev_b32_e32 v2, 1, v1
	v_lshl_or_b32 v152, s10, 6, v0
	v_lshl_or_b32 v0, v0, 6, v2
	v_lshlrev_b32_e32 v2, 2, v9
	v_and_b32_e32 v2, 32, v2
	v_bitop3_b32 v3, v0, s11, v2 bitop3:0xde
	v_bitop3_b32 v153, v0, s15, v2 bitop3:0xde
	v_lshlrev_b32_e32 v0, 15, v13
	v_and_b32_e32 v0, 0xffff0000, v0
	v_or_b32_e32 v154, s14, v1
	v_lshl_add_u32 v0, v12, 12, v0
	v_and_b32_e32 v1, 1, v13
	v_lshl_or_b32 v0, v1, 6, v0
	v_lshl_add_u32 v136, v14, 1, v0
	v_lshlrev_b32_e32 v0, 15, v8
	v_and_b32_e32 v0, 0xffff0000, v0
	s_waitcnt vmcnt(6)
	v_lshl_add_u32 v0, v10, 12, v0
	v_and_b32_e32 v1, 1, v8
	s_cselect_b64 s[10:11], -1, 0
	v_lshl_or_b32 v0, v1, 6, v0
	s_add_i32 s52, 0, 0x10000
	s_add_i32 s53, 0, 0x14000
	s_sext_i32_i16 s55, s2
	s_mov_b32 s50, 0
	s_ashr_i32 s51, s37, 31
	v_mov_b32_e32 v137, v133
	v_lshl_add_u32 v138, v11, 1, v0
	v_mov_b32_e32 v139, v133
	v_mov_b64_e32 v[140:141], 0x5c0
	v_mov_b64_e32 v[142:143], 0x5bf
	v_add_u32_e32 v155, s52, v153
	v_add_u32_e32 v156, s53, v153
	v_add_u32_e32 v157, 0, v3
	v_mov_b32_e32 v158, 0x358637bd
	s_movk_i32 s54, 0x2e00
	v_mov_b32_e32 v159, 0x3e38aa3b
	s_barrier
	s_branch .LBB0_869

; #define PG8_STAGE(bufoff, gbase, voff) do { _Pragma("unroll") for (int _i = 0; _i < 2; ++_i) \
;         __builtin_amdgcn_global_load_lds((const unsigned*)((const char*)(gbase) + (voff)[_i]), (PG8_LAS unsigned*)(lds + (bufoff) + ldsw + _i * 8192), 16, 0, 0); } while (0)
; #define PG8_WAIT_V(n) asm volatile("s_waitcnt vmcnt(" #n ")" ::: "memory")
; #define PG8_BAR __builtin_amdgcn_s_barrier()
; template <class Epi, class Sched, bool ALIGN_EPI = false, bool SP2 = false>
; __device__ __forceinline__ void gemm_phase(PG8_LAS unsigned char* lds, const Gemm g, const Sched& S, const Epi& E) {
;     ...
;     const unsigned ldsw = (unsigned)wid * 1024u;
;     const int aoff = lds_byte(wr * 64 + fr, fq * 8), boff = lds_byte(wc * 32 + fr, fq * 8);
;     ...
;     Unit cur, nxt; int ui = 0;
;     if (!S.next(0, cur)) return;
;     f32x4 acc[2][2][4][2];
; #pragma unroll
;     for (int a = 0; a < 2; ++a)
; #pragma unroll
;         for (int b = 0; b < 2; ++b)
; #pragma unroll
;             for (int m = 0; m < 4; ++m)
; #pragma unroll
;                 for (int n = 0; n < 2; ++n) acc[a][b][m][n] = (f32x4){0.f, 0.f, 0.f, 0.f};
;     bf16x8 At[4][2], B0[2][2], B1[2][2];
;     const char* cA = (const char*)g.A + (size_t)cur.pm * tstep; const char* cB = (const char*)g.Bt + (size_t)cur.pn * tstep;
;     S.a_ready(cur);
;     if constexpr (SP2) {
;         PG8_STAGE(PG8_SB(0, 0), cB, voffB); PG8_STAGE(PG8_SB(0, 1), cB + hstep, voffB); PG8_STAGE(PG8_SA(0, 0), cA, voffA); PG8_STAGE(PG8_SA(0, 1), cA + hstep, voffA);
;         if (wr == 1) PG8_BAR;
;         PG8_WAIT_V(2); PG8_BAR;
;         PG8_STAGE(PG8_SB(1, 0), cB + kstep, voffB); PG8_STAGE(PG8_SA(1, 0), cA + kstep, voffA); PG8_STAGE(PG8_SB(1, 1), cB + hstep + kstep, voffB);
;         PG8_WAIT_V(6); PG8_BAR;
.LBB0_1333:
	s_add_u32 s6, s8, 0x18600000
	s_addc_u32 s7, s5, 0
	s_add_u32 s8, s8, 0x34f60000
	s_addc_u32 s9, s5, 0
	s_lshl_b32 s3, s3, 5
	s_mov_b64 s[10:11], 0x80
	s_and_b32 s14, s3, 0x60
	s_add_i32 m0, s31, 0x18000
	v_lshl_add_u64 v[6:7], v[6:7], 0, s[10:11]
	s_lshl_b32 s5, s2, 13
	s_lshl_b32 s3, s14, 7
	s_waitcnt vmcnt(2)
	s_barrier
	global_load_lds_dwordx4 v[6:7], off
	v_lshl_add_u64 v[4:5], v[4:5], 0, s[10:11]
	s_add_i32 m0, s31, 0x1a000
	s_add_i32 s50, s31, 0x8000
	s_add_i32 s51, s31, 0xa000
	global_load_lds_dwordx4 v[4:5], off
	v_lshl_add_u64 v[0:1], v[0:1], 0, s[10:11]
	s_mov_b32 m0, s50
	s_add_u32 s12, s36, 0x80080
	global_load_lds_dwordx4 v[0:1], off
	v_mov_b64_e32 v[250:251], v[0:1]
	v_lshl_add_u64 v[0:1], v[2:3], 0, s[10:11]
	s_mov_b32 m0, s51
	s_addc_u32 s13, s37, 0
	global_load_lds_dwordx4 v[0:1], off
	v_mov_b64_e32 v[252:253], v[0:1]
	s_add_i32 m0, s31, 0x1c000
	v_lshl_add_u64 v[0:1], s[12:13], 0, v[154:155]
	global_load_lds_dwordx4 v[0:1], off
	v_lshl_add_u64 v[0:1], s[12:13], 0, v[158:159]
	s_add_i32 m0, s31, 0x1e000
	s_cmpk_lt_u32 s4, 0x100
	global_load_lds_dwordx4 v[0:1], off
	v_bfe_u32 v0, v8, 4, 2
	v_and_b32_e32 v1, 15, v8
	v_lshlrev_b32_e32 v2, 4, v0
	v_lshl_or_b32 v186, s2, 6, v1
	v_lshl_or_b32 v1, v1, 6, v2
	v_lshlrev_b32_e32 v2, 2, v8
	v_and_b32_e32 v2, 32, v2
	v_bitop3_b32 v187, v1, s3, v2 bitop3:0xde
	v_cmp_eq_u32_e64 s[2:3], 0, v0
	v_lshl_or_b32 v188, v0, 3, s14
	v_lshlrev_b32_e32 v0, 15, v9
	v_and_b32_e32 v0, 0xffff0000, v0
	v_bitop3_b32 v3, v1, s5, v2 bitop3:0xde
	v_lshl_add_u32 v0, v10, 12, v0
	v_and_b32_e32 v1, 1, v9
	v_lshl_or_b32 v0, v1, 6, v0
	v_lshl_add_u32 v160, v11, 1, v0
	v_lshlrev_b32_e32 v0, 15, v12
	v_and_b32_e32 v0, 0xffff0000, v0
	s_waitcnt vmcnt(6)
	v_lshl_add_u32 v0, v13, 12, v0
	v_and_b32_e32 v1, 1, v12
	s_cselect_b64 s[12:13], -1, 0
	v_lshl_or_b32 v0, v1, 6, v0
	s_add_i32 s54, 0, 0x10000
	s_add_i32 s55, 0, 0x14000
	s_ashr_i32 s52, s40, 31
	s_ashr_i32 s53, s33, 31
	v_mov_b32_e32 v161, v155
	v_lshl_add_u32 v162, v14, 1, v0
	v_mov_b32_e32 v163, v155
	v_mov_b64_e32 v[164:165], 0x200
	v_mov_b64_e32 v[166:167], 0x1ff
	v_add_u32_e32 v189, s54, v187
	v_add_u32_e32 v190, s55, v187
	v_add_u32_e32 v191, 0, v3
	s_mov_b32 s56, 0x4b800000
	s_barrier
	s_branch .LBB0_1336

; #define PG8_STAGE(bufoff, gbase, voff) do { _Pragma("unroll") for (int _i = 0; _i < 2; ++_i) \
;         __builtin_amdgcn_global_load_lds((const unsigned*)((const char*)(gbase) + (voff)[_i]), (PG8_LAS unsigned*)(lds + (bufoff) + ldsw + _i * 8192), 16, 0, 0); } while (0)
; #define PG8_WAIT_V(n) asm volatile("s_waitcnt vmcnt(" #n ")" ::: "memory")
; #define PG8_BAR __builtin_amdgcn_s_barrier()
; template <class Epi, class Sched, bool ALIGN_EPI = false, bool SP2 = false>
; __device__ __forceinline__ void gemm_phase(PG8_LAS unsigned char* lds, const Gemm g, const Sched& S, const Epi& E) {
;     ...
;     const unsigned ldsw = (unsigned)wid * 1024u;
;     const int aoff = lds_byte(wr * 64 + fr, fq * 8), boff = lds_byte(wc * 32 + fr, fq * 8);
;     ...
;     Unit cur, nxt; int ui = 0;
;     if (!S.next(0, cur)) return;
;     f32x4 acc[2][2][4][2];
; #pragma unroll
;     for (int a = 0; a < 2; ++a)
; #pragma unroll
;         for (int b = 0; b < 2; ++b)
; #pragma unroll
;             for (int m = 0; m < 4; ++m)
; #pragma unroll
;                 for (int n = 0; n < 2; ++n) acc[a][b][m][n] = (f32x4){0.f, 0.f, 0.f, 0.f};
;     bf16x8 At[4][2], B0[2][2], B1[2][2];
;     const char* cA = (const char*)g.A + (size_t)cur.pm * tstep; const char* cB = (const char*)g.Bt + (size_t)cur.pn * tstep;
;     S.a_ready(cur);
;     if constexpr (SP2) {
;         PG8_STAGE(PG8_SB(0, 0), cB, voffB); PG8_STAGE(PG8_SB(0, 1), cB + hstep, voffB); PG8_STAGE(PG8_SA(0, 0), cA, voffA); PG8_STAGE(PG8_SA(0, 1), cA + hstep, voffA);
;         if (wr == 1) PG8_BAR;
;         PG8_WAIT_V(2); PG8_BAR;
;         PG8_STAGE(PG8_SB(1, 0), cB + kstep, voffB); PG8_STAGE(PG8_SA(1, 0), cA + kstep, voffA); PG8_STAGE(PG8_SB(1, 1), cB + hstep + kstep, voffB);
;         PG8_WAIT_V(6); PG8_BAR;
.LBB0_1421:
	s_add_u32 s4, s6, 0x1c600000
	s_addc_u32 s5, s7, 0
	s_add_u32 s6, s6, 0x34f60000
	s_addc_u32 s7, s7, 0
	s_lshl_b32 s8, s8, 5
	s_and_b32 s14, s8, 0x60
	s_mov_b64 s[8:9], 0x80
	s_add_i32 m0, s25, 0x18000
	v_lshl_add_u64 v[6:7], v[6:7], 0, s[8:9]
	s_lshl_b32 s11, s10, 13
	s_lshl_b32 s15, s14, 7
	s_waitcnt vmcnt(2)
	s_barrier
	global_load_lds_dwordx4 v[6:7], off
	v_lshl_add_u64 v[4:5], v[4:5], 0, s[8:9]
	s_add_i32 m0, s25, 0x1a000
	s_add_i32 s48, s25, 0x8000
	s_add_i32 s49, s25, 0xa000
	global_load_lds_dwordx4 v[4:5], off
	v_lshl_add_u64 v[0:1], v[0:1], 0, s[8:9]
	s_mov_b32 m0, s48
	s_add_u32 s12, s30, 0x80080
	global_load_lds_dwordx4 v[0:1], off
	v_mov_b64_e32 v[250:251], v[0:1]
	v_lshl_add_u64 v[0:1], v[2:3], 0, s[8:9]
	s_mov_b32 m0, s49
	s_addc_u32 s13, s31, 0
	global_load_lds_dwordx4 v[0:1], off
	v_mov_b64_e32 v[252:253], v[0:1]
	s_add_i32 m0, s25, 0x1c000
	v_lshl_add_u64 v[0:1], s[12:13], 0, v[132:133]
	global_load_lds_dwordx4 v[0:1], off
	v_lshl_add_u64 v[0:1], s[12:13], 0, v[128:129]
	s_add_i32 m0, s25, 0x1e000
	s_cmpk_lt_u32 s3, 0x100
	global_load_lds_dwordx4 v[0:1], off
	v_lshrrev_b32_e32 v1, 1, v9
	v_and_b32_e32 v1, 24, v1
	v_and_b32_e32 v0, 15, v9
	v_lshlrev_b32_e32 v2, 1, v1
	v_lshl_or_b32 v148, s10, 6, v0
	v_lshl_or_b32 v0, v0, 6, v2
	v_lshlrev_b32_e32 v2, 2, v9
	v_and_b32_e32 v2, 32, v2
	v_bitop3_b32 v3, v0, s11, v2 bitop3:0xde
	v_bitop3_b32 v149, v0, s15, v2 bitop3:0xde
	v_lshlrev_b32_e32 v0, 15, v13
	v_and_b32_e32 v0, 0xffff0000, v0
	v_or_b32_e32 v150, s14, v1
	v_lshl_add_u32 v0, v12, 12, v0
	v_and_b32_e32 v1, 1, v13
	v_lshl_or_b32 v0, v1, 6, v0
	v_lshl_add_u32 v136, v14, 1, v0
	v_lshlrev_b32_e32 v0, 15, v8
	v_and_b32_e32 v0, 0xffff0000, v0
	s_waitcnt vmcnt(6)
	v_lshl_add_u32 v0, v10, 12, v0
	v_and_b32_e32 v1, 1, v8
	s_cselect_b64 s[10:11], -1, 0
	v_lshl_or_b32 v0, v1, 6, v0
	s_add_i32 s52, 0, 0x10000
	s_add_i32 s53, 0, 0x14000
	s_sext_i32_i16 s55, s2
	s_mov_b32 s50, 0
	s_ashr_i32 s51, s37, 31
	v_mov_b32_e32 v137, v133
	v_lshl_add_u32 v138, v11, 1, v0
	v_mov_b32_e32 v139, v133
	v_mov_b64_e32 v[140:141], 0xb00
	v_mov_b64_e32 v[142:143], 0xaff
	v_add_u32_e32 v151, s52, v149
	v_add_u32_e32 v152, s53, v149
	v_add_u32_e32 v153, 0, v3
	v_mov_b32_e32 v154, 0x358637bd
	s_movk_i32 s54, 0x2c00
	s_barrier
	s_branch .LBB0_1424

; #define PG8_STAGE(bufoff, gbase, voff) do { _Pragma("unroll") for (int _i = 0; _i < 2; ++_i) \
;         __builtin_amdgcn_global_load_lds((const unsigned*)((const char*)(gbase) + (voff)[_i]), (PG8_LAS unsigned*)(lds + (bufoff) + ldsw + _i * 8192), 16, 0, 0); } while (0)
; #define PG8_WAIT_V(n) asm volatile("s_waitcnt vmcnt(" #n ")" ::: "memory")
; #define PG8_BAR __builtin_amdgcn_s_barrier()
; template <class Epi, class Sched, bool ALIGN_EPI = false, bool SP2 = false>
; __device__ __forceinline__ void gemm_phase(PG8_LAS unsigned char* lds, const Gemm g, const Sched& S, const Epi& E) {
;     ...
;     const unsigned ldsw = (unsigned)wid * 1024u;
;     const int aoff = lds_byte(wr * 64 + fr, fq * 8), boff = lds_byte(wc * 32 + fr, fq * 8);
;     ...
;     Unit cur, nxt; int ui = 0;
;     if (!S.next(0, cur)) return;
;     f32x4 acc[2][2][4][2];
; #pragma unroll
;     for (int a = 0; a < 2; ++a)
; #pragma unroll
;         for (int b = 0; b < 2; ++b)
; #pragma unroll
;             for (int m = 0; m < 4; ++m)
; #pragma unroll
;                 for (int n = 0; n < 2; ++n) acc[a][b][m][n] = (f32x4){0.f, 0.f, 0.f, 0.f};
;     bf16x8 At[4][2], B0[2][2], B1[2][2];
;     const char* cA = (const char*)g.A + (size_t)cur.pm * tstep; const char* cB = (const char*)g.Bt + (size_t)cur.pn * tstep;
;     S.a_ready(cur);
;     if constexpr (SP2) {
;         PG8_STAGE(PG8_SB(0, 0), cB, voffB); PG8_STAGE(PG8_SB(0, 1), cB + hstep, voffB); PG8_STAGE(PG8_SA(0, 0), cA, voffA); PG8_STAGE(PG8_SA(0, 1), cA + hstep, voffA);
;         if (wr == 1) PG8_BAR;
;         PG8_WAIT_V(2); PG8_BAR;
;         PG8_STAGE(PG8_SB(1, 0), cB + kstep, voffB); PG8_STAGE(PG8_SA(1, 0), cA + kstep, voffA); PG8_STAGE(PG8_SB(1, 1), cB + hstep + kstep, voffB);
;         PG8_WAIT_V(6); PG8_BAR;
.LBB0_1496:
	s_add_u32 s8, s6, 0x18600000
	s_addc_u32 s9, s5, 0
	s_add_u32 s10, s6, 0x34f80000
	s_addc_u32 s11, s5, 0
	s_lshl_b32 s3, s3, 5
	s_mov_b64 s[12:13], 0x80
	s_and_b32 s6, s3, 0x60
	s_add_i32 m0, s40, 0x18000
	v_lshl_add_u64 v[6:7], v[6:7], 0, s[12:13]
	s_lshl_b32 s5, s2, 13
	s_lshl_b32 s3, s6, 7
	s_waitcnt vmcnt(2)
	s_barrier
	global_load_lds_dwordx4 v[6:7], off
	v_lshl_add_u64 v[2:3], v[2:3], 0, s[12:13]
	s_add_i32 m0, s40, 0x1a000
	s_add_i32 s45, s40, 0x8000
	s_add_i32 s46, s40, 0xa000
	global_load_lds_dwordx4 v[2:3], off
	v_lshl_add_u64 v[0:1], v[0:1], 0, s[12:13]
	s_mov_b32 m0, s45
	s_add_u32 s14, s24, 0x160080
	global_load_lds_dwordx4 v[0:1], off
	v_mov_b64_e32 v[250:251], v[0:1]
	v_lshl_add_u64 v[0:1], v[4:5], 0, s[12:13]
	s_mov_b32 m0, s46
	s_addc_u32 s15, s25, 0
	global_load_lds_dwordx4 v[0:1], off
	v_mov_b64_e32 v[252:253], v[0:1]
	s_add_i32 m0, s40, 0x1c000
	v_lshl_add_u64 v[0:1], s[14:15], 0, v[154:155]
	global_load_lds_dwordx4 v[0:1], off
	v_lshl_add_u64 v[0:1], s[14:15], 0, v[158:159]
	s_add_i32 m0, s40, 0x1e000
	s_cmpk_lt_u32 s4, 0x100
	global_load_lds_dwordx4 v[0:1], off
	v_bfe_u32 v0, v8, 4, 2
	v_and_b32_e32 v1, 15, v8
	v_lshlrev_b32_e32 v2, 4, v0
	v_lshl_or_b32 v186, s2, 6, v1
	v_lshl_or_b32 v1, v1, 6, v2
	v_lshlrev_b32_e32 v2, 2, v8
	v_and_b32_e32 v2, 32, v2
	v_bitop3_b32 v3, v1, s5, v2 bitop3:0xde
	v_bitop3_b32 v187, v1, s3, v2 bitop3:0xde
	v_cmp_eq_u32_e64 s[2:3], 0, v0
	v_lshl_or_b32 v188, v0, 3, s6
	v_lshrrev_b32_e32 v1, 1, v9
	v_mul_lo_u32 v0, v10, s7
	v_mad_u64_u32 v[0:1], s[4:5], v1, s16, v[0:1]
	v_or_b32_e32 v0, v0, v11
	s_mov_b64 s[28:29], 0x160080
	v_add_lshl_u32 v0, v0, v12, 1
	v_mov_b32_e32 v1, v155
	v_lshl_add_u64 v[160:161], v[0:1], 0, s[28:29]
	v_lshrrev_b32_e32 v1, 1, v13
	v_mul_lo_u32 v0, v14, s7
	v_mad_u64_u32 v[0:1], s[4:5], v1, s16, v[0:1]
	s_waitcnt vmcnt(6)
	v_or_b32_e32 v0, v0, v15
	s_cselect_b64 s[14:15], -1, 0
	v_add_lshl_u32 v0, v0, v16, 1
	v_mov_b32_e32 v1, v155
	s_add_i32 s49, 0, 0x10000
	s_add_i32 s50, 0, 0x14000
	s_ashr_i32 s47, s34, 31
	s_ashr_i32 s48, s33, 31
	v_lshl_add_u64 v[162:163], v[0:1], 0, s[28:29]
	v_mov_b64_e32 v[164:165], 0x200
	v_mov_b64_e32 v[166:167], 0x1ff
	v_add_u32_e32 v189, s49, v187
	v_add_u32_e32 v190, s50, v187
	v_add_u32_e32 v191, 0, v3
	s_mov_b32 s51, 0x4b800000
	s_barrier
	s_branch .LBB0_1499

; #define PG8_STAGE(bufoff, gbase, voff) do { _Pragma("unroll") for (int _i = 0; _i < 2; ++_i) \
;         __builtin_amdgcn_global_load_lds((const unsigned*)((const char*)(gbase) + (voff)[_i]), (PG8_LAS unsigned*)(lds + (bufoff) + ldsw + _i * 8192), 16, 0, 0); } while (0)
; #define PG8_WAIT_V(n) asm volatile("s_waitcnt vmcnt(" #n ")" ::: "memory")
; #define PG8_BAR __builtin_amdgcn_s_barrier()
; template <class Epi, class Sched, bool ALIGN_EPI = false, bool SP2 = false>
; __device__ __forceinline__ void gemm_phase(PG8_LAS unsigned char* lds, const Gemm g, const Sched& S, const Epi& E) {
;     ...
;     const unsigned ldsw = (unsigned)wid * 1024u;
;     const int aoff = lds_byte(wr * 64 + fr, fq * 8), boff = lds_byte(wc * 32 + fr, fq * 8);
;     ...
;     Unit cur, nxt; int ui = 0;
;     if (!S.next(0, cur)) return;
;     f32x4 acc[2][2][4][2];
; #pragma unroll
;     for (int a = 0; a < 2; ++a)
; #pragma unroll
;         for (int b = 0; b < 2; ++b)
; #pragma unroll
;             for (int m = 0; m < 4; ++m)
; #pragma unroll
;                 for (int n = 0; n < 2; ++n) acc[a][b][m][n] = (f32x4){0.f, 0.f, 0.f, 0.f};
;     bf16x8 At[4][2], B0[2][2], B1[2][2];
;     const char* cA = (const char*)g.A + (size_t)cur.pm * tstep; const char* cB = (const char*)g.Bt + (size_t)cur.pn * tstep;
;     S.a_ready(cur);
;     if constexpr (SP2) {
;         PG8_STAGE(PG8_SB(0, 0), cB, voffB); PG8_STAGE(PG8_SB(0, 1), cB + hstep, voffB); PG8_STAGE(PG8_SA(0, 0), cA, voffA); PG8_STAGE(PG8_SA(0, 1), cA + hstep, voffA);
;         if (wr == 1) PG8_BAR;
;         PG8_WAIT_V(2); PG8_BAR;
;         PG8_STAGE(PG8_SB(1, 0), cB + kstep, voffB); PG8_STAGE(PG8_SA(1, 0), cA + kstep, voffA); PG8_STAGE(PG8_SB(1, 1), cB + hstep + kstep, voffB);
;         PG8_WAIT_V(6); PG8_BAR;
.LBB0_1588:
	s_add_u32 s4, s6, 0x1c600000
	s_addc_u32 s5, s7, 0
	s_add_u32 s6, s6, 0x34f80000
	s_addc_u32 s7, s7, 0
	s_lshl_b32 s8, s8, 5
	s_and_b32 s14, s8, 0x60
	s_mov_b64 s[8:9], 0x80
	s_add_i32 m0, s25, 0x18000
	v_lshl_add_u64 v[6:7], v[6:7], 0, s[8:9]
	s_lshl_b32 s11, s10, 13
	s_lshl_b32 s15, s14, 7
	s_waitcnt vmcnt(2)
	s_barrier
	global_load_lds_dwordx4 v[6:7], off
	v_lshl_add_u64 v[4:5], v[4:5], 0, s[8:9]
	s_add_i32 m0, s25, 0x1a000
	s_add_i32 s48, s25, 0x8000
	s_add_i32 s49, s25, 0xa000
	global_load_lds_dwordx4 v[4:5], off
	v_lshl_add_u64 v[0:1], v[0:1], 0, s[8:9]
	s_mov_b32 m0, s48
	s_add_u32 s12, s30, 0x80080
	global_load_lds_dwordx4 v[0:1], off
	v_mov_b64_e32 v[250:251], v[0:1]
	v_lshl_add_u64 v[0:1], v[2:3], 0, s[8:9]
	s_mov_b32 m0, s49
	s_addc_u32 s13, s31, 0
	global_load_lds_dwordx4 v[0:1], off
	v_mov_b64_e32 v[252:253], v[0:1]
	s_add_i32 m0, s25, 0x1c000
	v_lshl_add_u64 v[0:1], s[12:13], 0, v[132:133]
	global_load_lds_dwordx4 v[0:1], off
	v_lshl_add_u64 v[0:1], s[12:13], 0, v[128:129]
	s_add_i32 m0, s25, 0x1e000
	s_cmpk_lt_u32 s3, 0x100
	global_load_lds_dwordx4 v[0:1], off
	v_lshrrev_b32_e32 v1, 1, v9
	v_and_b32_e32 v1, 24, v1
	v_and_b32_e32 v0, 15, v9
	v_lshlrev_b32_e32 v2, 1, v1
	v_lshl_or_b32 v152, s10, 6, v0
	v_lshl_or_b32 v0, v0, 6, v2
	v_lshlrev_b32_e32 v2, 2, v9
	v_and_b32_e32 v2, 32, v2
	v_bitop3_b32 v3, v0, s11, v2 bitop3:0xde
	v_bitop3_b32 v153, v0, s15, v2 bitop3:0xde
	v_lshlrev_b32_e32 v0, 15, v13
	v_and_b32_e32 v0, 0xffff0000, v0
	v_or_b32_e32 v154, s14, v1
	v_lshl_add_u32 v0, v12, 12, v0
	v_and_b32_e32 v1, 1, v13
	v_lshl_or_b32 v0, v1, 6, v0
	v_lshl_add_u32 v136, v14, 1, v0
	v_lshlrev_b32_e32 v0, 15, v8
	v_and_b32_e32 v0, 0xffff0000, v0
	s_waitcnt vmcnt(6)
	v_lshl_add_u32 v0, v10, 12, v0
	v_and_b32_e32 v1, 1, v8
	s_cselect_b64 s[10:11], -1, 0
	v_lshl_or_b32 v0, v1, 6, v0
	s_add_i32 s52, 0, 0x10000
	s_add_i32 s53, 0, 0x14000
	s_sext_i32_i16 s55, s2
	s_mov_b32 s50, 0
	s_ashr_i32 s51, s37, 31
	v_mov_b32_e32 v137, v133
	v_lshl_add_u32 v138, v11, 1, v0
	v_mov_b32_e32 v139, v133
	v_mov_b64_e32 v[140:141], 0x5c0
	v_mov_b64_e32 v[142:143], 0x5bf
	v_add_u32_e32 v155, s52, v153
	v_add_u32_e32 v156, s53, v153
	v_add_u32_e32 v157, 0, v3
	v_mov_b32_e32 v158, 0x358637bd
	s_movk_i32 s54, 0x2e00
	v_mov_b32_e32 v159, 0x3e38aa3b
	s_barrier
	s_branch .LBB0_1591

; #define PG8_STAGE(bufoff, gbase, voff) do { _Pragma("unroll") for (int _i = 0; _i < 2; ++_i) \
;         __builtin_amdgcn_global_load_lds((const unsigned*)((const char*)(gbase) + (voff)[_i]), (PG8_LAS unsigned*)(lds + (bufoff) + ldsw + _i * 8192), 16, 0, 0); } while (0)
; #define PG8_WAIT_V(n) asm volatile("s_waitcnt vmcnt(" #n ")" ::: "memory")
; #define PG8_BAR __builtin_amdgcn_s_barrier()
; template <class Epi, class Sched, bool ALIGN_EPI = false, bool SP2 = false>
; __device__ __forceinline__ void gemm_phase(PG8_LAS unsigned char* lds, const Gemm g, const Sched& S, const Epi& E) {
;     ...
;     const unsigned ldsw = (unsigned)wid * 1024u;
;     const int aoff = lds_byte(wr * 64 + fr, fq * 8), boff = lds_byte(wc * 32 + fr, fq * 8);
;     ...
;     Unit cur, nxt; int ui = 0;
;     if (!S.next(0, cur)) return;
;     f32x4 acc[2][2][4][2];
; #pragma unroll
;     for (int a = 0; a < 2; ++a)
; #pragma unroll
;         for (int b = 0; b < 2; ++b)
; #pragma unroll
;             for (int m = 0; m < 4; ++m)
; #pragma unroll
;                 for (int n = 0; n < 2; ++n) acc[a][b][m][n] = (f32x4){0.f, 0.f, 0.f, 0.f};
;     bf16x8 At[4][2], B0[2][2], B1[2][2];
;     const char* cA = (const char*)g.A + (size_t)cur.pm * tstep; const char* cB = (const char*)g.Bt + (size_t)cur.pn * tstep;
;     S.a_ready(cur);
;     if constexpr (SP2) {
;         PG8_STAGE(PG8_SB(0, 0), cB, voffB); PG8_STAGE(PG8_SB(0, 1), cB + hstep, voffB); PG8_STAGE(PG8_SA(0, 0), cA, voffA); PG8_STAGE(PG8_SA(0, 1), cA + hstep, voffA);
;         if (wr == 1) PG8_BAR;
;         PG8_WAIT_V(2); PG8_BAR;
;         PG8_STAGE(PG8_SB(1, 0), cB + kstep, voffB); PG8_STAGE(PG8_SA(1, 0), cA + kstep, voffA); PG8_STAGE(PG8_SB(1, 1), cB + hstep + kstep, voffB);
;         PG8_WAIT_V(6); PG8_BAR;
.LBB0_2055:
	s_add_u32 s6, s8, 0x18600000
	s_addc_u32 s7, s5, 0
	s_add_u32 s8, s8, 0x34fa0000
	s_addc_u32 s9, s5, 0
	s_lshl_b32 s3, s3, 5
	s_mov_b64 s[10:11], 0x80
	s_and_b32 s14, s3, 0x60
	s_add_i32 m0, s31, 0x18000
	v_lshl_add_u64 v[6:7], v[6:7], 0, s[10:11]
	s_lshl_b32 s5, s2, 13
	s_lshl_b32 s3, s14, 7
	s_waitcnt vmcnt(2)
	s_barrier
	global_load_lds_dwordx4 v[6:7], off
	v_lshl_add_u64 v[4:5], v[4:5], 0, s[10:11]
	s_add_i32 m0, s31, 0x1a000
	s_add_i32 s50, s31, 0x8000
	s_add_i32 s51, s31, 0xa000
	global_load_lds_dwordx4 v[4:5], off
	v_lshl_add_u64 v[0:1], v[0:1], 0, s[10:11]
	s_mov_b32 m0, s50
	s_add_u32 s12, s36, 0x80080
	global_load_lds_dwordx4 v[0:1], off
	v_mov_b64_e32 v[250:251], v[0:1]
	v_lshl_add_u64 v[0:1], v[2:3], 0, s[10:11]
	s_mov_b32 m0, s51
	s_addc_u32 s13, s37, 0
	global_load_lds_dwordx4 v[0:1], off
	v_mov_b64_e32 v[252:253], v[0:1]
	s_add_i32 m0, s31, 0x1c000
	v_lshl_add_u64 v[0:1], s[12:13], 0, v[154:155]
	global_load_lds_dwordx4 v[0:1], off
	v_lshl_add_u64 v[0:1], s[12:13], 0, v[158:159]
	s_add_i32 m0, s31, 0x1e000
	s_cmpk_lt_u32 s4, 0x100
	global_load_lds_dwordx4 v[0:1], off
	v_bfe_u32 v0, v8, 4, 2
	v_and_b32_e32 v1, 15, v8
	v_lshlrev_b32_e32 v2, 4, v0
	v_lshl_or_b32 v186, s2, 6, v1
	v_lshl_or_b32 v1, v1, 6, v2
	v_lshlrev_b32_e32 v2, 2, v8
	v_and_b32_e32 v2, 32, v2
	v_bitop3_b32 v187, v1, s3, v2 bitop3:0xde
	v_cmp_eq_u32_e64 s[2:3], 0, v0
	v_lshl_or_b32 v188, v0, 3, s14
	v_lshlrev_b32_e32 v0, 15, v9
	v_and_b32_e32 v0, 0xffff0000, v0
	v_bitop3_b32 v3, v1, s5, v2 bitop3:0xde
	v_lshl_add_u32 v0, v10, 12, v0
	v_and_b32_e32 v1, 1, v9
	v_lshl_or_b32 v0, v1, 6, v0
	v_lshl_add_u32 v160, v11, 1, v0
	v_lshlrev_b32_e32 v0, 15, v12
	v_and_b32_e32 v0, 0xffff0000, v0
	s_waitcnt vmcnt(6)
	v_lshl_add_u32 v0, v13, 12, v0
	v_and_b32_e32 v1, 1, v12
	s_cselect_b64 s[12:13], -1, 0
	v_lshl_or_b32 v0, v1, 6, v0
	s_add_i32 s54, 0, 0x10000
	s_add_i32 s55, 0, 0x14000
	s_ashr_i32 s52, s40, 31
	s_ashr_i32 s53, s33, 31
	v_mov_b32_e32 v161, v155
	v_lshl_add_u32 v162, v14, 1, v0
	v_mov_b32_e32 v163, v155
	v_mov_b64_e32 v[164:165], 0x200
	v_mov_b64_e32 v[166:167], 0x1ff
	v_add_u32_e32 v189, s54, v187
	v_add_u32_e32 v190, s55, v187
	v_add_u32_e32 v191, 0, v3
	s_mov_b32 s56, 0x4b800000
	s_barrier
	s_branch .LBB0_2058

; #define PG8_STAGE(bufoff, gbase, voff) do { _Pragma("unroll") for (int _i = 0; _i < 2; ++_i) \
;         __builtin_amdgcn_global_load_lds((const unsigned*)((const char*)(gbase) + (voff)[_i]), (PG8_LAS unsigned*)(lds + (bufoff) + ldsw + _i * 8192), 16, 0, 0); } while (0)
; #define PG8_WAIT_V(n) asm volatile("s_waitcnt vmcnt(" #n ")" ::: "memory")
; #define PG8_BAR __builtin_amdgcn_s_barrier()
; template <class Epi, class Sched, bool ALIGN_EPI = false, bool SP2 = false>
; __device__ __forceinline__ void gemm_phase(PG8_LAS unsigned char* lds, const Gemm g, const Sched& S, const Epi& E) {
;     ...
;     const unsigned ldsw = (unsigned)wid * 1024u;
;     const int aoff = lds_byte(wr * 64 + fr, fq * 8), boff = lds_byte(wc * 32 + fr, fq * 8);
;     ...
;     Unit cur, nxt; int ui = 0;
;     if (!S.next(0, cur)) return;
;     f32x4 acc[2][2][4][2];
; #pragma unroll
;     for (int a = 0; a < 2; ++a)
; #pragma unroll
;         for (int b = 0; b < 2; ++b)
; #pragma unroll
;             for (int m = 0; m < 4; ++m)
; #pragma unroll
;                 for (int n = 0; n < 2; ++n) acc[a][b][m][n] = (f32x4){0.f, 0.f, 0.f, 0.f};
;     bf16x8 At[4][2], B0[2][2], B1[2][2];
;     const char* cA = (const char*)g.A + (size_t)cur.pm * tstep; const char* cB = (const char*)g.Bt + (size_t)cur.pn * tstep;
;     S.a_ready(cur);
;     if constexpr (SP2) {
;         PG8_STAGE(PG8_SB(0, 0), cB, voffB); PG8_STAGE(PG8_SB(0, 1), cB + hstep, voffB); PG8_STAGE(PG8_SA(0, 0), cA, voffA); PG8_STAGE(PG8_SA(0, 1), cA + hstep, voffA);
;         if (wr == 1) PG8_BAR;
;         PG8_WAIT_V(2); PG8_BAR;
;         PG8_STAGE(PG8_SB(1, 0), cB + kstep, voffB); PG8_STAGE(PG8_SA(1, 0), cA + kstep, voffA); PG8_STAGE(PG8_SB(1, 1), cB + hstep + kstep, voffB);
;         PG8_WAIT_V(6); PG8_BAR;
.LBB0_2143:
	s_add_u32 s4, s6, 0x1c600000
	s_addc_u32 s5, s7, 0
	s_add_u32 s6, s6, 0x34fa0000
	s_addc_u32 s7, s7, 0
	s_lshl_b32 s8, s8, 5
	s_and_b32 s14, s8, 0x60
	s_mov_b64 s[8:9], 0x80
	s_add_i32 m0, s25, 0x18000
	v_lshl_add_u64 v[6:7], v[6:7], 0, s[8:9]
	s_lshl_b32 s11, s10, 13
	s_lshl_b32 s15, s14, 7
	s_waitcnt vmcnt(2)
	s_barrier
	global_load_lds_dwordx4 v[6:7], off
	v_lshl_add_u64 v[4:5], v[4:5], 0, s[8:9]
	s_add_i32 m0, s25, 0x1a000
	s_add_i32 s48, s25, 0x8000
	s_add_i32 s49, s25, 0xa000
	global_load_lds_dwordx4 v[4:5], off
	v_lshl_add_u64 v[0:1], v[0:1], 0, s[8:9]
	s_mov_b32 m0, s48
	s_add_u32 s12, s30, 0x80080
	global_load_lds_dwordx4 v[0:1], off
	v_mov_b64_e32 v[250:251], v[0:1]
	v_lshl_add_u64 v[0:1], v[2:3], 0, s[8:9]
	s_mov_b32 m0, s49
	s_addc_u32 s13, s31, 0
	global_load_lds_dwordx4 v[0:1], off
	v_mov_b64_e32 v[252:253], v[0:1]
	s_add_i32 m0, s25, 0x1c000
	v_lshl_add_u64 v[0:1], s[12:13], 0, v[132:133]
	global_load_lds_dwordx4 v[0:1], off
	v_lshl_add_u64 v[0:1], s[12:13], 0, v[128:129]
	s_add_i32 m0, s25, 0x1e000
	s_cmpk_lt_u32 s3, 0x100
	global_load_lds_dwordx4 v[0:1], off
	v_lshrrev_b32_e32 v1, 1, v9
	v_and_b32_e32 v1, 24, v1
	v_and_b32_e32 v0, 15, v9
	v_lshlrev_b32_e32 v2, 1, v1
	v_lshl_or_b32 v148, s10, 6, v0
	v_lshl_or_b32 v0, v0, 6, v2
	v_lshlrev_b32_e32 v2, 2, v9
	v_and_b32_e32 v2, 32, v2
	v_bitop3_b32 v3, v0, s11, v2 bitop3:0xde
	v_bitop3_b32 v149, v0, s15, v2 bitop3:0xde
	v_lshlrev_b32_e32 v0, 15, v13
	v_and_b32_e32 v0, 0xffff0000, v0
	v_or_b32_e32 v150, s14, v1
	v_lshl_add_u32 v0, v12, 12, v0
	v_and_b32_e32 v1, 1, v13
	v_lshl_or_b32 v0, v1, 6, v0
	v_lshl_add_u32 v136, v14, 1, v0
	v_lshlrev_b32_e32 v0, 15, v8
	v_and_b32_e32 v0, 0xffff0000, v0
	s_waitcnt vmcnt(6)
	v_lshl_add_u32 v0, v10, 12, v0
	v_and_b32_e32 v1, 1, v8
	s_cselect_b64 s[10:11], -1, 0
	v_lshl_or_b32 v0, v1, 6, v0
	s_add_i32 s52, 0, 0x10000
	s_add_i32 s53, 0, 0x14000
	s_sext_i32_i16 s55, s2
	s_mov_b32 s50, 0
	s_ashr_i32 s51, s37, 31
	v_mov_b32_e32 v137, v133
	v_lshl_add_u32 v138, v11, 1, v0
	v_mov_b32_e32 v139, v133
	v_mov_b64_e32 v[140:141], 0xb00
	v_mov_b64_e32 v[142:143], 0xaff
	v_add_u32_e32 v151, s52, v149
	v_add_u32_e32 v152, s53, v149
	v_add_u32_e32 v153, 0, v3
	v_mov_b32_e32 v154, 0x358637bd
	s_movk_i32 s54, 0x2c00
	s_barrier
	s_branch .LBB0_2146

; #define PG8_STAGE(bufoff, gbase, voff) do { _Pragma("unroll") for (int _i = 0; _i < 2; ++_i) \
;         __builtin_amdgcn_global_load_lds((const unsigned*)((const char*)(gbase) + (voff)[_i]), (PG8_LAS unsigned*)(lds + (bufoff) + ldsw + _i * 8192), 16, 0, 0); } while (0)
; #define PG8_WAIT_V(n) asm volatile("s_waitcnt vmcnt(" #n ")" ::: "memory")
; #define PG8_BAR __builtin_amdgcn_s_barrier()
; template <class Epi, class Sched, bool ALIGN_EPI = false, bool SP2 = false>
; __device__ __forceinline__ void gemm_phase(PG8_LAS unsigned char* lds, const Gemm g, const Sched& S, const Epi& E) {
;     ...
;     const unsigned ldsw = (unsigned)wid * 1024u;
;     const int aoff = lds_byte(wr * 64 + fr, fq * 8), boff = lds_byte(wc * 32 + fr, fq * 8);
;     ...
;     Unit cur, nxt; int ui = 0;
;     if (!S.next(0, cur)) return;
;     f32x4 acc[2][2][4][2];
; #pragma unroll
;     for (int a = 0; a < 2; ++a)
; #pragma unroll
;         for (int b = 0; b < 2; ++b)
; #pragma unroll
;             for (int m = 0; m < 4; ++m)
; #pragma unroll
;                 for (int n = 0; n < 2; ++n) acc[a][b][m][n] = (f32x4){0.f, 0.f, 0.f, 0.f};
;     bf16x8 At[4][2], B0[2][2], B1[2][2];
;     const char* cA = (const char*)g.A + (size_t)cur.pm * tstep; const char* cB = (const char*)g.Bt + (size_t)cur.pn * tstep;
;     S.a_ready(cur);
;     if constexpr (SP2) {
;         PG8_STAGE(PG8_SB(0, 0), cB, voffB); PG8_STAGE(PG8_SB(0, 1), cB + hstep, voffB); PG8_STAGE(PG8_SA(0, 0), cA, voffA); PG8_STAGE(PG8_SA(0, 1), cA + hstep, voffA);
;         if (wr == 1) PG8_BAR;
;         PG8_WAIT_V(2); PG8_BAR;
;         PG8_STAGE(PG8_SB(1, 0), cB + kstep, voffB); PG8_STAGE(PG8_SA(1, 0), cA + kstep, voffA); PG8_STAGE(PG8_SB(1, 1), cB + hstep + kstep, voffB);
;         PG8_WAIT_V(6); PG8_BAR;
.LBB0_2218:
	s_add_u32 s8, s6, 0x18600000
	s_addc_u32 s9, s5, 0
	s_add_u32 s10, s6, 0x34fc0000
	s_addc_u32 s11, s5, 0
	s_lshl_b32 s3, s3, 5
	s_mov_b64 s[12:13], 0x80
	s_and_b32 s6, s3, 0x60
	s_add_i32 m0, s40, 0x18000
	v_lshl_add_u64 v[6:7], v[6:7], 0, s[12:13]
	s_lshl_b32 s5, s2, 13
	s_lshl_b32 s3, s6, 7
	s_waitcnt vmcnt(2)
	s_barrier
	global_load_lds_dwordx4 v[6:7], off
	v_lshl_add_u64 v[2:3], v[2:3], 0, s[12:13]
	s_add_i32 m0, s40, 0x1a000
	s_add_i32 s45, s40, 0x8000
	s_add_i32 s46, s40, 0xa000
	global_load_lds_dwordx4 v[2:3], off
	v_lshl_add_u64 v[0:1], v[0:1], 0, s[12:13]
	s_mov_b32 m0, s45
	s_add_u32 s14, s24, 0x160080
	global_load_lds_dwordx4 v[0:1], off
	v_mov_b64_e32 v[250:251], v[0:1]
	v_lshl_add_u64 v[0:1], v[4:5], 0, s[12:13]
	s_mov_b32 m0, s46
	s_addc_u32 s15, s25, 0
	global_load_lds_dwordx4 v[0:1], off
	v_mov_b64_e32 v[252:253], v[0:1]
	s_add_i32 m0, s40, 0x1c000
	v_lshl_add_u64 v[0:1], s[14:15], 0, v[154:155]
	global_load_lds_dwordx4 v[0:1], off
	v_lshl_add_u64 v[0:1], s[14:15], 0, v[158:159]
	s_add_i32 m0, s40, 0x1e000
	s_cmpk_lt_u32 s4, 0x100
	global_load_lds_dwordx4 v[0:1], off
	v_bfe_u32 v0, v8, 4, 2
	v_and_b32_e32 v1, 15, v8
	v_lshlrev_b32_e32 v2, 4, v0
	v_lshl_or_b32 v186, s2, 6, v1
	v_lshl_or_b32 v1, v1, 6, v2
	v_lshlrev_b32_e32 v2, 2, v8
	v_and_b32_e32 v2, 32, v2
	v_bitop3_b32 v3, v1, s5, v2 bitop3:0xde
	v_bitop3_b32 v187, v1, s3, v2 bitop3:0xde
	v_cmp_eq_u32_e64 s[2:3], 0, v0
	v_lshl_or_b32 v188, v0, 3, s6
	v_lshrrev_b32_e32 v1, 1, v9
	v_mul_lo_u32 v0, v10, s7
	v_mad_u64_u32 v[0:1], s[4:5], v1, s16, v[0:1]
	v_or_b32_e32 v0, v0, v11
	s_mov_b64 s[28:29], 0x160080
	v_add_lshl_u32 v0, v0, v12, 1
	v_mov_b32_e32 v1, v155
	v_lshl_add_u64 v[160:161], v[0:1], 0, s[28:29]
	v_lshrrev_b32_e32 v1, 1, v13
	v_mul_lo_u32 v0, v14, s7
	v_mad_u64_u32 v[0:1], s[4:5], v1, s16, v[0:1]
	s_waitcnt vmcnt(6)
	v_or_b32_e32 v0, v0, v15
	s_cselect_b64 s[14:15], -1, 0
	v_add_lshl_u32 v0, v0, v16, 1
	v_mov_b32_e32 v1, v155
	s_add_i32 s49, 0, 0x10000
	s_add_i32 s50, 0, 0x14000
	s_ashr_i32 s47, s34, 31
	s_ashr_i32 s48, s33, 31
	v_lshl_add_u64 v[162:163], v[0:1], 0, s[28:29]
	v_mov_b64_e32 v[164:165], 0x200
	v_mov_b64_e32 v[166:167], 0x1ff
	v_add_u32_e32 v189, s49, v187
	v_add_u32_e32 v190, s50, v187
	v_add_u32_e32 v191, 0, v3
	s_mov_b32 s51, 0x4b800000
	s_barrier
	s_branch .LBB0_2221

; #define PG8_STAGE(bufoff, gbase, voff) do { _Pragma("unroll") for (int _i = 0; _i < 2; ++_i) \
;         __builtin_amdgcn_global_load_lds((const unsigned*)((const char*)(gbase) + (voff)[_i]), (PG8_LAS unsigned*)(lds + (bufoff) + ldsw + _i * 8192), 16, 0, 0); } while (0)
; #define PG8_WAIT_V(n) asm volatile("s_waitcnt vmcnt(" #n ")" ::: "memory")
; #define PG8_BAR __builtin_amdgcn_s_barrier()
; template <class Epi, class Sched, bool ALIGN_EPI = false, bool SP2 = false>
; __device__ __forceinline__ void gemm_phase(PG8_LAS unsigned char* lds, const Gemm g, const Sched& S, const Epi& E) {
;     ...
;     const unsigned ldsw = (unsigned)wid * 1024u;
;     const int aoff = lds_byte(wr * 64 + fr, fq * 8), boff = lds_byte(wc * 32 + fr, fq * 8);
;     ...
;     Unit cur, nxt; int ui = 0;
;     if (!S.next(0, cur)) return;
;     f32x4 acc[2][2][4][2];
; #pragma unroll
;     for (int a = 0; a < 2; ++a)
; #pragma unroll
;         for (int b = 0; b < 2; ++b)
; #pragma unroll
;             for (int m = 0; m < 4; ++m)
; #pragma unroll
;                 for (int n = 0; n < 2; ++n) acc[a][b][m][n] = (f32x4){0.f, 0.f, 0.f, 0.f};
;     bf16x8 At[4][2], B0[2][2], B1[2][2];
;     const char* cA = (const char*)g.A + (size_t)cur.pm * tstep; const char* cB = (const char*)g.Bt + (size_t)cur.pn * tstep;
;     S.a_ready(cur);
;     if constexpr (SP2) {
;         PG8_STAGE(PG8_SB(0, 0), cB, voffB); PG8_STAGE(PG8_SB(0, 1), cB + hstep, voffB); PG8_STAGE(PG8_SA(0, 0), cA, voffA); PG8_STAGE(PG8_SA(0, 1), cA + hstep, voffA);
;         if (wr == 1) PG8_BAR;
;         PG8_WAIT_V(2); PG8_BAR;
;         PG8_STAGE(PG8_SB(1, 0), cB + kstep, voffB); PG8_STAGE(PG8_SA(1, 0), cA + kstep, voffA); PG8_STAGE(PG8_SB(1, 1), cB + hstep + kstep, voffB);
;         PG8_WAIT_V(6); PG8_BAR;
.LBB0_2310:
	s_add_u32 s4, s6, 0x1c600000
	s_addc_u32 s5, s7, 0
	s_add_u32 s6, s6, 0x34fc0000
	s_addc_u32 s7, s7, 0
	s_lshl_b32 s8, s8, 5
	s_and_b32 s14, s8, 0x60
	s_mov_b64 s[8:9], 0x80
	s_add_i32 m0, s25, 0x18000
	v_lshl_add_u64 v[6:7], v[6:7], 0, s[8:9]
	s_lshl_b32 s11, s10, 13
	s_lshl_b32 s15, s14, 7
	s_waitcnt vmcnt(2)
	s_barrier
	global_load_lds_dwordx4 v[6:7], off
	v_lshl_add_u64 v[4:5], v[4:5], 0, s[8:9]
	s_add_i32 m0, s25, 0x1a000
	s_add_i32 s48, s25, 0x8000
	s_add_i32 s49, s25, 0xa000
	global_load_lds_dwordx4 v[4:5], off
	v_lshl_add_u64 v[0:1], v[0:1], 0, s[8:9]
	s_mov_b32 m0, s48
	s_add_u32 s12, s30, 0x80080
	global_load_lds_dwordx4 v[0:1], off
	v_mov_b64_e32 v[250:251], v[0:1]
	v_lshl_add_u64 v[0:1], v[2:3], 0, s[8:9]
	s_mov_b32 m0, s49
	s_addc_u32 s13, s31, 0
	global_load_lds_dwordx4 v[0:1], off
	v_mov_b64_e32 v[252:253], v[0:1]
	s_add_i32 m0, s25, 0x1c000
	v_lshl_add_u64 v[0:1], s[12:13], 0, v[132:133]
	global_load_lds_dwordx4 v[0:1], off
	v_lshl_add_u64 v[0:1], s[12:13], 0, v[128:129]
	s_add_i32 m0, s25, 0x1e000
	s_cmpk_lt_u32 s3, 0x100
	global_load_lds_dwordx4 v[0:1], off
	v_lshrrev_b32_e32 v1, 1, v9
	v_and_b32_e32 v1, 24, v1
	v_and_b32_e32 v0, 15, v9
	v_lshlrev_b32_e32 v2, 1, v1
	v_lshl_or_b32 v152, s10, 6, v0
	v_lshl_or_b32 v0, v0, 6, v2
	v_lshlrev_b32_e32 v2, 2, v9
	v_and_b32_e32 v2, 32, v2
	v_bitop3_b32 v3, v0, s11, v2 bitop3:0xde
	v_bitop3_b32 v153, v0, s15, v2 bitop3:0xde
	v_lshlrev_b32_e32 v0, 15, v13
	v_and_b32_e32 v0, 0xffff0000, v0
	v_or_b32_e32 v154, s14, v1
	v_lshl_add_u32 v0, v12, 12, v0
	v_and_b32_e32 v1, 1, v13
	v_lshl_or_b32 v0, v1, 6, v0
	v_lshl_add_u32 v136, v14, 1, v0
	v_lshlrev_b32_e32 v0, 15, v8
	v_and_b32_e32 v0, 0xffff0000, v0
	s_waitcnt vmcnt(6)
	v_lshl_add_u32 v0, v10, 12, v0
	v_and_b32_e32 v1, 1, v8
	s_cselect_b64 s[10:11], -1, 0
	v_lshl_or_b32 v0, v1, 6, v0
	s_add_i32 s52, 0, 0x10000
	s_add_i32 s53, 0, 0x14000
	s_sext_i32_i16 s55, s2
	s_mov_b32 s50, 0
	s_ashr_i32 s51, s37, 31
	v_mov_b32_e32 v137, v133
	v_lshl_add_u32 v138, v11, 1, v0
	v_mov_b32_e32 v139, v133
	v_mov_b64_e32 v[140:141], 0x5c0
	v_mov_b64_e32 v[142:143], 0x5bf
	v_add_u32_e32 v155, s52, v153
	v_add_u32_e32 v156, s53, v153
	v_add_u32_e32 v157, 0, v3
	v_mov_b32_e32 v158, 0x358637bd
	s_movk_i32 s54, 0x2e00
	v_mov_b32_e32 v159, 0x3e38aa3b
	s_barrier
	s_branch .LBB0_2313

; #define PG8_STAGE(bufoff, gbase, voff) do { _Pragma("unroll") for (int _i = 0; _i < 2; ++_i) \
;         __builtin_amdgcn_global_load_lds((const unsigned*)((const char*)(gbase) + (voff)[_i]), (PG8_LAS unsigned*)(lds + (bufoff) + ldsw + _i * 8192), 16, 0, 0); } while (0)
; #define PG8_WAIT_V(n) asm volatile("s_waitcnt vmcnt(" #n ")" ::: "memory")
; #define PG8_BAR __builtin_amdgcn_s_barrier()
; template <class Epi, class Sched, bool ALIGN_EPI = false, bool SP2 = false>
; __device__ __forceinline__ void gemm_phase(PG8_LAS unsigned char* lds, const Gemm g, const Sched& S, const Epi& E) {
;     ...
;     const unsigned ldsw = (unsigned)wid * 1024u;
;     const int aoff = lds_byte(wr * 64 + fr, fq * 8), boff = lds_byte(wc * 32 + fr, fq * 8);
;     ...
;     Unit cur, nxt; int ui = 0;
;     if (!S.next(0, cur)) return;
;     f32x4 acc[2][2][4][2];
; #pragma unroll
;     for (int a = 0; a < 2; ++a)
; #pragma unroll
;         for (int b = 0; b < 2; ++b)
; #pragma unroll
;             for (int m = 0; m < 4; ++m)
; #pragma unroll
;                 for (int n = 0; n < 2; ++n) acc[a][b][m][n] = (f32x4){0.f, 0.f, 0.f, 0.f};
;     bf16x8 At[4][2], B0[2][2], B1[2][2];
;     const char* cA = (const char*)g.A + (size_t)cur.pm * tstep; const char* cB = (const char*)g.Bt + (size_t)cur.pn * tstep;
;     S.a_ready(cur);
;     if constexpr (SP2) {
;         PG8_STAGE(PG8_SB(0, 0), cB, voffB); PG8_STAGE(PG8_SB(0, 1), cB + hstep, voffB); PG8_STAGE(PG8_SA(0, 0), cA, voffA); PG8_STAGE(PG8_SA(0, 1), cA + hstep, voffA);
;         if (wr == 1) PG8_BAR;
;         PG8_WAIT_V(2); PG8_BAR;
;         PG8_STAGE(PG8_SB(1, 0), cB + kstep, voffB); PG8_STAGE(PG8_SA(1, 0), cA + kstep, voffA); PG8_STAGE(PG8_SB(1, 1), cB + hstep + kstep, voffB);
;         PG8_WAIT_V(6); PG8_BAR;
.LBB0_2777:
	s_add_u32 s6, s8, 0x18600000
	s_addc_u32 s7, s5, 0
	s_add_u32 s8, s8, 0x34fe0000
	s_addc_u32 s9, s5, 0
	s_lshl_b32 s3, s3, 5
	s_mov_b64 s[10:11], 0x80
	s_and_b32 s14, s3, 0x60
	s_add_i32 m0, s31, 0x18000
	v_lshl_add_u64 v[6:7], v[6:7], 0, s[10:11]
	s_lshl_b32 s5, s2, 13
	s_lshl_b32 s3, s14, 7
	s_waitcnt vmcnt(2)
	s_barrier
	global_load_lds_dwordx4 v[6:7], off
	v_lshl_add_u64 v[4:5], v[4:5], 0, s[10:11]
	s_add_i32 m0, s31, 0x1a000
	s_add_i32 s50, s31, 0x8000
	s_add_i32 s51, s31, 0xa000
	global_load_lds_dwordx4 v[4:5], off
	v_lshl_add_u64 v[0:1], v[0:1], 0, s[10:11]
	s_mov_b32 m0, s50
	s_add_u32 s12, s36, 0x80080
	global_load_lds_dwordx4 v[0:1], off
	v_mov_b64_e32 v[250:251], v[0:1]
	v_lshl_add_u64 v[0:1], v[2:3], 0, s[10:11]
	s_mov_b32 m0, s51
	s_addc_u32 s13, s37, 0
	global_load_lds_dwordx4 v[0:1], off
	v_mov_b64_e32 v[252:253], v[0:1]
	s_add_i32 m0, s31, 0x1c000
	v_lshl_add_u64 v[0:1], s[12:13], 0, v[154:155]
	global_load_lds_dwordx4 v[0:1], off
	v_lshl_add_u64 v[0:1], s[12:13], 0, v[158:159]
	s_add_i32 m0, s31, 0x1e000
	s_cmpk_lt_u32 s4, 0x100
	global_load_lds_dwordx4 v[0:1], off
	v_bfe_u32 v0, v8, 4, 2
	v_and_b32_e32 v1, 15, v8
	v_lshlrev_b32_e32 v2, 4, v0
	v_lshl_or_b32 v186, s2, 6, v1
	v_lshl_or_b32 v1, v1, 6, v2
	v_lshlrev_b32_e32 v2, 2, v8
	v_and_b32_e32 v2, 32, v2
	v_bitop3_b32 v187, v1, s3, v2 bitop3:0xde
	v_cmp_eq_u32_e64 s[2:3], 0, v0
	v_lshl_or_b32 v188, v0, 3, s14
	v_lshlrev_b32_e32 v0, 15, v9
	v_and_b32_e32 v0, 0xffff0000, v0
	v_bitop3_b32 v3, v1, s5, v2 bitop3:0xde
	v_lshl_add_u32 v0, v10, 12, v0
	v_and_b32_e32 v1, 1, v9
	v_lshl_or_b32 v0, v1, 6, v0
	v_lshl_add_u32 v160, v11, 1, v0
	v_lshlrev_b32_e32 v0, 15, v12
	v_and_b32_e32 v0, 0xffff0000, v0
	s_waitcnt vmcnt(6)
	v_lshl_add_u32 v0, v13, 12, v0
	v_and_b32_e32 v1, 1, v12
	s_cselect_b64 s[12:13], -1, 0
	v_lshl_or_b32 v0, v1, 6, v0
	s_add_i32 s54, 0, 0x10000
	s_add_i32 s55, 0, 0x14000
	s_ashr_i32 s52, s40, 31
	s_ashr_i32 s53, s33, 31
	v_mov_b32_e32 v161, v155
	v_lshl_add_u32 v162, v14, 1, v0
	v_mov_b32_e32 v163, v155
	v_mov_b64_e32 v[164:165], 0x200
	v_mov_b64_e32 v[166:167], 0x1ff
	v_add_u32_e32 v189, s54, v187
	v_add_u32_e32 v190, s55, v187
	v_add_u32_e32 v191, 0, v3
	s_mov_b32 s56, 0x4b800000
	s_barrier
	s_branch .LBB0_2780

; #define PG8_STAGE(bufoff, gbase, voff) do { _Pragma("unroll") for (int _i = 0; _i < 2; ++_i) \
;         __builtin_amdgcn_global_load_lds((const unsigned*)((const char*)(gbase) + (voff)[_i]), (PG8_LAS unsigned*)(lds + (bufoff) + ldsw + _i * 8192), 16, 0, 0); } while (0)
; #define PG8_WAIT_V(n) asm volatile("s_waitcnt vmcnt(" #n ")" ::: "memory")
; #define PG8_BAR __builtin_amdgcn_s_barrier()
; template <class Epi, class Sched, bool ALIGN_EPI = false, bool SP2 = false>
; __device__ __forceinline__ void gemm_phase(PG8_LAS unsigned char* lds, const Gemm g, const Sched& S, const Epi& E) {
;     ...
;     const unsigned ldsw = (unsigned)wid * 1024u;
;     const int aoff = lds_byte(wr * 64 + fr, fq * 8), boff = lds_byte(wc * 32 + fr, fq * 8);
;     ...
;     Unit cur, nxt; int ui = 0;
;     if (!S.next(0, cur)) return;
;     f32x4 acc[2][2][4][2];
; #pragma unroll
;     for (int a = 0; a < 2; ++a)
; #pragma unroll
;         for (int b = 0; b < 2; ++b)
; #pragma unroll
;             for (int m = 0; m < 4; ++m)
; #pragma unroll
;                 for (int n = 0; n < 2; ++n) acc[a][b][m][n] = (f32x4){0.f, 0.f, 0.f, 0.f};
;     bf16x8 At[4][2], B0[2][2], B1[2][2];
;     const char* cA = (const char*)g.A + (size_t)cur.pm * tstep; const char* cB = (const char*)g.Bt + (size_t)cur.pn * tstep;
;     S.a_ready(cur);
;     if constexpr (SP2) {
;         PG8_STAGE(PG8_SB(0, 0), cB, voffB); PG8_STAGE(PG8_SB(0, 1), cB + hstep, voffB); PG8_STAGE(PG8_SA(0, 0), cA, voffA); PG8_STAGE(PG8_SA(0, 1), cA + hstep, voffA);
;         if (wr == 1) PG8_BAR;
;         PG8_WAIT_V(2); PG8_BAR;
;         PG8_STAGE(PG8_SB(1, 0), cB + kstep, voffB); PG8_STAGE(PG8_SA(1, 0), cA + kstep, voffA); PG8_STAGE(PG8_SB(1, 1), cB + hstep + kstep, voffB);
;         PG8_WAIT_V(6); PG8_BAR;
.LBB0_2865:
	s_add_u32 s4, s6, 0x1c600000
	s_addc_u32 s5, s7, 0
	s_add_u32 s6, s6, 0x34fe0000
	s_addc_u32 s7, s7, 0
	s_lshl_b32 s8, s8, 5
	s_and_b32 s14, s8, 0x60
	s_mov_b64 s[8:9], 0x80
	s_add_i32 m0, s25, 0x18000
	v_lshl_add_u64 v[6:7], v[6:7], 0, s[8:9]
	s_lshl_b32 s11, s10, 13
	s_lshl_b32 s15, s14, 7
	s_waitcnt vmcnt(2)
	s_barrier
	global_load_lds_dwordx4 v[6:7], off
	v_lshl_add_u64 v[4:5], v[4:5], 0, s[8:9]
	s_add_i32 m0, s25, 0x1a000
	s_add_i32 s48, s25, 0x8000
	s_add_i32 s49, s25, 0xa000
	global_load_lds_dwordx4 v[4:5], off
	v_lshl_add_u64 v[0:1], v[0:1], 0, s[8:9]
	s_mov_b32 m0, s48
	s_add_u32 s12, s30, 0x80080
	global_load_lds_dwordx4 v[0:1], off
	v_mov_b64_e32 v[250:251], v[0:1]
	v_lshl_add_u64 v[0:1], v[2:3], 0, s[8:9]
	s_mov_b32 m0, s49
	s_addc_u32 s13, s31, 0
	global_load_lds_dwordx4 v[0:1], off
	v_mov_b64_e32 v[252:253], v[0:1]
	s_add_i32 m0, s25, 0x1c000
	v_lshl_add_u64 v[0:1], s[12:13], 0, v[132:133]
	global_load_lds_dwordx4 v[0:1], off
	v_lshl_add_u64 v[0:1], s[12:13], 0, v[128:129]
	s_add_i32 m0, s25, 0x1e000
	s_cmpk_lt_u32 s3, 0x100
	global_load_lds_dwordx4 v[0:1], off
	v_lshrrev_b32_e32 v1, 1, v9
	v_and_b32_e32 v1, 24, v1
	v_and_b32_e32 v0, 15, v9
	v_lshlrev_b32_e32 v2, 1, v1
	v_lshl_or_b32 v148, s10, 6, v0
	v_lshl_or_b32 v0, v0, 6, v2
	v_lshlrev_b32_e32 v2, 2, v9
	v_and_b32_e32 v2, 32, v2
	v_bitop3_b32 v3, v0, s11, v2 bitop3:0xde
	v_bitop3_b32 v149, v0, s15, v2 bitop3:0xde
	v_lshlrev_b32_e32 v0, 15, v13
	v_and_b32_e32 v0, 0xffff0000, v0
	v_or_b32_e32 v150, s14, v1
	v_lshl_add_u32 v0, v12, 12, v0
	v_and_b32_e32 v1, 1, v13
	v_lshl_or_b32 v0, v1, 6, v0
	v_lshl_add_u32 v136, v14, 1, v0
	v_lshlrev_b32_e32 v0, 15, v8
	v_and_b32_e32 v0, 0xffff0000, v0
	s_waitcnt vmcnt(6)
	v_lshl_add_u32 v0, v10, 12, v0
	v_and_b32_e32 v1, 1, v8
	s_cselect_b64 s[10:11], -1, 0
	v_lshl_or_b32 v0, v1, 6, v0
	s_add_i32 s52, 0, 0x10000
	s_add_i32 s53, 0, 0x14000
	s_sext_i32_i16 s55, s2
	s_mov_b32 s50, 0
	s_ashr_i32 s51, s37, 31
	v_mov_b32_e32 v137, v133
	v_lshl_add_u32 v138, v11, 1, v0
	v_mov_b32_e32 v139, v133
	v_mov_b64_e32 v[140:141], 0xb00
	v_mov_b64_e32 v[142:143], 0xaff
	v_add_u32_e32 v151, s52, v149
	v_add_u32_e32 v152, s53, v149
	v_add_u32_e32 v153, 0, v3
	v_mov_b32_e32 v154, 0x358637bd
	s_movk_i32 s54, 0x2c00
	s_barrier
	s_branch .LBB0_2868

; #define PG8_STAGE(bufoff, gbase, voff) do { _Pragma("unroll") for (int _i = 0; _i < 2; ++_i) \
;         __builtin_amdgcn_global_load_lds((const unsigned*)((const char*)(gbase) + (voff)[_i]), (PG8_LAS unsigned*)(lds + (bufoff) + ldsw + _i * 8192), 16, 0, 0); } while (0)
; #define PG8_WAIT_V(n) asm volatile("s_waitcnt vmcnt(" #n ")" ::: "memory")
; #define PG8_BAR __builtin_amdgcn_s_barrier()
; template <class Epi, class Sched, bool ALIGN_EPI = false, bool SP2 = false>
; __device__ __forceinline__ void gemm_phase(PG8_LAS unsigned char* lds, const Gemm g, const Sched& S, const Epi& E) {
;     ...
;     const unsigned ldsw = (unsigned)wid * 1024u;
;     const int aoff = lds_byte(wr * 64 + fr, fq * 8), boff = lds_byte(wc * 32 + fr, fq * 8);
;     ...
;     Unit cur, nxt; int ui = 0;
;     if (!S.next(0, cur)) return;
;     f32x4 acc[2][2][4][2];
; #pragma unroll
;     for (int a = 0; a < 2; ++a)
; #pragma unroll
;         for (int b = 0; b < 2; ++b)
; #pragma unroll
;             for (int m = 0; m < 4; ++m)
; #pragma unroll
;                 for (int n = 0; n < 2; ++n) acc[a][b][m][n] = (f32x4){0.f, 0.f, 0.f, 0.f};
;     bf16x8 At[4][2], B0[2][2], B1[2][2];
;     const char* cA = (const char*)g.A + (size_t)cur.pm * tstep; const char* cB = (const char*)g.Bt + (size_t)cur.pn * tstep;
;     S.a_ready(cur);
;     if constexpr (SP2) {
;         PG8_STAGE(PG8_SB(0, 0), cB, voffB); PG8_STAGE(PG8_SB(0, 1), cB + hstep, voffB); PG8_STAGE(PG8_SA(0, 0), cA, voffA); PG8_STAGE(PG8_SA(0, 1), cA + hstep, voffA);
;         if (wr == 1) PG8_BAR;
;         PG8_WAIT_V(2); PG8_BAR;
;         PG8_STAGE(PG8_SB(1, 0), cB + kstep, voffB); PG8_STAGE(PG8_SA(1, 0), cA + kstep, voffA); PG8_STAGE(PG8_SB(1, 1), cB + hstep + kstep, voffB);
;         PG8_WAIT_V(6); PG8_BAR;
.LBB0_2940:
	s_add_u32 s8, s6, 0x18600000
	s_addc_u32 s9, s5, 0
	s_add_u32 s10, s6, 0x35000000
	s_addc_u32 s11, s5, 0
	s_lshl_b32 s3, s3, 5
	s_mov_b64 s[12:13], 0x80
	s_and_b32 s6, s3, 0x60
	s_add_i32 m0, s40, 0x18000
	v_lshl_add_u64 v[6:7], v[6:7], 0, s[12:13]
	s_lshl_b32 s5, s2, 13
	s_lshl_b32 s3, s6, 7
	s_waitcnt vmcnt(2)
	s_barrier
	global_load_lds_dwordx4 v[6:7], off
	v_lshl_add_u64 v[2:3], v[2:3], 0, s[12:13]
	s_add_i32 m0, s40, 0x1a000
	s_add_i32 s45, s40, 0x8000
	s_add_i32 s46, s40, 0xa000
	global_load_lds_dwordx4 v[2:3], off
	v_lshl_add_u64 v[0:1], v[0:1], 0, s[12:13]
	s_mov_b32 m0, s45
	s_add_u32 s14, s24, 0x160080
	global_load_lds_dwordx4 v[0:1], off
	v_mov_b64_e32 v[250:251], v[0:1]
	v_lshl_add_u64 v[0:1], v[4:5], 0, s[12:13]
	s_mov_b32 m0, s46
	s_addc_u32 s15, s25, 0
	global_load_lds_dwordx4 v[0:1], off
	v_mov_b64_e32 v[252:253], v[0:1]
	s_add_i32 m0, s40, 0x1c000
	v_lshl_add_u64 v[0:1], s[14:15], 0, v[154:155]
	global_load_lds_dwordx4 v[0:1], off
	v_lshl_add_u64 v[0:1], s[14:15], 0, v[158:159]
	s_add_i32 m0, s40, 0x1e000
	s_cmpk_lt_u32 s4, 0x100
	global_load_lds_dwordx4 v[0:1], off
	v_bfe_u32 v0, v8, 4, 2
	v_and_b32_e32 v1, 15, v8
	v_lshlrev_b32_e32 v2, 4, v0
	v_lshl_or_b32 v186, s2, 6, v1
	v_lshl_or_b32 v1, v1, 6, v2
	v_lshlrev_b32_e32 v2, 2, v8
	v_and_b32_e32 v2, 32, v2
	v_bitop3_b32 v3, v1, s5, v2 bitop3:0xde
	v_bitop3_b32 v187, v1, s3, v2 bitop3:0xde
	v_cmp_eq_u32_e64 s[2:3], 0, v0
	v_lshl_or_b32 v188, v0, 3, s6
	v_lshrrev_b32_e32 v1, 1, v9
	v_mul_lo_u32 v0, v10, s7
	v_mad_u64_u32 v[0:1], s[4:5], v1, s16, v[0:1]
	v_or_b32_e32 v0, v0, v11
	s_mov_b64 s[28:29], 0x160080
	v_add_lshl_u32 v0, v0, v12, 1
	v_mov_b32_e32 v1, v155
	v_lshl_add_u64 v[160:161], v[0:1], 0, s[28:29]
	v_lshrrev_b32_e32 v1, 1, v13
	v_mul_lo_u32 v0, v14, s7
	v_mad_u64_u32 v[0:1], s[4:5], v1, s16, v[0:1]
	s_waitcnt vmcnt(6)
	v_or_b32_e32 v0, v0, v15
	s_cselect_b64 s[14:15], -1, 0
	v_add_lshl_u32 v0, v0, v16, 1
	v_mov_b32_e32 v1, v155
	s_add_i32 s49, 0, 0x10000
	s_add_i32 s50, 0, 0x14000
	s_ashr_i32 s47, s34, 31
	s_ashr_i32 s48, s33, 31
	v_lshl_add_u64 v[162:163], v[0:1], 0, s[28:29]
	v_mov_b64_e32 v[164:165], 0x200
	v_mov_b64_e32 v[166:167], 0x1ff
	v_add_u32_e32 v189, s49, v187
	v_add_u32_e32 v190, s50, v187
	v_add_u32_e32 v191, 0, v3
	s_mov_b32 s51, 0x4b800000
	s_barrier
	s_branch .LBB0_2943
